# GEMM K-loops: all 16 LDS-DMA addresses per K-tile pair from scalar base pairs (no 64-bit VGPR address arithmetic left in the loop)
# baseline (speedup 1.0000x reference)
.LBB0_272:
	ds_read_b128 v[146:149], v153
	ds_read_b128 v[156:159], v153 offset:1024
	ds_read_b128 v[160:163], v153 offset:2048
	ds_read_b128 v[164:167], v153 offset:3072
	ds_read_b128 v[168:171], v154
	ds_read_b128 v[172:175], v154 offset:1024
	ds_read_b128 v[176:179], v154 offset:2048
	ds_read_b128 v[180:183], v154 offset:3072
	s_add_u32 s62, s60, 0xfffc0080
	s_addc_u32 s63, s61, -1
	s_cmp_eq_u32 s86, 12
	s_cselect_b32 s65, s37, s63
	s_cselect_b32 s64, s43, s62
	s_cselect_b32 s63, s35, s85
	s_cselect_b32 s62, s55, s84
	s_add_i32 m0, s69, 0xc000
	ds_read_b128 v[184:187], v155
	ds_read_b128 v[192:195], v155 offset:1024
	ds_read_b128 v[196:199], v155 offset:2048
	ds_read_b128 v[200:203], v155 offset:3072
	ds_read_b128 v[204:207], v155 offset:4096
	ds_read_b128 v[208:211], v155 offset:5120
	ds_read_b128 v[212:215], v155 offset:6144
	ds_read_b128 v[216:219], v155 offset:7168
	global_load_lds_dwordx4 v138, s[60:61]
	v_lshl_add_u64 v[188:189], s[60:61], 0, v[140:141]
	s_add_i32 m0, s69, 0xe000
	s_nop 0
	global_load_lds_dwordx4 v[188:189], off
	s_waitcnt vmcnt(8)
	s_waitcnt lgkmcnt(0)
	s_barrier
	s_setprio 1
	s_waitcnt lgkmcnt(0)
	v_mfma_f32_16x16x32_bf16 v[124:127], v[146:149], v[184:187], v[124:127]
	v_mfma_f32_16x16x32_bf16 v[120:123], v[160:163], v[184:187], v[120:123]
	v_mfma_f32_16x16x32_bf16 v[116:119], v[146:149], v[196:199], v[116:119]
	v_mfma_f32_16x16x32_bf16 v[108:111], v[160:163], v[196:199], v[108:111]
	v_mfma_f32_16x16x32_bf16 v[100:103], v[146:149], v[204:207], v[100:103]
	v_mfma_f32_16x16x32_bf16 v[92:95], v[160:163], v[204:207], v[92:95]
	v_mfma_f32_16x16x32_bf16 v[84:87], v[146:149], v[212:215], v[84:87]
	v_mfma_f32_16x16x32_bf16 v[76:79], v[160:163], v[212:215], v[76:79]
	v_mfma_f32_16x16x32_bf16 v[124:127], v[156:159], v[192:195], v[124:127]
	v_mfma_f32_16x16x32_bf16 v[120:123], v[164:167], v[192:195], v[120:123]
	v_mfma_f32_16x16x32_bf16 v[116:119], v[156:159], v[200:203], v[116:119]
	v_mfma_f32_16x16x32_bf16 v[108:111], v[164:167], v[200:203], v[108:111]
	v_mfma_f32_16x16x32_bf16 v[100:103], v[156:159], v[208:211], v[100:103]
	v_mfma_f32_16x16x32_bf16 v[92:95], v[164:167], v[208:211], v[92:95]
	v_mfma_f32_16x16x32_bf16 v[84:87], v[156:159], v[216:219], v[84:87]
	v_mfma_f32_16x16x32_bf16 v[76:79], v[164:167], v[216:219], v[76:79]
	s_setprio 0
	s_setprio 1
	v_mfma_f32_16x16x32_bf16 v[112:115], v[168:171], v[184:187], v[112:115]
	v_mfma_f32_16x16x32_bf16 v[104:107], v[176:179], v[184:187], v[104:107]
	v_mfma_f32_16x16x32_bf16 v[96:99], v[168:171], v[196:199], v[96:99]
	v_mfma_f32_16x16x32_bf16 v[88:91], v[176:179], v[196:199], v[88:91]
	v_mfma_f32_16x16x32_bf16 v[80:83], v[168:171], v[204:207], v[80:83]
	v_mfma_f32_16x16x32_bf16 v[72:75], v[176:179], v[204:207], v[72:75]
	v_mfma_f32_16x16x32_bf16 v[68:71], v[168:171], v[212:215], v[68:71]
	v_mfma_f32_16x16x32_bf16 v[64:67], v[176:179], v[212:215], v[64:67]
	v_mfma_f32_16x16x32_bf16 v[112:115], v[172:175], v[192:195], v[112:115]
	v_mfma_f32_16x16x32_bf16 v[104:107], v[180:183], v[192:195], v[104:107]
	v_mfma_f32_16x16x32_bf16 v[96:99], v[172:175], v[200:203], v[96:99]
	v_mfma_f32_16x16x32_bf16 v[88:91], v[180:183], v[200:203], v[88:91]
	v_mfma_f32_16x16x32_bf16 v[80:83], v[172:175], v[208:211], v[80:83]
	v_mfma_f32_16x16x32_bf16 v[72:75], v[180:183], v[208:211], v[72:75]
	v_mfma_f32_16x16x32_bf16 v[68:71], v[172:175], v[216:219], v[68:71]
	v_mfma_f32_16x16x32_bf16 v[64:67], v[180:183], v[216:219], v[64:67]
	s_setprio 0
	s_barrier
	s_add_i32 s87, s76, s68
	s_add_u32 s98, s62, 0x80
	s_addc_u32 s99, s63, 0
	s_mov_b32 m0, s87
	ds_read_b128 v[184:187], v155 offset:16384
	ds_read_b128 v[192:195], v155 offset:17408
	ds_read_b128 v[196:199], v155 offset:18432
	ds_read_b128 v[200:203], v155 offset:19456
	ds_read_b128 v[204:207], v155 offset:20480
	ds_read_b128 v[208:211], v155 offset:21504
	ds_read_b128 v[212:215], v155 offset:22528
	ds_read_b128 v[216:219], v155 offset:23552
	global_load_lds_dwordx4 v132, s[62:63]
	s_add_i32 m0, s87, 0x2000
	s_add_u32 s88, s62, 0x40000
	s_addc_u32 s89, s63, 0
	s_add_i32 s87, s77, s68
	global_load_lds_dwordx4 v128, s[62:63]
	s_mov_b32 m0, s87
	s_add_u32 s100, s64, 0x80
	s_addc_u32 s101, s65, 0
	global_load_lds_dwordx4 v132, s[88:89]
	s_add_i32 m0, s87, 0x2000
	s_nop 0
	global_load_lds_dwordx4 v128, s[88:89]
	s_mov_b32 m0, s69
	s_nop 0
	global_load_lds_dwordx4 v134, s[64:65]
	s_mov_b32 m0, s70
	s_nop 0
	global_load_lds_dwordx4 v130, s[64:65]
	s_waitcnt vmcnt(8)
	s_waitcnt lgkmcnt(0)
	s_barrier
	s_setprio 1
	s_waitcnt lgkmcnt(0)
	v_mfma_f32_16x16x32_bf16 v[60:63], v[146:149], v[184:187], v[60:63]
	v_mfma_f32_16x16x32_bf16 v[56:59], v[160:163], v[184:187], v[56:59]
	v_mfma_f32_16x16x32_bf16 v[52:55], v[146:149], v[196:199], v[52:55]
	v_mfma_f32_16x16x32_bf16 v[44:47], v[160:163], v[196:199], v[44:47]
	v_mfma_f32_16x16x32_bf16 v[36:39], v[146:149], v[204:207], v[36:39]
	v_mfma_f32_16x16x32_bf16 v[28:31], v[160:163], v[204:207], v[28:31]
	v_mfma_f32_16x16x32_bf16 v[20:23], v[146:149], v[212:215], v[20:23]
	v_mfma_f32_16x16x32_bf16 v[12:15], v[160:163], v[212:215], v[12:15]
	v_mfma_f32_16x16x32_bf16 v[60:63], v[156:159], v[192:195], v[60:63]
	v_mfma_f32_16x16x32_bf16 v[56:59], v[164:167], v[192:195], v[56:59]
	v_mfma_f32_16x16x32_bf16 v[52:55], v[156:159], v[200:203], v[52:55]
	v_mfma_f32_16x16x32_bf16 v[44:47], v[164:167], v[200:203], v[44:47]
	v_mfma_f32_16x16x32_bf16 v[36:39], v[156:159], v[208:211], v[36:39]
	v_mfma_f32_16x16x32_bf16 v[28:31], v[164:167], v[208:211], v[28:31]
	v_mfma_f32_16x16x32_bf16 v[20:23], v[156:159], v[216:219], v[20:23]
	v_mfma_f32_16x16x32_bf16 v[12:15], v[164:167], v[216:219], v[12:15]
	s_setprio 0
	s_setprio 1
	v_mfma_f32_16x16x32_bf16 v[48:51], v[168:171], v[184:187], v[48:51]
	v_mfma_f32_16x16x32_bf16 v[40:43], v[176:179], v[184:187], v[40:43]
	v_mfma_f32_16x16x32_bf16 v[32:35], v[168:171], v[196:199], v[32:35]
	v_mfma_f32_16x16x32_bf16 v[24:27], v[176:179], v[196:199], v[24:27]
	v_mfma_f32_16x16x32_bf16 v[16:19], v[168:171], v[204:207], v[16:19]
	v_mfma_f32_16x16x32_bf16 v[8:11], v[176:179], v[204:207], v[8:11]
	v_mfma_f32_16x16x32_bf16 v[4:7], v[168:171], v[212:215], v[4:7]
	v_mfma_f32_16x16x32_bf16 v[0:3], v[176:179], v[212:215], v[0:3]
	v_mfma_f32_16x16x32_bf16 v[48:51], v[172:175], v[192:195], v[48:51]
	v_mfma_f32_16x16x32_bf16 v[40:43], v[180:183], v[192:195], v[40:43]
	v_mfma_f32_16x16x32_bf16 v[32:35], v[172:175], v[200:203], v[32:35]
	v_mfma_f32_16x16x32_bf16 v[24:27], v[180:183], v[200:203], v[24:27]
	v_mfma_f32_16x16x32_bf16 v[16:19], v[172:175], v[208:211], v[16:19]
	v_mfma_f32_16x16x32_bf16 v[8:11], v[180:183], v[208:211], v[8:11]
	v_mfma_f32_16x16x32_bf16 v[4:7], v[172:175], v[216:219], v[4:7]
	v_mfma_f32_16x16x32_bf16 v[0:3], v[180:183], v[216:219], v[0:3]
	s_setprio 0
	s_barrier
	s_add_i32 s87, 0, 0x18000
	s_add_i32 s88, 0, 0x1c000
	v_add_u32_e32 v164, s87, v151
	v_add_u32_e32 v180, s88, v151
	ds_read_b128 v[146:149], v164
	ds_read_b128 v[156:159], v164 offset:1024
	ds_read_b128 v[160:163], v164 offset:2048
	ds_read_b128 v[164:167], v164 offset:3072
	ds_read_b128 v[168:171], v180
	ds_read_b128 v[172:175], v180 offset:1024
	ds_read_b128 v[176:179], v180 offset:2048
	ds_read_b128 v[180:183], v180 offset:3072
	s_add_u32 s64, s64, 0x40000
	s_addc_u32 s65, s65, 0
	s_mov_b32 m0, s71
	ds_read_b128 v[184:187], v155 offset:32768
	ds_read_b128 v[192:195], v155 offset:33792
	ds_read_b128 v[196:199], v155 offset:34816
	ds_read_b128 v[200:203], v155 offset:35840
	ds_read_b128 v[204:207], v155 offset:36864
	ds_read_b128 v[208:211], v155 offset:37888
	ds_read_b128 v[212:215], v155 offset:38912
	ds_read_b128 v[216:219], v155 offset:39936
	global_load_lds_dwordx4 v134, s[64:65]
	s_mov_b32 m0, s72
	s_nop 0
	global_load_lds_dwordx4 v130, s[64:65]
	s_waitcnt vmcnt(8)
	s_waitcnt lgkmcnt(0)
	s_barrier
	s_setprio 1
	s_waitcnt lgkmcnt(0)
	v_mfma_f32_16x16x32_bf16 v[124:127], v[146:149], v[184:187], v[124:127]
	v_mfma_f32_16x16x32_bf16 v[120:123], v[160:163], v[184:187], v[120:123]
	v_mfma_f32_16x16x32_bf16 v[116:119], v[146:149], v[196:199], v[116:119]
	v_mfma_f32_16x16x32_bf16 v[108:111], v[160:163], v[196:199], v[108:111]
	v_mfma_f32_16x16x32_bf16 v[100:103], v[146:149], v[204:207], v[100:103]
	v_mfma_f32_16x16x32_bf16 v[92:95], v[160:163], v[204:207], v[92:95]
	v_mfma_f32_16x16x32_bf16 v[84:87], v[146:149], v[212:215], v[84:87]
	v_mfma_f32_16x16x32_bf16 v[76:79], v[160:163], v[212:215], v[76:79]
	v_mfma_f32_16x16x32_bf16 v[124:127], v[156:159], v[192:195], v[124:127]
	v_mfma_f32_16x16x32_bf16 v[120:123], v[164:167], v[192:195], v[120:123]
	v_mfma_f32_16x16x32_bf16 v[116:119], v[156:159], v[200:203], v[116:119]
	v_mfma_f32_16x16x32_bf16 v[108:111], v[164:167], v[200:203], v[108:111]
	v_mfma_f32_16x16x32_bf16 v[100:103], v[156:159], v[208:211], v[100:103]
	v_mfma_f32_16x16x32_bf16 v[92:95], v[164:167], v[208:211], v[92:95]
	v_mfma_f32_16x16x32_bf16 v[84:87], v[156:159], v[216:219], v[84:87]
	v_mfma_f32_16x16x32_bf16 v[76:79], v[164:167], v[216:219], v[76:79]
	s_setprio 0
	s_setprio 1
	v_mfma_f32_16x16x32_bf16 v[112:115], v[168:171], v[184:187], v[112:115]
	v_mfma_f32_16x16x32_bf16 v[104:107], v[176:179], v[184:187], v[104:107]
	v_mfma_f32_16x16x32_bf16 v[96:99], v[168:171], v[196:199], v[96:99]
	v_mfma_f32_16x16x32_bf16 v[88:91], v[176:179], v[196:199], v[88:91]
	v_mfma_f32_16x16x32_bf16 v[80:83], v[168:171], v[204:207], v[80:83]
	v_mfma_f32_16x16x32_bf16 v[72:75], v[176:179], v[204:207], v[72:75]
	v_mfma_f32_16x16x32_bf16 v[68:71], v[168:171], v[212:215], v[68:71]
	v_mfma_f32_16x16x32_bf16 v[64:67], v[176:179], v[212:215], v[64:67]
	v_mfma_f32_16x16x32_bf16 v[112:115], v[172:175], v[192:195], v[112:115]
	v_mfma_f32_16x16x32_bf16 v[104:107], v[180:183], v[192:195], v[104:107]
	v_mfma_f32_16x16x32_bf16 v[96:99], v[172:175], v[200:203], v[96:99]
	v_mfma_f32_16x16x32_bf16 v[88:91], v[180:183], v[200:203], v[88:91]
	v_mfma_f32_16x16x32_bf16 v[80:83], v[172:175], v[208:211], v[80:83]
	v_mfma_f32_16x16x32_bf16 v[72:75], v[180:183], v[208:211], v[72:75]
	v_mfma_f32_16x16x32_bf16 v[68:71], v[172:175], v[216:219], v[68:71]
	v_mfma_f32_16x16x32_bf16 v[64:67], v[180:183], v[216:219], v[64:67]
	s_setprio 0
	s_barrier
	s_add_i32 s64, s87, s68
	s_mov_b32 m0, s64
	ds_read_b128 v[184:187], v155 offset:49152
	ds_read_b128 v[192:195], v155 offset:50176
	ds_read_b128 v[196:199], v155 offset:51200
	ds_read_b128 v[200:203], v155 offset:52224
	ds_read_b128 v[204:207], v155 offset:53248
	ds_read_b128 v[208:211], v155 offset:54272
	ds_read_b128 v[212:215], v155 offset:55296
	ds_read_b128 v[216:219], v155 offset:56320
	global_load_lds_dwordx4 v132, s[98:99]
	s_add_i32 m0, s64, 0x2000
	s_add_u32 s62, s62, 0x40080
	s_addc_u32 s63, s63, 0
	s_add_i32 s64, s88, s68
	global_load_lds_dwordx4 v128, s[98:99]
	s_mov_b32 m0, s64
	s_nop 0
	global_load_lds_dwordx4 v132, s[62:63]
	s_add_i32 m0, s64, 0x2000
	s_nop 0
	global_load_lds_dwordx4 v128, s[62:63]
	s_mov_b32 m0, s33
	s_nop 0
	global_load_lds_dwordx4 v134, s[100:101]
	s_mov_b32 m0, s74
	s_nop 0
	global_load_lds_dwordx4 v130, s[100:101]
	s_waitcnt vmcnt(8)
	s_waitcnt lgkmcnt(0)
	s_barrier
	s_setprio 1
	s_waitcnt lgkmcnt(0)
	v_mfma_f32_16x16x32_bf16 v[60:63], v[146:149], v[184:187], v[60:63]
	v_mfma_f32_16x16x32_bf16 v[56:59], v[160:163], v[184:187], v[56:59]
	v_mfma_f32_16x16x32_bf16 v[52:55], v[146:149], v[196:199], v[52:55]
	v_mfma_f32_16x16x32_bf16 v[44:47], v[160:163], v[196:199], v[44:47]
	v_mfma_f32_16x16x32_bf16 v[36:39], v[146:149], v[204:207], v[36:39]
	v_mfma_f32_16x16x32_bf16 v[28:31], v[160:163], v[204:207], v[28:31]
	v_mfma_f32_16x16x32_bf16 v[20:23], v[146:149], v[212:215], v[20:23]
	v_mfma_f32_16x16x32_bf16 v[12:15], v[160:163], v[212:215], v[12:15]
	v_mfma_f32_16x16x32_bf16 v[60:63], v[156:159], v[192:195], v[60:63]
	v_mfma_f32_16x16x32_bf16 v[56:59], v[164:167], v[192:195], v[56:59]
	v_mfma_f32_16x16x32_bf16 v[52:55], v[156:159], v[200:203], v[52:55]
	v_mfma_f32_16x16x32_bf16 v[44:47], v[164:167], v[200:203], v[44:47]
	v_mfma_f32_16x16x32_bf16 v[36:39], v[156:159], v[208:211], v[36:39]
	v_mfma_f32_16x16x32_bf16 v[28:31], v[164:167], v[208:211], v[28:31]
	v_mfma_f32_16x16x32_bf16 v[20:23], v[156:159], v[216:219], v[20:23]
	v_mfma_f32_16x16x32_bf16 v[12:15], v[164:167], v[216:219], v[12:15]
	s_setprio 0
	s_setprio 1
	v_mfma_f32_16x16x32_bf16 v[48:51], v[168:171], v[184:187], v[48:51]
	v_mfma_f32_16x16x32_bf16 v[40:43], v[176:179], v[184:187], v[40:43]
	v_mfma_f32_16x16x32_bf16 v[32:35], v[168:171], v[196:199], v[32:35]
	v_mfma_f32_16x16x32_bf16 v[24:27], v[176:179], v[196:199], v[24:27]
	v_mfma_f32_16x16x32_bf16 v[16:19], v[168:171], v[204:207], v[16:19]
	v_mfma_f32_16x16x32_bf16 v[8:11], v[176:179], v[204:207], v[8:11]
	v_mfma_f32_16x16x32_bf16 v[4:7], v[168:171], v[212:215], v[4:7]
	v_mfma_f32_16x16x32_bf16 v[0:3], v[176:179], v[212:215], v[0:3]
	v_mfma_f32_16x16x32_bf16 v[48:51], v[172:175], v[192:195], v[48:51]
	v_mfma_f32_16x16x32_bf16 v[40:43], v[180:183], v[192:195], v[40:43]
	v_mfma_f32_16x16x32_bf16 v[32:35], v[172:175], v[200:203], v[32:35]
	v_mfma_f32_16x16x32_bf16 v[24:27], v[180:183], v[200:203], v[24:27]
	v_mfma_f32_16x16x32_bf16 v[16:19], v[172:175], v[208:211], v[16:19]
	v_mfma_f32_16x16x32_bf16 v[8:11], v[180:183], v[208:211], v[8:11]
	v_mfma_f32_16x16x32_bf16 v[4:7], v[172:175], v[216:219], v[4:7]
	v_mfma_f32_16x16x32_bf16 v[0:3], v[180:183], v[216:219], v[0:3]
	s_setprio 0
	s_barrier
	s_add_i32 s86, s86, 2
	s_add_u32 s60, s60, 0x100
	s_addc_u32 s61, s61, 0
	s_add_u32 s84, s84, 0x100
	s_addc_u32 s85, s85, 0
	s_cmp_gt_u32 s86, 13
	s_cbranch_scc0 .LBB0_272
	s_and_b64 vcc, exec, s[12:13]
	s_cbranch_vccz .LBB0_277
	s_barrier
	v_lshl_add_u32 v148, s42, 8, v150
	s_cmp_gt_i32 s54, 7
	s_mov_b64 s[42:43], -1
	s_cbranch_scc1 .LBB0_278

.LBB0_302:
	ds_read_b128 v[152:155], v149
	ds_read_b128 v[156:159], v149 offset:1024
	ds_read_b128 v[160:163], v149 offset:2048
	ds_read_b128 v[164:167], v149 offset:3072
	ds_read_b128 v[168:171], v150
	ds_read_b128 v[172:175], v150 offset:1024
	ds_read_b128 v[176:179], v150 offset:2048
	ds_read_b128 v[180:183], v150 offset:3072
	s_add_u32 s38, s36, 0xfffc0080
	s_addc_u32 s39, s37, -1
	s_cmp_eq_u32 s75, 12
	s_cselect_b32 s41, s27, s39
	s_cselect_b32 s40, s55, s38
	s_cselect_b32 s39, s25, s74
	s_cselect_b32 s38, s72, s73
	v_lshl_add_u64 v[144:145], s[36:37], 0, v[136:137]
	s_add_i32 m0, s35, 0xc000
	ds_read_b128 v[184:187], v151
	ds_read_b128 v[192:195], v151 offset:1024
	ds_read_b128 v[196:199], v151 offset:2048
	ds_read_b128 v[200:203], v151 offset:3072
	ds_read_b128 v[204:207], v151 offset:4096
	ds_read_b128 v[208:211], v151 offset:5120
	ds_read_b128 v[212:215], v151 offset:6144
	ds_read_b128 v[216:219], v151 offset:7168
	global_load_lds_dwordx4 v[144:145], off
	s_add_i32 m0, s35, 0xe000
	s_nop 0
	global_load_lds_dwordx4 v138, s[36:37]
	s_waitcnt vmcnt(8)
	s_waitcnt lgkmcnt(0)
	s_barrier
	s_setprio 1
	s_waitcnt lgkmcnt(0)
	v_mfma_f32_16x16x32_bf16 v[124:127], v[152:155], v[184:187], v[124:127]
	v_mfma_f32_16x16x32_bf16 v[120:123], v[160:163], v[184:187], v[120:123]
	v_mfma_f32_16x16x32_bf16 v[116:119], v[152:155], v[196:199], v[116:119]
	v_mfma_f32_16x16x32_bf16 v[108:111], v[160:163], v[196:199], v[108:111]
	v_mfma_f32_16x16x32_bf16 v[100:103], v[152:155], v[204:207], v[100:103]
	v_mfma_f32_16x16x32_bf16 v[92:95], v[160:163], v[204:207], v[92:95]
	v_mfma_f32_16x16x32_bf16 v[84:87], v[152:155], v[212:215], v[84:87]
	v_mfma_f32_16x16x32_bf16 v[76:79], v[160:163], v[212:215], v[76:79]
	v_mfma_f32_16x16x32_bf16 v[124:127], v[156:159], v[192:195], v[124:127]
	v_mfma_f32_16x16x32_bf16 v[120:123], v[164:167], v[192:195], v[120:123]
	v_mfma_f32_16x16x32_bf16 v[116:119], v[156:159], v[200:203], v[116:119]
	v_mfma_f32_16x16x32_bf16 v[108:111], v[164:167], v[200:203], v[108:111]
	v_mfma_f32_16x16x32_bf16 v[100:103], v[156:159], v[208:211], v[100:103]
	v_mfma_f32_16x16x32_bf16 v[92:95], v[164:167], v[208:211], v[92:95]
	v_mfma_f32_16x16x32_bf16 v[84:87], v[156:159], v[216:219], v[84:87]
	v_mfma_f32_16x16x32_bf16 v[76:79], v[164:167], v[216:219], v[76:79]
	s_setprio 0
	s_setprio 1
	v_mfma_f32_16x16x32_bf16 v[112:115], v[168:171], v[184:187], v[112:115]
	v_mfma_f32_16x16x32_bf16 v[104:107], v[176:179], v[184:187], v[104:107]
	v_mfma_f32_16x16x32_bf16 v[96:99], v[168:171], v[196:199], v[96:99]
	v_mfma_f32_16x16x32_bf16 v[88:91], v[176:179], v[196:199], v[88:91]
	v_mfma_f32_16x16x32_bf16 v[80:83], v[168:171], v[204:207], v[80:83]
	v_mfma_f32_16x16x32_bf16 v[72:75], v[176:179], v[204:207], v[72:75]
	v_mfma_f32_16x16x32_bf16 v[68:71], v[168:171], v[212:215], v[68:71]
	v_mfma_f32_16x16x32_bf16 v[64:67], v[176:179], v[212:215], v[64:67]
	v_mfma_f32_16x16x32_bf16 v[112:115], v[172:175], v[192:195], v[112:115]
	v_mfma_f32_16x16x32_bf16 v[104:107], v[180:183], v[192:195], v[104:107]
	v_mfma_f32_16x16x32_bf16 v[96:99], v[172:175], v[200:203], v[96:99]
	v_mfma_f32_16x16x32_bf16 v[88:91], v[180:183], v[200:203], v[88:91]
	v_mfma_f32_16x16x32_bf16 v[80:83], v[172:175], v[208:211], v[80:83]
	v_mfma_f32_16x16x32_bf16 v[72:75], v[180:183], v[208:211], v[72:75]
	v_mfma_f32_16x16x32_bf16 v[68:71], v[172:175], v[216:219], v[68:71]
	v_mfma_f32_16x16x32_bf16 v[64:67], v[180:183], v[216:219], v[64:67]
	s_setprio 0
	s_barrier
	s_add_i32 s76, s66, s53
	s_add_u32 s98, s38, 0x80
	s_addc_u32 s99, s39, 0
	s_mov_b32 m0, s76
	ds_read_b128 v[184:187], v151 offset:16384
	ds_read_b128 v[192:195], v151 offset:17408
	ds_read_b128 v[196:199], v151 offset:18432
	ds_read_b128 v[200:203], v151 offset:19456
	ds_read_b128 v[204:207], v151 offset:20480
	ds_read_b128 v[208:211], v151 offset:21504
	ds_read_b128 v[212:215], v151 offset:22528
	ds_read_b128 v[216:219], v151 offset:23552
	global_load_lds_dwordx4 v130, s[38:39]
	s_add_i32 m0, s76, 0x2000
	s_add_u32 s76, s38, 0x40000
	s_addc_u32 s77, s39, 0
	s_add_i32 s80, s67, s53
	global_load_lds_dwordx4 v134, s[38:39]
	s_mov_b32 m0, s80
	s_add_u32 s100, s40, 0x80
	s_addc_u32 s101, s41, 0
	global_load_lds_dwordx4 v130, s[76:77]
	s_add_i32 m0, s80, 0x2000
	s_nop 0
	global_load_lds_dwordx4 v134, s[76:77]
	s_mov_b32 m0, s35
	s_nop 0
	global_load_lds_dwordx4 v128, s[40:41]
	s_mov_b32 m0, s33
	s_nop 0
	global_load_lds_dwordx4 v132, s[40:41]
	s_waitcnt vmcnt(8)
	s_waitcnt lgkmcnt(0)
	s_barrier
	s_setprio 1
	s_waitcnt lgkmcnt(0)
	v_mfma_f32_16x16x32_bf16 v[60:63], v[152:155], v[184:187], v[60:63]
	v_mfma_f32_16x16x32_bf16 v[56:59], v[160:163], v[184:187], v[56:59]
	v_mfma_f32_16x16x32_bf16 v[52:55], v[152:155], v[196:199], v[52:55]
	v_mfma_f32_16x16x32_bf16 v[44:47], v[160:163], v[196:199], v[44:47]
	v_mfma_f32_16x16x32_bf16 v[36:39], v[152:155], v[204:207], v[36:39]
	v_mfma_f32_16x16x32_bf16 v[28:31], v[160:163], v[204:207], v[28:31]
	v_mfma_f32_16x16x32_bf16 v[20:23], v[152:155], v[212:215], v[20:23]
	v_mfma_f32_16x16x32_bf16 v[12:15], v[160:163], v[212:215], v[12:15]
	v_mfma_f32_16x16x32_bf16 v[60:63], v[156:159], v[192:195], v[60:63]
	v_mfma_f32_16x16x32_bf16 v[56:59], v[164:167], v[192:195], v[56:59]
	v_mfma_f32_16x16x32_bf16 v[52:55], v[156:159], v[200:203], v[52:55]
	v_mfma_f32_16x16x32_bf16 v[44:47], v[164:167], v[200:203], v[44:47]
	v_mfma_f32_16x16x32_bf16 v[36:39], v[156:159], v[208:211], v[36:39]
	v_mfma_f32_16x16x32_bf16 v[28:31], v[164:167], v[208:211], v[28:31]
	v_mfma_f32_16x16x32_bf16 v[20:23], v[156:159], v[216:219], v[20:23]
	v_mfma_f32_16x16x32_bf16 v[12:15], v[164:167], v[216:219], v[12:15]
	s_setprio 0
	s_setprio 1
	v_mfma_f32_16x16x32_bf16 v[48:51], v[168:171], v[184:187], v[48:51]
	v_mfma_f32_16x16x32_bf16 v[40:43], v[176:179], v[184:187], v[40:43]
	v_mfma_f32_16x16x32_bf16 v[32:35], v[168:171], v[196:199], v[32:35]
	v_mfma_f32_16x16x32_bf16 v[24:27], v[176:179], v[196:199], v[24:27]
	v_mfma_f32_16x16x32_bf16 v[16:19], v[168:171], v[204:207], v[16:19]
	v_mfma_f32_16x16x32_bf16 v[8:11], v[176:179], v[204:207], v[8:11]
	v_mfma_f32_16x16x32_bf16 v[4:7], v[168:171], v[212:215], v[4:7]
	v_mfma_f32_16x16x32_bf16 v[0:3], v[176:179], v[212:215], v[0:3]
	v_mfma_f32_16x16x32_bf16 v[48:51], v[172:175], v[192:195], v[48:51]
	v_mfma_f32_16x16x32_bf16 v[40:43], v[180:183], v[192:195], v[40:43]
	v_mfma_f32_16x16x32_bf16 v[32:35], v[172:175], v[200:203], v[32:35]
	v_mfma_f32_16x16x32_bf16 v[24:27], v[180:183], v[200:203], v[24:27]
	v_mfma_f32_16x16x32_bf16 v[16:19], v[172:175], v[208:211], v[16:19]
	v_mfma_f32_16x16x32_bf16 v[8:11], v[180:183], v[208:211], v[8:11]
	v_mfma_f32_16x16x32_bf16 v[4:7], v[172:175], v[216:219], v[4:7]
	v_mfma_f32_16x16x32_bf16 v[0:3], v[180:183], v[216:219], v[0:3]
	s_setprio 0
	s_barrier
	s_add_i32 s76, 0, 0x18000
	s_add_i32 s77, 0, 0x1c000
	v_add_u32_e32 v164, s76, v147
	v_add_u32_e32 v180, s77, v147
	ds_read_b128 v[152:155], v164
	ds_read_b128 v[156:159], v164 offset:1024
	ds_read_b128 v[160:163], v164 offset:2048
	ds_read_b128 v[164:167], v164 offset:3072
	ds_read_b128 v[168:171], v180
	ds_read_b128 v[172:175], v180 offset:1024
	ds_read_b128 v[176:179], v180 offset:2048
	ds_read_b128 v[180:183], v180 offset:3072
	s_add_u32 s40, s40, 0x40000
	s_addc_u32 s41, s41, 0
	s_mov_b32 m0, s60
	ds_read_b128 v[184:187], v151 offset:32768
	ds_read_b128 v[192:195], v151 offset:33792
	ds_read_b128 v[196:199], v151 offset:34816
	ds_read_b128 v[200:203], v151 offset:35840
	ds_read_b128 v[204:207], v151 offset:36864
	ds_read_b128 v[208:211], v151 offset:37888
	ds_read_b128 v[212:215], v151 offset:38912
	ds_read_b128 v[216:219], v151 offset:39936
	global_load_lds_dwordx4 v128, s[40:41]
	s_mov_b32 m0, s61
	s_nop 0
	global_load_lds_dwordx4 v132, s[40:41]
	s_waitcnt vmcnt(8)
	s_waitcnt lgkmcnt(0)
	s_barrier
	s_setprio 1
	s_waitcnt lgkmcnt(0)
	v_mfma_f32_16x16x32_bf16 v[124:127], v[152:155], v[184:187], v[124:127]
	v_mfma_f32_16x16x32_bf16 v[120:123], v[160:163], v[184:187], v[120:123]
	v_mfma_f32_16x16x32_bf16 v[116:119], v[152:155], v[196:199], v[116:119]
	v_mfma_f32_16x16x32_bf16 v[108:111], v[160:163], v[196:199], v[108:111]
	v_mfma_f32_16x16x32_bf16 v[100:103], v[152:155], v[204:207], v[100:103]
	v_mfma_f32_16x16x32_bf16 v[92:95], v[160:163], v[204:207], v[92:95]
	v_mfma_f32_16x16x32_bf16 v[84:87], v[152:155], v[212:215], v[84:87]
	v_mfma_f32_16x16x32_bf16 v[76:79], v[160:163], v[212:215], v[76:79]
	v_mfma_f32_16x16x32_bf16 v[124:127], v[156:159], v[192:195], v[124:127]
	v_mfma_f32_16x16x32_bf16 v[120:123], v[164:167], v[192:195], v[120:123]
	v_mfma_f32_16x16x32_bf16 v[116:119], v[156:159], v[200:203], v[116:119]
	v_mfma_f32_16x16x32_bf16 v[108:111], v[164:167], v[200:203], v[108:111]
	v_mfma_f32_16x16x32_bf16 v[100:103], v[156:159], v[208:211], v[100:103]
	v_mfma_f32_16x16x32_bf16 v[92:95], v[164:167], v[208:211], v[92:95]
	v_mfma_f32_16x16x32_bf16 v[84:87], v[156:159], v[216:219], v[84:87]
	v_mfma_f32_16x16x32_bf16 v[76:79], v[164:167], v[216:219], v[76:79]
	s_setprio 0
	s_setprio 1
	v_mfma_f32_16x16x32_bf16 v[112:115], v[168:171], v[184:187], v[112:115]
	v_mfma_f32_16x16x32_bf16 v[104:107], v[176:179], v[184:187], v[104:107]
	v_mfma_f32_16x16x32_bf16 v[96:99], v[168:171], v[196:199], v[96:99]
	v_mfma_f32_16x16x32_bf16 v[88:91], v[176:179], v[196:199], v[88:91]
	v_mfma_f32_16x16x32_bf16 v[80:83], v[168:171], v[204:207], v[80:83]
	v_mfma_f32_16x16x32_bf16 v[72:75], v[176:179], v[204:207], v[72:75]
	v_mfma_f32_16x16x32_bf16 v[68:71], v[168:171], v[212:215], v[68:71]
	v_mfma_f32_16x16x32_bf16 v[64:67], v[176:179], v[212:215], v[64:67]
	v_mfma_f32_16x16x32_bf16 v[112:115], v[172:175], v[192:195], v[112:115]
	v_mfma_f32_16x16x32_bf16 v[104:107], v[180:183], v[192:195], v[104:107]
	v_mfma_f32_16x16x32_bf16 v[96:99], v[172:175], v[200:203], v[96:99]
	v_mfma_f32_16x16x32_bf16 v[88:91], v[180:183], v[200:203], v[88:91]
	v_mfma_f32_16x16x32_bf16 v[80:83], v[172:175], v[208:211], v[80:83]
	v_mfma_f32_16x16x32_bf16 v[72:75], v[180:183], v[208:211], v[72:75]
	v_mfma_f32_16x16x32_bf16 v[68:71], v[172:175], v[216:219], v[68:71]
	v_mfma_f32_16x16x32_bf16 v[64:67], v[180:183], v[216:219], v[64:67]
	s_setprio 0
	s_barrier
	s_add_i32 s40, s76, s53
	s_mov_b32 m0, s40
	ds_read_b128 v[184:187], v151 offset:49152
	ds_read_b128 v[192:195], v151 offset:50176
	ds_read_b128 v[196:199], v151 offset:51200
	ds_read_b128 v[200:203], v151 offset:52224
	ds_read_b128 v[204:207], v151 offset:53248
	ds_read_b128 v[208:211], v151 offset:54272
	ds_read_b128 v[212:215], v151 offset:55296
	ds_read_b128 v[216:219], v151 offset:56320
	global_load_lds_dwordx4 v130, s[98:99]
	s_add_i32 m0, s40, 0x2000
	s_add_u32 s38, s38, 0x40080
	s_addc_u32 s39, s39, 0
	s_add_i32 s40, s77, s53
	global_load_lds_dwordx4 v134, s[98:99]
	s_mov_b32 m0, s40
	s_nop 0
	global_load_lds_dwordx4 v130, s[38:39]
	s_add_i32 m0, s40, 0x2000
	s_nop 0
	global_load_lds_dwordx4 v134, s[38:39]
	s_mov_b32 m0, s63
	s_nop 0
	global_load_lds_dwordx4 v128, s[100:101]
	s_mov_b32 m0, s64
	s_nop 0
	global_load_lds_dwordx4 v132, s[100:101]
	s_waitcnt vmcnt(8)
	s_waitcnt lgkmcnt(0)
	s_barrier
	s_setprio 1
	s_waitcnt lgkmcnt(0)
	v_mfma_f32_16x16x32_bf16 v[60:63], v[152:155], v[184:187], v[60:63]
	v_mfma_f32_16x16x32_bf16 v[56:59], v[160:163], v[184:187], v[56:59]
	v_mfma_f32_16x16x32_bf16 v[52:55], v[152:155], v[196:199], v[52:55]
	v_mfma_f32_16x16x32_bf16 v[44:47], v[160:163], v[196:199], v[44:47]
	v_mfma_f32_16x16x32_bf16 v[36:39], v[152:155], v[204:207], v[36:39]
	v_mfma_f32_16x16x32_bf16 v[28:31], v[160:163], v[204:207], v[28:31]
	v_mfma_f32_16x16x32_bf16 v[20:23], v[152:155], v[212:215], v[20:23]
	v_mfma_f32_16x16x32_bf16 v[12:15], v[160:163], v[212:215], v[12:15]
	v_mfma_f32_16x16x32_bf16 v[60:63], v[156:159], v[192:195], v[60:63]
	v_mfma_f32_16x16x32_bf16 v[56:59], v[164:167], v[192:195], v[56:59]
	v_mfma_f32_16x16x32_bf16 v[52:55], v[156:159], v[200:203], v[52:55]
	v_mfma_f32_16x16x32_bf16 v[44:47], v[164:167], v[200:203], v[44:47]
	v_mfma_f32_16x16x32_bf16 v[36:39], v[156:159], v[208:211], v[36:39]
	v_mfma_f32_16x16x32_bf16 v[28:31], v[164:167], v[208:211], v[28:31]
	v_mfma_f32_16x16x32_bf16 v[20:23], v[156:159], v[216:219], v[20:23]
	v_mfma_f32_16x16x32_bf16 v[12:15], v[164:167], v[216:219], v[12:15]
	s_setprio 0
	s_setprio 1
	v_mfma_f32_16x16x32_bf16 v[48:51], v[168:171], v[184:187], v[48:51]
	v_mfma_f32_16x16x32_bf16 v[40:43], v[176:179], v[184:187], v[40:43]
	v_mfma_f32_16x16x32_bf16 v[32:35], v[168:171], v[196:199], v[32:35]
	v_mfma_f32_16x16x32_bf16 v[24:27], v[176:179], v[196:199], v[24:27]
	v_mfma_f32_16x16x32_bf16 v[16:19], v[168:171], v[204:207], v[16:19]
	v_mfma_f32_16x16x32_bf16 v[8:11], v[176:179], v[204:207], v[8:11]
	v_mfma_f32_16x16x32_bf16 v[4:7], v[168:171], v[212:215], v[4:7]
	v_mfma_f32_16x16x32_bf16 v[0:3], v[176:179], v[212:215], v[0:3]
	v_mfma_f32_16x16x32_bf16 v[48:51], v[172:175], v[192:195], v[48:51]
	v_mfma_f32_16x16x32_bf16 v[40:43], v[180:183], v[192:195], v[40:43]
	v_mfma_f32_16x16x32_bf16 v[32:35], v[172:175], v[200:203], v[32:35]
	v_mfma_f32_16x16x32_bf16 v[24:27], v[180:183], v[200:203], v[24:27]
	v_mfma_f32_16x16x32_bf16 v[16:19], v[172:175], v[208:211], v[16:19]
	v_mfma_f32_16x16x32_bf16 v[8:11], v[180:183], v[208:211], v[8:11]
	v_mfma_f32_16x16x32_bf16 v[4:7], v[172:175], v[216:219], v[4:7]
	v_mfma_f32_16x16x32_bf16 v[0:3], v[180:183], v[216:219], v[0:3]
	s_setprio 0
	s_barrier
	s_add_i32 s75, s75, 2
	s_add_u32 s36, s36, 0x100
	s_addc_u32 s37, s37, 0
	s_add_u32 s73, s73, 0x100
	s_addc_u32 s74, s74, 0
	s_cmp_gt_u32 s75, 13
	s_cbranch_scc0 .LBB0_302
	s_and_b64 vcc, exec, s[14:15]
	s_cbranch_vccz .LBB0_305
	s_barrier

.LBB0_700:
	ds_read_b128 v[152:155], v149
	ds_read_b128 v[156:159], v149 offset:1024
	ds_read_b128 v[160:163], v149 offset:2048
	ds_read_b128 v[164:167], v149 offset:3072
	ds_read_b128 v[168:171], v150
	ds_read_b128 v[172:175], v150 offset:1024
	ds_read_b128 v[176:179], v150 offset:2048
	ds_read_b128 v[180:183], v150 offset:3072
	s_add_u32 s38, s34, 0xfffc0080
	s_addc_u32 s39, s35, -1
	s_cmp_eq_u32 s75, 12
	s_cselect_b32 s41, s25, s39
	s_cselect_b32 s40, s55, s38
	s_cselect_b32 s39, s23, s74
	s_cselect_b32 s38, s72, s73
	s_add_i32 m0, s31, 0xc000
	ds_read_b128 v[184:187], v151
	ds_read_b128 v[192:195], v151 offset:1024
	ds_read_b128 v[196:199], v151 offset:2048
	ds_read_b128 v[200:203], v151 offset:3072
	ds_read_b128 v[204:207], v151 offset:4096
	ds_read_b128 v[208:211], v151 offset:5120
	ds_read_b128 v[212:215], v151 offset:6144
	ds_read_b128 v[216:219], v151 offset:7168
	global_load_lds_dwordx4 v136, s[34:35]
	s_add_i32 m0, s31, 0xe000
	s_nop 0
	global_load_lds_dwordx4 v138, s[34:35]
	s_waitcnt vmcnt(8)
	s_waitcnt lgkmcnt(0)
	s_barrier
	s_setprio 1
	s_waitcnt lgkmcnt(0)
	v_mfma_f32_16x16x32_bf16 v[124:127], v[152:155], v[184:187], v[124:127]
	v_mfma_f32_16x16x32_bf16 v[120:123], v[160:163], v[184:187], v[120:123]
	v_mfma_f32_16x16x32_bf16 v[116:119], v[152:155], v[196:199], v[116:119]
	v_mfma_f32_16x16x32_bf16 v[108:111], v[160:163], v[196:199], v[108:111]
	v_mfma_f32_16x16x32_bf16 v[100:103], v[152:155], v[204:207], v[100:103]
	v_mfma_f32_16x16x32_bf16 v[92:95], v[160:163], v[204:207], v[92:95]
	v_mfma_f32_16x16x32_bf16 v[84:87], v[152:155], v[212:215], v[84:87]
	v_mfma_f32_16x16x32_bf16 v[76:79], v[160:163], v[212:215], v[76:79]
	v_mfma_f32_16x16x32_bf16 v[124:127], v[156:159], v[192:195], v[124:127]
	v_mfma_f32_16x16x32_bf16 v[120:123], v[164:167], v[192:195], v[120:123]
	v_mfma_f32_16x16x32_bf16 v[116:119], v[156:159], v[200:203], v[116:119]
	v_mfma_f32_16x16x32_bf16 v[108:111], v[164:167], v[200:203], v[108:111]
	v_mfma_f32_16x16x32_bf16 v[100:103], v[156:159], v[208:211], v[100:103]
	v_mfma_f32_16x16x32_bf16 v[92:95], v[164:167], v[208:211], v[92:95]
	v_mfma_f32_16x16x32_bf16 v[84:87], v[156:159], v[216:219], v[84:87]
	v_mfma_f32_16x16x32_bf16 v[76:79], v[164:167], v[216:219], v[76:79]
	s_setprio 0
	s_setprio 1
	v_mfma_f32_16x16x32_bf16 v[112:115], v[168:171], v[184:187], v[112:115]
	v_mfma_f32_16x16x32_bf16 v[104:107], v[176:179], v[184:187], v[104:107]
	v_mfma_f32_16x16x32_bf16 v[96:99], v[168:171], v[196:199], v[96:99]
	v_mfma_f32_16x16x32_bf16 v[88:91], v[176:179], v[196:199], v[88:91]
	v_mfma_f32_16x16x32_bf16 v[80:83], v[168:171], v[204:207], v[80:83]
	v_mfma_f32_16x16x32_bf16 v[72:75], v[176:179], v[204:207], v[72:75]
	v_mfma_f32_16x16x32_bf16 v[68:71], v[168:171], v[212:215], v[68:71]
	v_mfma_f32_16x16x32_bf16 v[64:67], v[176:179], v[212:215], v[64:67]
	v_mfma_f32_16x16x32_bf16 v[112:115], v[172:175], v[192:195], v[112:115]
	v_mfma_f32_16x16x32_bf16 v[104:107], v[180:183], v[192:195], v[104:107]
	v_mfma_f32_16x16x32_bf16 v[96:99], v[172:175], v[200:203], v[96:99]
	v_mfma_f32_16x16x32_bf16 v[88:91], v[180:183], v[200:203], v[88:91]
	v_mfma_f32_16x16x32_bf16 v[80:83], v[172:175], v[208:211], v[80:83]
	v_mfma_f32_16x16x32_bf16 v[72:75], v[180:183], v[208:211], v[72:75]
	v_mfma_f32_16x16x32_bf16 v[68:71], v[172:175], v[216:219], v[68:71]
	v_mfma_f32_16x16x32_bf16 v[64:67], v[180:183], v[216:219], v[64:67]
	s_setprio 0
	s_barrier
	s_add_i32 s76, s66, s53
	s_add_u32 s98, s38, 0x80
	s_addc_u32 s99, s39, 0
	s_mov_b32 m0, s76
	ds_read_b128 v[184:187], v151 offset:16384
	ds_read_b128 v[192:195], v151 offset:17408
	ds_read_b128 v[196:199], v151 offset:18432
	ds_read_b128 v[200:203], v151 offset:19456
	ds_read_b128 v[204:207], v151 offset:20480
	ds_read_b128 v[208:211], v151 offset:21504
	ds_read_b128 v[212:215], v151 offset:22528
	ds_read_b128 v[216:219], v151 offset:23552
	global_load_lds_dwordx4 v130, s[38:39]
	s_add_i32 m0, s76, 0x2000
	s_add_u32 s76, s38, 0x40000
	s_addc_u32 s77, s39, 0
	s_add_i32 s79, s67, s53
	global_load_lds_dwordx4 v134, s[38:39]
	s_mov_b32 m0, s79
	s_add_u32 s100, s40, 0x80
	s_addc_u32 s101, s41, 0
	global_load_lds_dwordx4 v130, s[76:77]
	s_add_i32 m0, s79, 0x2000
	s_nop 0
	global_load_lds_dwordx4 v134, s[76:77]
	s_mov_b32 m0, s31
	s_nop 0
	global_load_lds_dwordx4 v128, s[40:41]
	s_mov_b32 m0, s33
	s_nop 0
	global_load_lds_dwordx4 v132, s[40:41]
	s_waitcnt vmcnt(8)
	s_waitcnt lgkmcnt(0)
	s_barrier
	s_setprio 1
	s_waitcnt lgkmcnt(0)
	v_mfma_f32_16x16x32_bf16 v[60:63], v[152:155], v[184:187], v[60:63]
	v_mfma_f32_16x16x32_bf16 v[56:59], v[160:163], v[184:187], v[56:59]
	v_mfma_f32_16x16x32_bf16 v[52:55], v[152:155], v[196:199], v[52:55]
	v_mfma_f32_16x16x32_bf16 v[44:47], v[160:163], v[196:199], v[44:47]
	v_mfma_f32_16x16x32_bf16 v[36:39], v[152:155], v[204:207], v[36:39]
	v_mfma_f32_16x16x32_bf16 v[28:31], v[160:163], v[204:207], v[28:31]
	v_mfma_f32_16x16x32_bf16 v[20:23], v[152:155], v[212:215], v[20:23]
	v_mfma_f32_16x16x32_bf16 v[12:15], v[160:163], v[212:215], v[12:15]
	v_mfma_f32_16x16x32_bf16 v[60:63], v[156:159], v[192:195], v[60:63]
	v_mfma_f32_16x16x32_bf16 v[56:59], v[164:167], v[192:195], v[56:59]
	v_mfma_f32_16x16x32_bf16 v[52:55], v[156:159], v[200:203], v[52:55]
	v_mfma_f32_16x16x32_bf16 v[44:47], v[164:167], v[200:203], v[44:47]
	v_mfma_f32_16x16x32_bf16 v[36:39], v[156:159], v[208:211], v[36:39]
	v_mfma_f32_16x16x32_bf16 v[28:31], v[164:167], v[208:211], v[28:31]
	v_mfma_f32_16x16x32_bf16 v[20:23], v[156:159], v[216:219], v[20:23]
	v_mfma_f32_16x16x32_bf16 v[12:15], v[164:167], v[216:219], v[12:15]
	s_setprio 0
	s_setprio 1
	v_mfma_f32_16x16x32_bf16 v[48:51], v[168:171], v[184:187], v[48:51]
	v_mfma_f32_16x16x32_bf16 v[40:43], v[176:179], v[184:187], v[40:43]
	v_mfma_f32_16x16x32_bf16 v[32:35], v[168:171], v[196:199], v[32:35]
	v_mfma_f32_16x16x32_bf16 v[24:27], v[176:179], v[196:199], v[24:27]
	v_mfma_f32_16x16x32_bf16 v[16:19], v[168:171], v[204:207], v[16:19]
	v_mfma_f32_16x16x32_bf16 v[8:11], v[176:179], v[204:207], v[8:11]
	v_mfma_f32_16x16x32_bf16 v[4:7], v[168:171], v[212:215], v[4:7]
	v_mfma_f32_16x16x32_bf16 v[0:3], v[176:179], v[212:215], v[0:3]
	v_mfma_f32_16x16x32_bf16 v[48:51], v[172:175], v[192:195], v[48:51]
	v_mfma_f32_16x16x32_bf16 v[40:43], v[180:183], v[192:195], v[40:43]
	v_mfma_f32_16x16x32_bf16 v[32:35], v[172:175], v[200:203], v[32:35]
	v_mfma_f32_16x16x32_bf16 v[24:27], v[180:183], v[200:203], v[24:27]
	v_mfma_f32_16x16x32_bf16 v[16:19], v[172:175], v[208:211], v[16:19]
	v_mfma_f32_16x16x32_bf16 v[8:11], v[180:183], v[208:211], v[8:11]
	v_mfma_f32_16x16x32_bf16 v[4:7], v[172:175], v[216:219], v[4:7]
	v_mfma_f32_16x16x32_bf16 v[0:3], v[180:183], v[216:219], v[0:3]
	s_setprio 0
	s_barrier
	s_add_i32 s76, 0, 0x18000
	s_add_i32 s77, 0, 0x1c000
	v_add_u32_e32 v164, s76, v147
	v_add_u32_e32 v180, s77, v147
	ds_read_b128 v[152:155], v164
	ds_read_b128 v[156:159], v164 offset:1024
	ds_read_b128 v[160:163], v164 offset:2048
	ds_read_b128 v[164:167], v164 offset:3072
	ds_read_b128 v[168:171], v180
	ds_read_b128 v[172:175], v180 offset:1024
	ds_read_b128 v[176:179], v180 offset:2048
	ds_read_b128 v[180:183], v180 offset:3072
	s_add_u32 s40, s40, 0x40000
	s_addc_u32 s41, s41, 0
	s_mov_b32 m0, s60
	ds_read_b128 v[184:187], v151 offset:32768
	ds_read_b128 v[192:195], v151 offset:33792
	ds_read_b128 v[196:199], v151 offset:34816
	ds_read_b128 v[200:203], v151 offset:35840
	ds_read_b128 v[204:207], v151 offset:36864
	ds_read_b128 v[208:211], v151 offset:37888
	ds_read_b128 v[212:215], v151 offset:38912
	ds_read_b128 v[216:219], v151 offset:39936
	global_load_lds_dwordx4 v128, s[40:41]
	s_mov_b32 m0, s61
	s_nop 0
	global_load_lds_dwordx4 v132, s[40:41]
	s_waitcnt vmcnt(8)
	s_waitcnt lgkmcnt(0)
	s_barrier
	s_setprio 1
	s_waitcnt lgkmcnt(0)
	v_mfma_f32_16x16x32_bf16 v[124:127], v[152:155], v[184:187], v[124:127]
	v_mfma_f32_16x16x32_bf16 v[120:123], v[160:163], v[184:187], v[120:123]
	v_mfma_f32_16x16x32_bf16 v[116:119], v[152:155], v[196:199], v[116:119]
	v_mfma_f32_16x16x32_bf16 v[108:111], v[160:163], v[196:199], v[108:111]
	v_mfma_f32_16x16x32_bf16 v[100:103], v[152:155], v[204:207], v[100:103]
	v_mfma_f32_16x16x32_bf16 v[92:95], v[160:163], v[204:207], v[92:95]
	v_mfma_f32_16x16x32_bf16 v[84:87], v[152:155], v[212:215], v[84:87]
	v_mfma_f32_16x16x32_bf16 v[76:79], v[160:163], v[212:215], v[76:79]
	v_mfma_f32_16x16x32_bf16 v[124:127], v[156:159], v[192:195], v[124:127]
	v_mfma_f32_16x16x32_bf16 v[120:123], v[164:167], v[192:195], v[120:123]
	v_mfma_f32_16x16x32_bf16 v[116:119], v[156:159], v[200:203], v[116:119]
	v_mfma_f32_16x16x32_bf16 v[108:111], v[164:167], v[200:203], v[108:111]
	v_mfma_f32_16x16x32_bf16 v[100:103], v[156:159], v[208:211], v[100:103]
	v_mfma_f32_16x16x32_bf16 v[92:95], v[164:167], v[208:211], v[92:95]
	v_mfma_f32_16x16x32_bf16 v[84:87], v[156:159], v[216:219], v[84:87]
	v_mfma_f32_16x16x32_bf16 v[76:79], v[164:167], v[216:219], v[76:79]
	s_setprio 0
	s_setprio 1
	v_mfma_f32_16x16x32_bf16 v[112:115], v[168:171], v[184:187], v[112:115]
	v_mfma_f32_16x16x32_bf16 v[104:107], v[176:179], v[184:187], v[104:107]
	v_mfma_f32_16x16x32_bf16 v[96:99], v[168:171], v[196:199], v[96:99]
	v_mfma_f32_16x16x32_bf16 v[88:91], v[176:179], v[196:199], v[88:91]
	v_mfma_f32_16x16x32_bf16 v[80:83], v[168:171], v[204:207], v[80:83]
	v_mfma_f32_16x16x32_bf16 v[72:75], v[176:179], v[204:207], v[72:75]
	v_mfma_f32_16x16x32_bf16 v[68:71], v[168:171], v[212:215], v[68:71]
	v_mfma_f32_16x16x32_bf16 v[64:67], v[176:179], v[212:215], v[64:67]
	v_mfma_f32_16x16x32_bf16 v[112:115], v[172:175], v[192:195], v[112:115]
	v_mfma_f32_16x16x32_bf16 v[104:107], v[180:183], v[192:195], v[104:107]
	v_mfma_f32_16x16x32_bf16 v[96:99], v[172:175], v[200:203], v[96:99]
	v_mfma_f32_16x16x32_bf16 v[88:91], v[180:183], v[200:203], v[88:91]
	v_mfma_f32_16x16x32_bf16 v[80:83], v[172:175], v[208:211], v[80:83]
	v_mfma_f32_16x16x32_bf16 v[72:75], v[180:183], v[208:211], v[72:75]
	v_mfma_f32_16x16x32_bf16 v[68:71], v[172:175], v[216:219], v[68:71]
	v_mfma_f32_16x16x32_bf16 v[64:67], v[180:183], v[216:219], v[64:67]
	s_setprio 0
	s_barrier
	s_add_i32 s40, s76, s53
	s_mov_b32 m0, s40
	ds_read_b128 v[184:187], v151 offset:49152
	ds_read_b128 v[192:195], v151 offset:50176
	ds_read_b128 v[196:199], v151 offset:51200
	ds_read_b128 v[200:203], v151 offset:52224
	ds_read_b128 v[204:207], v151 offset:53248
	ds_read_b128 v[208:211], v151 offset:54272
	ds_read_b128 v[212:215], v151 offset:55296
	ds_read_b128 v[216:219], v151 offset:56320
	global_load_lds_dwordx4 v130, s[98:99]
	s_add_i32 m0, s40, 0x2000
	s_add_u32 s38, s38, 0x40080
	s_addc_u32 s39, s39, 0
	s_add_i32 s40, s77, s53
	global_load_lds_dwordx4 v134, s[98:99]
	s_mov_b32 m0, s40
	s_nop 0
	global_load_lds_dwordx4 v130, s[38:39]
	s_add_i32 m0, s40, 0x2000
	s_nop 0
	global_load_lds_dwordx4 v134, s[38:39]
	s_mov_b32 m0, s63
	s_nop 0
	global_load_lds_dwordx4 v128, s[100:101]
	s_mov_b32 m0, s64
	s_nop 0
	global_load_lds_dwordx4 v132, s[100:101]
	s_waitcnt vmcnt(8)
	s_waitcnt lgkmcnt(0)
	s_barrier
	s_setprio 1
	s_waitcnt lgkmcnt(0)
	v_mfma_f32_16x16x32_bf16 v[60:63], v[152:155], v[184:187], v[60:63]
	v_mfma_f32_16x16x32_bf16 v[56:59], v[160:163], v[184:187], v[56:59]
	v_mfma_f32_16x16x32_bf16 v[52:55], v[152:155], v[196:199], v[52:55]
	v_mfma_f32_16x16x32_bf16 v[44:47], v[160:163], v[196:199], v[44:47]
	v_mfma_f32_16x16x32_bf16 v[36:39], v[152:155], v[204:207], v[36:39]
	v_mfma_f32_16x16x32_bf16 v[28:31], v[160:163], v[204:207], v[28:31]
	v_mfma_f32_16x16x32_bf16 v[20:23], v[152:155], v[212:215], v[20:23]
	v_mfma_f32_16x16x32_bf16 v[12:15], v[160:163], v[212:215], v[12:15]
	v_mfma_f32_16x16x32_bf16 v[60:63], v[156:159], v[192:195], v[60:63]
	v_mfma_f32_16x16x32_bf16 v[56:59], v[164:167], v[192:195], v[56:59]
	v_mfma_f32_16x16x32_bf16 v[52:55], v[156:159], v[200:203], v[52:55]
	v_mfma_f32_16x16x32_bf16 v[44:47], v[164:167], v[200:203], v[44:47]
	v_mfma_f32_16x16x32_bf16 v[36:39], v[156:159], v[208:211], v[36:39]
	v_mfma_f32_16x16x32_bf16 v[28:31], v[164:167], v[208:211], v[28:31]
	v_mfma_f32_16x16x32_bf16 v[20:23], v[156:159], v[216:219], v[20:23]
	v_mfma_f32_16x16x32_bf16 v[12:15], v[164:167], v[216:219], v[12:15]
	s_setprio 0
	s_setprio 1
	v_mfma_f32_16x16x32_bf16 v[48:51], v[168:171], v[184:187], v[48:51]
	v_mfma_f32_16x16x32_bf16 v[40:43], v[176:179], v[184:187], v[40:43]
	v_mfma_f32_16x16x32_bf16 v[32:35], v[168:171], v[196:199], v[32:35]
	v_mfma_f32_16x16x32_bf16 v[24:27], v[176:179], v[196:199], v[24:27]
	v_mfma_f32_16x16x32_bf16 v[16:19], v[168:171], v[204:207], v[16:19]
	v_mfma_f32_16x16x32_bf16 v[8:11], v[176:179], v[204:207], v[8:11]
	v_mfma_f32_16x16x32_bf16 v[4:7], v[168:171], v[212:215], v[4:7]
	v_mfma_f32_16x16x32_bf16 v[0:3], v[176:179], v[212:215], v[0:3]
	v_mfma_f32_16x16x32_bf16 v[48:51], v[172:175], v[192:195], v[48:51]
	v_mfma_f32_16x16x32_bf16 v[40:43], v[180:183], v[192:195], v[40:43]
	v_mfma_f32_16x16x32_bf16 v[32:35], v[172:175], v[200:203], v[32:35]
	v_mfma_f32_16x16x32_bf16 v[24:27], v[180:183], v[200:203], v[24:27]
	v_mfma_f32_16x16x32_bf16 v[16:19], v[172:175], v[208:211], v[16:19]
	v_mfma_f32_16x16x32_bf16 v[8:11], v[180:183], v[208:211], v[8:11]
	v_mfma_f32_16x16x32_bf16 v[4:7], v[172:175], v[216:219], v[4:7]
	v_mfma_f32_16x16x32_bf16 v[0:3], v[180:183], v[216:219], v[0:3]
	s_setprio 0
	s_barrier
	s_add_i32 s75, s75, 2
	s_add_u32 s34, s34, 0x100
	s_addc_u32 s35, s35, 0
	s_add_u32 s73, s73, 0x100
	s_addc_u32 s74, s74, 0
	s_cmp_gt_u32 s75, 13
	s_cbranch_scc0 .LBB0_700
	s_and_b64 vcc, exec, s[14:15]
	s_cbranch_vccz .LBB0_703
	s_barrier

.LBB0_837:
	ds_read_b128 v[152:155], v149
	ds_read_b128 v[156:159], v149 offset:1024
	ds_read_b128 v[160:163], v149 offset:2048
	ds_read_b128 v[164:167], v149 offset:3072
	ds_read_b128 v[168:171], v150
	ds_read_b128 v[172:175], v150 offset:1024
	ds_read_b128 v[176:179], v150 offset:2048
	ds_read_b128 v[180:183], v150 offset:3072
	s_add_u32 s40, s34, 0xfffc0080
	s_addc_u32 s41, s35, -1
	s_cmp_eq_u32 s77, 12
	s_cselect_b32 s43, s25, s41
	s_cselect_b32 s42, s54, s40
	s_cselect_b32 s41, s23, s76
	s_cselect_b32 s40, s55, s75
	s_add_i32 m0, s31, 0xc000
	ds_read_b128 v[184:187], v151
	ds_read_b128 v[192:195], v151 offset:1024
	ds_read_b128 v[196:199], v151 offset:2048
	ds_read_b128 v[200:203], v151 offset:3072
	ds_read_b128 v[204:207], v151 offset:4096
	ds_read_b128 v[208:211], v151 offset:5120
	ds_read_b128 v[212:215], v151 offset:6144
	ds_read_b128 v[216:219], v151 offset:7168
	global_load_lds_dwordx4 v136, s[34:35]
	s_add_i32 m0, s31, 0xe000
	s_nop 0
	global_load_lds_dwordx4 v138, s[34:35]
	s_waitcnt vmcnt(8)
	s_waitcnt lgkmcnt(0)
	s_barrier
	s_setprio 1
	s_waitcnt lgkmcnt(0)
	v_mfma_f32_16x16x32_bf16 v[124:127], v[152:155], v[184:187], v[124:127]
	v_mfma_f32_16x16x32_bf16 v[120:123], v[160:163], v[184:187], v[120:123]
	v_mfma_f32_16x16x32_bf16 v[108:111], v[152:155], v[196:199], v[108:111]
	v_mfma_f32_16x16x32_bf16 v[104:107], v[160:163], v[196:199], v[104:107]
	v_mfma_f32_16x16x32_bf16 v[92:95], v[152:155], v[204:207], v[92:95]
	v_mfma_f32_16x16x32_bf16 v[88:91], v[160:163], v[204:207], v[88:91]
	v_mfma_f32_16x16x32_bf16 v[76:79], v[152:155], v[212:215], v[76:79]
	v_mfma_f32_16x16x32_bf16 v[72:75], v[160:163], v[212:215], v[72:75]
	v_mfma_f32_16x16x32_bf16 v[124:127], v[156:159], v[192:195], v[124:127]
	v_mfma_f32_16x16x32_bf16 v[120:123], v[164:167], v[192:195], v[120:123]
	v_mfma_f32_16x16x32_bf16 v[108:111], v[156:159], v[200:203], v[108:111]
	v_mfma_f32_16x16x32_bf16 v[104:107], v[164:167], v[200:203], v[104:107]
	v_mfma_f32_16x16x32_bf16 v[92:95], v[156:159], v[208:211], v[92:95]
	v_mfma_f32_16x16x32_bf16 v[88:91], v[164:167], v[208:211], v[88:91]
	v_mfma_f32_16x16x32_bf16 v[76:79], v[156:159], v[216:219], v[76:79]
	v_mfma_f32_16x16x32_bf16 v[72:75], v[164:167], v[216:219], v[72:75]
	s_setprio 0
	s_setprio 1
	v_mfma_f32_16x16x32_bf16 v[116:119], v[168:171], v[184:187], v[116:119]
	v_mfma_f32_16x16x32_bf16 v[112:115], v[176:179], v[184:187], v[112:115]
	v_mfma_f32_16x16x32_bf16 v[100:103], v[168:171], v[196:199], v[100:103]
	v_mfma_f32_16x16x32_bf16 v[96:99], v[176:179], v[196:199], v[96:99]
	v_mfma_f32_16x16x32_bf16 v[84:87], v[168:171], v[204:207], v[84:87]
	v_mfma_f32_16x16x32_bf16 v[80:83], v[176:179], v[204:207], v[80:83]
	v_mfma_f32_16x16x32_bf16 v[68:71], v[168:171], v[212:215], v[68:71]
	v_mfma_f32_16x16x32_bf16 v[64:67], v[176:179], v[212:215], v[64:67]
	v_mfma_f32_16x16x32_bf16 v[116:119], v[172:175], v[192:195], v[116:119]
	v_mfma_f32_16x16x32_bf16 v[112:115], v[180:183], v[192:195], v[112:115]
	v_mfma_f32_16x16x32_bf16 v[100:103], v[172:175], v[200:203], v[100:103]
	v_mfma_f32_16x16x32_bf16 v[96:99], v[180:183], v[200:203], v[96:99]
	v_mfma_f32_16x16x32_bf16 v[84:87], v[172:175], v[208:211], v[84:87]
	v_mfma_f32_16x16x32_bf16 v[80:83], v[180:183], v[208:211], v[80:83]
	v_mfma_f32_16x16x32_bf16 v[68:71], v[172:175], v[216:219], v[68:71]
	v_mfma_f32_16x16x32_bf16 v[64:67], v[180:183], v[216:219], v[64:67]
	s_setprio 0
	s_barrier
	s_add_i32 s79, s69, s63
	s_add_u32 s98, s40, 0x80
	s_addc_u32 s99, s41, 0
	s_mov_b32 m0, s79
	ds_read_b128 v[184:187], v151 offset:16384
	ds_read_b128 v[192:195], v151 offset:17408
	ds_read_b128 v[196:199], v151 offset:18432
	ds_read_b128 v[200:203], v151 offset:19456
	ds_read_b128 v[204:207], v151 offset:20480
	ds_read_b128 v[208:211], v151 offset:21504
	ds_read_b128 v[212:215], v151 offset:22528
	ds_read_b128 v[216:219], v151 offset:23552
	global_load_lds_dwordx4 v130, s[40:41]
	s_add_i32 m0, s79, 0x2000
	s_add_u32 s80, s40, 0x40000
	s_addc_u32 s81, s41, 0
	s_add_i32 s79, s70, s63
	global_load_lds_dwordx4 v134, s[40:41]
	s_mov_b32 m0, s79
	s_add_u32 s100, s42, 0x80
	s_addc_u32 s101, s43, 0
	global_load_lds_dwordx4 v130, s[80:81]
	s_add_i32 m0, s79, 0x2000
	s_nop 0
	global_load_lds_dwordx4 v134, s[80:81]
	s_mov_b32 m0, s31
	s_nop 0
	global_load_lds_dwordx4 v128, s[42:43]
	s_mov_b32 m0, s64
	s_nop 0
	global_load_lds_dwordx4 v132, s[42:43]
	s_waitcnt vmcnt(8)
	s_waitcnt lgkmcnt(0)
	s_barrier
	s_setprio 1
	s_waitcnt lgkmcnt(0)
	v_mfma_f32_16x16x32_bf16 v[60:63], v[152:155], v[184:187], v[60:63]
	v_mfma_f32_16x16x32_bf16 v[56:59], v[160:163], v[184:187], v[56:59]
	v_mfma_f32_16x16x32_bf16 v[44:47], v[152:155], v[196:199], v[44:47]
	v_mfma_f32_16x16x32_bf16 v[40:43], v[160:163], v[196:199], v[40:43]
	v_mfma_f32_16x16x32_bf16 v[28:31], v[152:155], v[204:207], v[28:31]
	v_mfma_f32_16x16x32_bf16 v[24:27], v[160:163], v[204:207], v[24:27]
	v_mfma_f32_16x16x32_bf16 v[12:15], v[152:155], v[212:215], v[12:15]
	v_mfma_f32_16x16x32_bf16 v[8:11], v[160:163], v[212:215], v[8:11]
	v_mfma_f32_16x16x32_bf16 v[60:63], v[156:159], v[192:195], v[60:63]
	v_mfma_f32_16x16x32_bf16 v[56:59], v[164:167], v[192:195], v[56:59]
	v_mfma_f32_16x16x32_bf16 v[44:47], v[156:159], v[200:203], v[44:47]
	v_mfma_f32_16x16x32_bf16 v[40:43], v[164:167], v[200:203], v[40:43]
	v_mfma_f32_16x16x32_bf16 v[28:31], v[156:159], v[208:211], v[28:31]
	v_mfma_f32_16x16x32_bf16 v[24:27], v[164:167], v[208:211], v[24:27]
	v_mfma_f32_16x16x32_bf16 v[12:15], v[156:159], v[216:219], v[12:15]
	v_mfma_f32_16x16x32_bf16 v[8:11], v[164:167], v[216:219], v[8:11]
	s_setprio 0
	s_setprio 1
	v_mfma_f32_16x16x32_bf16 v[52:55], v[168:171], v[184:187], v[52:55]
	v_mfma_f32_16x16x32_bf16 v[48:51], v[176:179], v[184:187], v[48:51]
	v_mfma_f32_16x16x32_bf16 v[36:39], v[168:171], v[196:199], v[36:39]
	v_mfma_f32_16x16x32_bf16 v[32:35], v[176:179], v[196:199], v[32:35]
	v_mfma_f32_16x16x32_bf16 v[20:23], v[168:171], v[204:207], v[20:23]
	v_mfma_f32_16x16x32_bf16 v[16:19], v[176:179], v[204:207], v[16:19]
	v_mfma_f32_16x16x32_bf16 v[4:7], v[168:171], v[212:215], v[4:7]
	v_mfma_f32_16x16x32_bf16 v[0:3], v[176:179], v[212:215], v[0:3]
	v_mfma_f32_16x16x32_bf16 v[52:55], v[172:175], v[192:195], v[52:55]
	v_mfma_f32_16x16x32_bf16 v[48:51], v[180:183], v[192:195], v[48:51]
	v_mfma_f32_16x16x32_bf16 v[36:39], v[172:175], v[200:203], v[36:39]
	v_mfma_f32_16x16x32_bf16 v[32:35], v[180:183], v[200:203], v[32:35]
	v_mfma_f32_16x16x32_bf16 v[20:23], v[172:175], v[208:211], v[20:23]
	v_mfma_f32_16x16x32_bf16 v[16:19], v[180:183], v[208:211], v[16:19]
	v_mfma_f32_16x16x32_bf16 v[4:7], v[172:175], v[216:219], v[4:7]
	v_mfma_f32_16x16x32_bf16 v[0:3], v[180:183], v[216:219], v[0:3]
	s_setprio 0
	s_barrier
	s_add_i32 s79, 0, 0x18000
	s_add_i32 s80, 0, 0x1c000
	v_add_u32_e32 v164, s79, v147
	v_add_u32_e32 v180, s80, v147
	ds_read_b128 v[152:155], v164
	ds_read_b128 v[156:159], v164 offset:1024
	ds_read_b128 v[160:163], v164 offset:2048
	ds_read_b128 v[164:167], v164 offset:3072
	ds_read_b128 v[168:171], v180
	ds_read_b128 v[172:175], v180 offset:1024
	ds_read_b128 v[176:179], v180 offset:2048
	ds_read_b128 v[180:183], v180 offset:3072
	s_add_u32 s42, s42, 0x40000
	s_addc_u32 s43, s43, 0
	s_mov_b32 m0, s65
	ds_read_b128 v[184:187], v151 offset:32768
	ds_read_b128 v[192:195], v151 offset:33792
	ds_read_b128 v[196:199], v151 offset:34816
	ds_read_b128 v[200:203], v151 offset:35840
	ds_read_b128 v[204:207], v151 offset:36864
	ds_read_b128 v[208:211], v151 offset:37888
	ds_read_b128 v[212:215], v151 offset:38912
	ds_read_b128 v[216:219], v151 offset:39936
	global_load_lds_dwordx4 v128, s[42:43]
	s_mov_b32 m0, s66
	s_nop 0
	global_load_lds_dwordx4 v132, s[42:43]
	s_waitcnt vmcnt(8)
	s_waitcnt lgkmcnt(0)
	s_barrier
	s_setprio 1
	s_waitcnt lgkmcnt(0)
	v_mfma_f32_16x16x32_bf16 v[124:127], v[152:155], v[184:187], v[124:127]
	v_mfma_f32_16x16x32_bf16 v[120:123], v[160:163], v[184:187], v[120:123]
	v_mfma_f32_16x16x32_bf16 v[108:111], v[152:155], v[196:199], v[108:111]
	v_mfma_f32_16x16x32_bf16 v[104:107], v[160:163], v[196:199], v[104:107]
	v_mfma_f32_16x16x32_bf16 v[92:95], v[152:155], v[204:207], v[92:95]
	v_mfma_f32_16x16x32_bf16 v[88:91], v[160:163], v[204:207], v[88:91]
	v_mfma_f32_16x16x32_bf16 v[76:79], v[152:155], v[212:215], v[76:79]
	v_mfma_f32_16x16x32_bf16 v[72:75], v[160:163], v[212:215], v[72:75]
	v_mfma_f32_16x16x32_bf16 v[124:127], v[156:159], v[192:195], v[124:127]
	v_mfma_f32_16x16x32_bf16 v[120:123], v[164:167], v[192:195], v[120:123]
	v_mfma_f32_16x16x32_bf16 v[108:111], v[156:159], v[200:203], v[108:111]
	v_mfma_f32_16x16x32_bf16 v[104:107], v[164:167], v[200:203], v[104:107]
	v_mfma_f32_16x16x32_bf16 v[92:95], v[156:159], v[208:211], v[92:95]
	v_mfma_f32_16x16x32_bf16 v[88:91], v[164:167], v[208:211], v[88:91]
	v_mfma_f32_16x16x32_bf16 v[76:79], v[156:159], v[216:219], v[76:79]
	v_mfma_f32_16x16x32_bf16 v[72:75], v[164:167], v[216:219], v[72:75]
	s_setprio 0
	s_setprio 1
	v_mfma_f32_16x16x32_bf16 v[116:119], v[168:171], v[184:187], v[116:119]
	v_mfma_f32_16x16x32_bf16 v[112:115], v[176:179], v[184:187], v[112:115]
	v_mfma_f32_16x16x32_bf16 v[100:103], v[168:171], v[196:199], v[100:103]
	v_mfma_f32_16x16x32_bf16 v[96:99], v[176:179], v[196:199], v[96:99]
	v_mfma_f32_16x16x32_bf16 v[84:87], v[168:171], v[204:207], v[84:87]
	v_mfma_f32_16x16x32_bf16 v[80:83], v[176:179], v[204:207], v[80:83]
	v_mfma_f32_16x16x32_bf16 v[68:71], v[168:171], v[212:215], v[68:71]
	v_mfma_f32_16x16x32_bf16 v[64:67], v[176:179], v[212:215], v[64:67]
	v_mfma_f32_16x16x32_bf16 v[116:119], v[172:175], v[192:195], v[116:119]
	v_mfma_f32_16x16x32_bf16 v[112:115], v[180:183], v[192:195], v[112:115]
	v_mfma_f32_16x16x32_bf16 v[100:103], v[172:175], v[200:203], v[100:103]
	v_mfma_f32_16x16x32_bf16 v[96:99], v[180:183], v[200:203], v[96:99]
	v_mfma_f32_16x16x32_bf16 v[84:87], v[172:175], v[208:211], v[84:87]
	v_mfma_f32_16x16x32_bf16 v[80:83], v[180:183], v[208:211], v[80:83]
	v_mfma_f32_16x16x32_bf16 v[68:71], v[172:175], v[216:219], v[68:71]
	v_mfma_f32_16x16x32_bf16 v[64:67], v[180:183], v[216:219], v[64:67]
	s_setprio 0
	s_barrier
	s_add_i32 s42, s79, s63
	s_mov_b32 m0, s42
	ds_read_b128 v[184:187], v151 offset:49152
	ds_read_b128 v[192:195], v151 offset:50176
	ds_read_b128 v[196:199], v151 offset:51200
	ds_read_b128 v[200:203], v151 offset:52224
	ds_read_b128 v[204:207], v151 offset:53248
	ds_read_b128 v[208:211], v151 offset:54272
	ds_read_b128 v[212:215], v151 offset:55296
	ds_read_b128 v[216:219], v151 offset:56320
	global_load_lds_dwordx4 v130, s[98:99]
	s_add_i32 m0, s42, 0x2000
	s_add_u32 s40, s40, 0x40080
	s_addc_u32 s41, s41, 0
	s_add_i32 s42, s80, s63
	global_load_lds_dwordx4 v134, s[98:99]
	s_mov_b32 m0, s42
	s_nop 0
	global_load_lds_dwordx4 v130, s[40:41]
	s_add_i32 m0, s42, 0x2000
	s_nop 0
	global_load_lds_dwordx4 v134, s[40:41]
	s_mov_b32 m0, s52
	s_nop 0
	global_load_lds_dwordx4 v128, s[100:101]
	s_mov_b32 m0, s53
	s_nop 0
	global_load_lds_dwordx4 v132, s[100:101]
	s_waitcnt vmcnt(8)
	s_waitcnt lgkmcnt(0)
	s_barrier
	s_setprio 1
	s_waitcnt lgkmcnt(0)
	v_mfma_f32_16x16x32_bf16 v[60:63], v[152:155], v[184:187], v[60:63]
	v_mfma_f32_16x16x32_bf16 v[56:59], v[160:163], v[184:187], v[56:59]
	v_mfma_f32_16x16x32_bf16 v[44:47], v[152:155], v[196:199], v[44:47]
	v_mfma_f32_16x16x32_bf16 v[40:43], v[160:163], v[196:199], v[40:43]
	v_mfma_f32_16x16x32_bf16 v[28:31], v[152:155], v[204:207], v[28:31]
	v_mfma_f32_16x16x32_bf16 v[24:27], v[160:163], v[204:207], v[24:27]
	v_mfma_f32_16x16x32_bf16 v[12:15], v[152:155], v[212:215], v[12:15]
	v_mfma_f32_16x16x32_bf16 v[8:11], v[160:163], v[212:215], v[8:11]
	v_mfma_f32_16x16x32_bf16 v[60:63], v[156:159], v[192:195], v[60:63]
	v_mfma_f32_16x16x32_bf16 v[56:59], v[164:167], v[192:195], v[56:59]
	v_mfma_f32_16x16x32_bf16 v[44:47], v[156:159], v[200:203], v[44:47]
	v_mfma_f32_16x16x32_bf16 v[40:43], v[164:167], v[200:203], v[40:43]
	v_mfma_f32_16x16x32_bf16 v[28:31], v[156:159], v[208:211], v[28:31]
	v_mfma_f32_16x16x32_bf16 v[24:27], v[164:167], v[208:211], v[24:27]
	v_mfma_f32_16x16x32_bf16 v[12:15], v[156:159], v[216:219], v[12:15]
	v_mfma_f32_16x16x32_bf16 v[8:11], v[164:167], v[216:219], v[8:11]
	s_setprio 0
	s_setprio 1
	v_mfma_f32_16x16x32_bf16 v[52:55], v[168:171], v[184:187], v[52:55]
	v_mfma_f32_16x16x32_bf16 v[48:51], v[176:179], v[184:187], v[48:51]
	v_mfma_f32_16x16x32_bf16 v[36:39], v[168:171], v[196:199], v[36:39]
	v_mfma_f32_16x16x32_bf16 v[32:35], v[176:179], v[196:199], v[32:35]
	v_mfma_f32_16x16x32_bf16 v[20:23], v[168:171], v[204:207], v[20:23]
	v_mfma_f32_16x16x32_bf16 v[16:19], v[176:179], v[204:207], v[16:19]
	v_mfma_f32_16x16x32_bf16 v[4:7], v[168:171], v[212:215], v[4:7]
	v_mfma_f32_16x16x32_bf16 v[0:3], v[176:179], v[212:215], v[0:3]
	v_mfma_f32_16x16x32_bf16 v[52:55], v[172:175], v[192:195], v[52:55]
	v_mfma_f32_16x16x32_bf16 v[48:51], v[180:183], v[192:195], v[48:51]
	v_mfma_f32_16x16x32_bf16 v[36:39], v[172:175], v[200:203], v[36:39]
	v_mfma_f32_16x16x32_bf16 v[32:35], v[180:183], v[200:203], v[32:35]
	v_mfma_f32_16x16x32_bf16 v[20:23], v[172:175], v[208:211], v[20:23]
	v_mfma_f32_16x16x32_bf16 v[16:19], v[180:183], v[208:211], v[16:19]
	v_mfma_f32_16x16x32_bf16 v[4:7], v[172:175], v[216:219], v[4:7]
	v_mfma_f32_16x16x32_bf16 v[0:3], v[180:183], v[216:219], v[0:3]
	s_setprio 0
	s_barrier
	s_add_i32 s77, s77, 2
	s_add_u32 s34, s34, 0x100
	s_addc_u32 s35, s35, 0
	s_add_u32 s75, s75, 0x100
	s_addc_u32 s76, s76, 0
	s_cmp_gt_u32 s77, 13
	s_cbranch_scc0 .LBB0_837
	s_and_b64 vcc, exec, s[12:13]
	s_cbranch_vccz .LBB0_840
	s_barrier

.LBB0_916:
	ds_read_b128 v[152:155], v149
	ds_read_b128 v[156:159], v149 offset:1024
	ds_read_b128 v[160:163], v149 offset:2048
	ds_read_b128 v[164:167], v149 offset:3072
	ds_read_b128 v[168:171], v150
	ds_read_b128 v[172:175], v150 offset:1024
	ds_read_b128 v[176:179], v150 offset:2048
	ds_read_b128 v[180:183], v150 offset:3072
	s_add_u32 s40, s34, 0xfff00080
	s_addc_u32 s41, s35, -1
	s_cmp_eq_u32 s77, 60
	s_cselect_b32 s43, s25, s41
	s_cselect_b32 s42, s55, s40
	s_cselect_b32 s41, s23, s76
	s_cselect_b32 s40, s74, s75
	s_add_i32 m0, s31, 0xc000
	ds_read_b128 v[184:187], v151
	ds_read_b128 v[192:195], v151 offset:1024
	ds_read_b128 v[196:199], v151 offset:2048
	ds_read_b128 v[200:203], v151 offset:3072
	ds_read_b128 v[204:207], v151 offset:4096
	ds_read_b128 v[208:211], v151 offset:5120
	ds_read_b128 v[212:215], v151 offset:6144
	ds_read_b128 v[216:219], v151 offset:7168
	global_load_lds_dwordx4 v136, s[34:35]
	s_add_i32 m0, s31, 0xe000
	s_nop 0
	global_load_lds_dwordx4 v138, s[34:35]
	s_waitcnt vmcnt(8)
	s_waitcnt lgkmcnt(0)
	s_barrier
	s_setprio 1
	s_waitcnt lgkmcnt(0)
	v_mfma_f32_16x16x32_bf16 v[124:127], v[152:155], v[184:187], v[124:127]
	v_mfma_f32_16x16x32_bf16 v[120:123], v[160:163], v[184:187], v[120:123]
	v_mfma_f32_16x16x32_bf16 v[116:119], v[152:155], v[196:199], v[116:119]
	v_mfma_f32_16x16x32_bf16 v[108:111], v[160:163], v[196:199], v[108:111]
	v_mfma_f32_16x16x32_bf16 v[100:103], v[152:155], v[204:207], v[100:103]
	v_mfma_f32_16x16x32_bf16 v[92:95], v[160:163], v[204:207], v[92:95]
	v_mfma_f32_16x16x32_bf16 v[84:87], v[152:155], v[212:215], v[84:87]
	v_mfma_f32_16x16x32_bf16 v[76:79], v[160:163], v[212:215], v[76:79]
	v_mfma_f32_16x16x32_bf16 v[124:127], v[156:159], v[192:195], v[124:127]
	v_mfma_f32_16x16x32_bf16 v[120:123], v[164:167], v[192:195], v[120:123]
	v_mfma_f32_16x16x32_bf16 v[116:119], v[156:159], v[200:203], v[116:119]
	v_mfma_f32_16x16x32_bf16 v[108:111], v[164:167], v[200:203], v[108:111]
	v_mfma_f32_16x16x32_bf16 v[100:103], v[156:159], v[208:211], v[100:103]
	v_mfma_f32_16x16x32_bf16 v[92:95], v[164:167], v[208:211], v[92:95]
	v_mfma_f32_16x16x32_bf16 v[84:87], v[156:159], v[216:219], v[84:87]
	v_mfma_f32_16x16x32_bf16 v[76:79], v[164:167], v[216:219], v[76:79]
	s_setprio 0
	s_setprio 1
	v_mfma_f32_16x16x32_bf16 v[112:115], v[168:171], v[184:187], v[112:115]
	v_mfma_f32_16x16x32_bf16 v[104:107], v[176:179], v[184:187], v[104:107]
	v_mfma_f32_16x16x32_bf16 v[96:99], v[168:171], v[196:199], v[96:99]
	v_mfma_f32_16x16x32_bf16 v[88:91], v[176:179], v[196:199], v[88:91]
	v_mfma_f32_16x16x32_bf16 v[80:83], v[168:171], v[204:207], v[80:83]
	v_mfma_f32_16x16x32_bf16 v[72:75], v[176:179], v[204:207], v[72:75]
	v_mfma_f32_16x16x32_bf16 v[68:71], v[168:171], v[212:215], v[68:71]
	v_mfma_f32_16x16x32_bf16 v[64:67], v[176:179], v[212:215], v[64:67]
	v_mfma_f32_16x16x32_bf16 v[112:115], v[172:175], v[192:195], v[112:115]
	v_mfma_f32_16x16x32_bf16 v[104:107], v[180:183], v[192:195], v[104:107]
	v_mfma_f32_16x16x32_bf16 v[96:99], v[172:175], v[200:203], v[96:99]
	v_mfma_f32_16x16x32_bf16 v[88:91], v[180:183], v[200:203], v[88:91]
	v_mfma_f32_16x16x32_bf16 v[80:83], v[172:175], v[208:211], v[80:83]
	v_mfma_f32_16x16x32_bf16 v[72:75], v[180:183], v[208:211], v[72:75]
	v_mfma_f32_16x16x32_bf16 v[68:71], v[172:175], v[216:219], v[68:71]
	v_mfma_f32_16x16x32_bf16 v[64:67], v[180:183], v[216:219], v[64:67]
	s_setprio 0
	s_barrier
	s_add_i32 s79, s68, s61
	s_add_u32 s98, s40, 0x80
	s_addc_u32 s99, s41, 0
	s_mov_b32 m0, s79
	ds_read_b128 v[184:187], v151 offset:16384
	ds_read_b128 v[192:195], v151 offset:17408
	ds_read_b128 v[196:199], v151 offset:18432
	ds_read_b128 v[200:203], v151 offset:19456
	ds_read_b128 v[204:207], v151 offset:20480
	ds_read_b128 v[208:211], v151 offset:21504
	ds_read_b128 v[212:215], v151 offset:22528
	ds_read_b128 v[216:219], v151 offset:23552
	global_load_lds_dwordx4 v130, s[40:41]
	s_add_i32 m0, s79, 0x2000
	s_add_u32 s80, s40, 0x100000
	s_addc_u32 s81, s41, 0
	s_add_i32 s79, s69, s61
	global_load_lds_dwordx4 v134, s[40:41]
	s_mov_b32 m0, s79
	s_add_u32 s100, s42, 0x80
	s_addc_u32 s101, s43, 0
	global_load_lds_dwordx4 v130, s[80:81]
	s_add_i32 m0, s79, 0x2000
	s_nop 0
	global_load_lds_dwordx4 v134, s[80:81]
	s_mov_b32 m0, s31
	s_nop 0
	global_load_lds_dwordx4 v128, s[42:43]
	s_mov_b32 m0, s33
	s_nop 0
	global_load_lds_dwordx4 v132, s[42:43]
	s_waitcnt vmcnt(8)
	s_waitcnt lgkmcnt(0)
	s_barrier
	s_setprio 1
	s_waitcnt lgkmcnt(0)
	v_mfma_f32_16x16x32_bf16 v[60:63], v[152:155], v[184:187], v[60:63]
	v_mfma_f32_16x16x32_bf16 v[56:59], v[160:163], v[184:187], v[56:59]
	v_mfma_f32_16x16x32_bf16 v[52:55], v[152:155], v[196:199], v[52:55]
	v_mfma_f32_16x16x32_bf16 v[44:47], v[160:163], v[196:199], v[44:47]
	v_mfma_f32_16x16x32_bf16 v[36:39], v[152:155], v[204:207], v[36:39]
	v_mfma_f32_16x16x32_bf16 v[28:31], v[160:163], v[204:207], v[28:31]
	v_mfma_f32_16x16x32_bf16 v[20:23], v[152:155], v[212:215], v[20:23]
	v_mfma_f32_16x16x32_bf16 v[12:15], v[160:163], v[212:215], v[12:15]
	v_mfma_f32_16x16x32_bf16 v[60:63], v[156:159], v[192:195], v[60:63]
	v_mfma_f32_16x16x32_bf16 v[56:59], v[164:167], v[192:195], v[56:59]
	v_mfma_f32_16x16x32_bf16 v[52:55], v[156:159], v[200:203], v[52:55]
	v_mfma_f32_16x16x32_bf16 v[44:47], v[164:167], v[200:203], v[44:47]
	v_mfma_f32_16x16x32_bf16 v[36:39], v[156:159], v[208:211], v[36:39]
	v_mfma_f32_16x16x32_bf16 v[28:31], v[164:167], v[208:211], v[28:31]
	v_mfma_f32_16x16x32_bf16 v[20:23], v[156:159], v[216:219], v[20:23]
	v_mfma_f32_16x16x32_bf16 v[12:15], v[164:167], v[216:219], v[12:15]
	s_setprio 0
	s_setprio 1
	v_mfma_f32_16x16x32_bf16 v[48:51], v[168:171], v[184:187], v[48:51]
	v_mfma_f32_16x16x32_bf16 v[40:43], v[176:179], v[184:187], v[40:43]
	v_mfma_f32_16x16x32_bf16 v[32:35], v[168:171], v[196:199], v[32:35]
	v_mfma_f32_16x16x32_bf16 v[24:27], v[176:179], v[196:199], v[24:27]
	v_mfma_f32_16x16x32_bf16 v[16:19], v[168:171], v[204:207], v[16:19]
	v_mfma_f32_16x16x32_bf16 v[8:11], v[176:179], v[204:207], v[8:11]
	v_mfma_f32_16x16x32_bf16 v[4:7], v[168:171], v[212:215], v[4:7]
	v_mfma_f32_16x16x32_bf16 v[0:3], v[176:179], v[212:215], v[0:3]
	v_mfma_f32_16x16x32_bf16 v[48:51], v[172:175], v[192:195], v[48:51]
	v_mfma_f32_16x16x32_bf16 v[40:43], v[180:183], v[192:195], v[40:43]
	v_mfma_f32_16x16x32_bf16 v[32:35], v[172:175], v[200:203], v[32:35]
	v_mfma_f32_16x16x32_bf16 v[24:27], v[180:183], v[200:203], v[24:27]
	v_mfma_f32_16x16x32_bf16 v[16:19], v[172:175], v[208:211], v[16:19]
	v_mfma_f32_16x16x32_bf16 v[8:11], v[180:183], v[208:211], v[8:11]
	v_mfma_f32_16x16x32_bf16 v[4:7], v[172:175], v[216:219], v[4:7]
	v_mfma_f32_16x16x32_bf16 v[0:3], v[180:183], v[216:219], v[0:3]
	s_setprio 0
	s_barrier
	s_add_i32 s79, 0, 0x18000
	s_add_i32 s80, 0, 0x1c000
	v_add_u32_e32 v164, s79, v147
	v_add_u32_e32 v180, s80, v147
	ds_read_b128 v[152:155], v164
	ds_read_b128 v[156:159], v164 offset:1024
	ds_read_b128 v[160:163], v164 offset:2048
	ds_read_b128 v[164:167], v164 offset:3072
	ds_read_b128 v[168:171], v180
	ds_read_b128 v[172:175], v180 offset:1024
	ds_read_b128 v[176:179], v180 offset:2048
	ds_read_b128 v[180:183], v180 offset:3072
	s_add_u32 s42, s42, 0x100000
	s_addc_u32 s43, s43, 0
	s_mov_b32 m0, s62
	ds_read_b128 v[184:187], v151 offset:32768
	ds_read_b128 v[192:195], v151 offset:33792
	ds_read_b128 v[196:199], v151 offset:34816
	ds_read_b128 v[200:203], v151 offset:35840
	ds_read_b128 v[204:207], v151 offset:36864
	ds_read_b128 v[208:211], v151 offset:37888
	ds_read_b128 v[212:215], v151 offset:38912
	ds_read_b128 v[216:219], v151 offset:39936
	global_load_lds_dwordx4 v128, s[42:43]
	s_mov_b32 m0, s63
	s_nop 0
	global_load_lds_dwordx4 v132, s[42:43]
	s_waitcnt vmcnt(8)
	s_waitcnt lgkmcnt(0)
	s_barrier
	s_setprio 1
	s_waitcnt lgkmcnt(0)
	v_mfma_f32_16x16x32_bf16 v[124:127], v[152:155], v[184:187], v[124:127]
	v_mfma_f32_16x16x32_bf16 v[120:123], v[160:163], v[184:187], v[120:123]
	v_mfma_f32_16x16x32_bf16 v[116:119], v[152:155], v[196:199], v[116:119]
	v_mfma_f32_16x16x32_bf16 v[108:111], v[160:163], v[196:199], v[108:111]
	v_mfma_f32_16x16x32_bf16 v[100:103], v[152:155], v[204:207], v[100:103]
	v_mfma_f32_16x16x32_bf16 v[92:95], v[160:163], v[204:207], v[92:95]
	v_mfma_f32_16x16x32_bf16 v[84:87], v[152:155], v[212:215], v[84:87]
	v_mfma_f32_16x16x32_bf16 v[76:79], v[160:163], v[212:215], v[76:79]
	v_mfma_f32_16x16x32_bf16 v[124:127], v[156:159], v[192:195], v[124:127]
	v_mfma_f32_16x16x32_bf16 v[120:123], v[164:167], v[192:195], v[120:123]
	v_mfma_f32_16x16x32_bf16 v[116:119], v[156:159], v[200:203], v[116:119]
	v_mfma_f32_16x16x32_bf16 v[108:111], v[164:167], v[200:203], v[108:111]
	v_mfma_f32_16x16x32_bf16 v[100:103], v[156:159], v[208:211], v[100:103]
	v_mfma_f32_16x16x32_bf16 v[92:95], v[164:167], v[208:211], v[92:95]
	v_mfma_f32_16x16x32_bf16 v[84:87], v[156:159], v[216:219], v[84:87]
	v_mfma_f32_16x16x32_bf16 v[76:79], v[164:167], v[216:219], v[76:79]
	s_setprio 0
	s_setprio 1
	v_mfma_f32_16x16x32_bf16 v[112:115], v[168:171], v[184:187], v[112:115]
	v_mfma_f32_16x16x32_bf16 v[104:107], v[176:179], v[184:187], v[104:107]
	v_mfma_f32_16x16x32_bf16 v[96:99], v[168:171], v[196:199], v[96:99]
	v_mfma_f32_16x16x32_bf16 v[88:91], v[176:179], v[196:199], v[88:91]
	v_mfma_f32_16x16x32_bf16 v[80:83], v[168:171], v[204:207], v[80:83]
	v_mfma_f32_16x16x32_bf16 v[72:75], v[176:179], v[204:207], v[72:75]
	v_mfma_f32_16x16x32_bf16 v[68:71], v[168:171], v[212:215], v[68:71]
	v_mfma_f32_16x16x32_bf16 v[64:67], v[176:179], v[212:215], v[64:67]
	v_mfma_f32_16x16x32_bf16 v[112:115], v[172:175], v[192:195], v[112:115]
	v_mfma_f32_16x16x32_bf16 v[104:107], v[180:183], v[192:195], v[104:107]
	v_mfma_f32_16x16x32_bf16 v[96:99], v[172:175], v[200:203], v[96:99]
	v_mfma_f32_16x16x32_bf16 v[88:91], v[180:183], v[200:203], v[88:91]
	v_mfma_f32_16x16x32_bf16 v[80:83], v[172:175], v[208:211], v[80:83]
	v_mfma_f32_16x16x32_bf16 v[72:75], v[180:183], v[208:211], v[72:75]
	v_mfma_f32_16x16x32_bf16 v[68:71], v[172:175], v[216:219], v[68:71]
	v_mfma_f32_16x16x32_bf16 v[64:67], v[180:183], v[216:219], v[64:67]
	s_setprio 0
	s_barrier
	s_add_i32 s42, s79, s61
	s_mov_b32 m0, s42
	ds_read_b128 v[184:187], v151 offset:49152
	ds_read_b128 v[192:195], v151 offset:50176
	ds_read_b128 v[196:199], v151 offset:51200
	ds_read_b128 v[200:203], v151 offset:52224
	ds_read_b128 v[204:207], v151 offset:53248
	ds_read_b128 v[208:211], v151 offset:54272
	ds_read_b128 v[212:215], v151 offset:55296
	ds_read_b128 v[216:219], v151 offset:56320
	global_load_lds_dwordx4 v130, s[98:99]
	s_add_i32 m0, s42, 0x2000
	s_add_u32 s40, s40, 0x100080
	s_addc_u32 s41, s41, 0
	s_add_i32 s42, s80, s61
	global_load_lds_dwordx4 v134, s[98:99]
	s_mov_b32 m0, s42
	s_nop 0
	global_load_lds_dwordx4 v130, s[40:41]
	s_add_i32 m0, s42, 0x2000
	s_nop 0
	global_load_lds_dwordx4 v134, s[40:41]
	s_mov_b32 m0, s65
	s_nop 0
	global_load_lds_dwordx4 v128, s[100:101]
	s_mov_b32 m0, s66
	s_nop 0
	global_load_lds_dwordx4 v132, s[100:101]
	s_waitcnt vmcnt(8)
	s_waitcnt lgkmcnt(0)
	s_barrier
	s_setprio 1
	s_waitcnt lgkmcnt(0)
	v_mfma_f32_16x16x32_bf16 v[60:63], v[152:155], v[184:187], v[60:63]
	v_mfma_f32_16x16x32_bf16 v[56:59], v[160:163], v[184:187], v[56:59]
	v_mfma_f32_16x16x32_bf16 v[52:55], v[152:155], v[196:199], v[52:55]
	v_mfma_f32_16x16x32_bf16 v[44:47], v[160:163], v[196:199], v[44:47]
	v_mfma_f32_16x16x32_bf16 v[36:39], v[152:155], v[204:207], v[36:39]
	v_mfma_f32_16x16x32_bf16 v[28:31], v[160:163], v[204:207], v[28:31]
	v_mfma_f32_16x16x32_bf16 v[20:23], v[152:155], v[212:215], v[20:23]
	v_mfma_f32_16x16x32_bf16 v[12:15], v[160:163], v[212:215], v[12:15]
	v_mfma_f32_16x16x32_bf16 v[60:63], v[156:159], v[192:195], v[60:63]
	v_mfma_f32_16x16x32_bf16 v[56:59], v[164:167], v[192:195], v[56:59]
	v_mfma_f32_16x16x32_bf16 v[52:55], v[156:159], v[200:203], v[52:55]
	v_mfma_f32_16x16x32_bf16 v[44:47], v[164:167], v[200:203], v[44:47]
	v_mfma_f32_16x16x32_bf16 v[36:39], v[156:159], v[208:211], v[36:39]
	v_mfma_f32_16x16x32_bf16 v[28:31], v[164:167], v[208:211], v[28:31]
	v_mfma_f32_16x16x32_bf16 v[20:23], v[156:159], v[216:219], v[20:23]
	v_mfma_f32_16x16x32_bf16 v[12:15], v[164:167], v[216:219], v[12:15]
	s_setprio 0
	s_setprio 1
	v_mfma_f32_16x16x32_bf16 v[48:51], v[168:171], v[184:187], v[48:51]
	v_mfma_f32_16x16x32_bf16 v[40:43], v[176:179], v[184:187], v[40:43]
	v_mfma_f32_16x16x32_bf16 v[32:35], v[168:171], v[196:199], v[32:35]
	v_mfma_f32_16x16x32_bf16 v[24:27], v[176:179], v[196:199], v[24:27]
	v_mfma_f32_16x16x32_bf16 v[16:19], v[168:171], v[204:207], v[16:19]
	v_mfma_f32_16x16x32_bf16 v[8:11], v[176:179], v[204:207], v[8:11]
	v_mfma_f32_16x16x32_bf16 v[4:7], v[168:171], v[212:215], v[4:7]
	v_mfma_f32_16x16x32_bf16 v[0:3], v[176:179], v[212:215], v[0:3]
	v_mfma_f32_16x16x32_bf16 v[48:51], v[172:175], v[192:195], v[48:51]
	v_mfma_f32_16x16x32_bf16 v[40:43], v[180:183], v[192:195], v[40:43]
	v_mfma_f32_16x16x32_bf16 v[32:35], v[172:175], v[200:203], v[32:35]
	v_mfma_f32_16x16x32_bf16 v[24:27], v[180:183], v[200:203], v[24:27]
	v_mfma_f32_16x16x32_bf16 v[16:19], v[172:175], v[208:211], v[16:19]
	v_mfma_f32_16x16x32_bf16 v[8:11], v[180:183], v[208:211], v[8:11]
	v_mfma_f32_16x16x32_bf16 v[4:7], v[172:175], v[216:219], v[4:7]
	v_mfma_f32_16x16x32_bf16 v[0:3], v[180:183], v[216:219], v[0:3]
	s_setprio 0
	s_barrier
	s_add_i32 s77, s77, 2
	s_add_u32 s34, s34, 0x100
	s_addc_u32 s35, s35, 0
	s_add_u32 s75, s75, 0x100
	s_addc_u32 s76, s76, 0
	s_cmp_gt_u32 s77, 61
	s_cbranch_scc0 .LBB0_916
	s_and_b64 vcc, exec, s[12:13]
	s_cbranch_vccz .LBB0_919
	s_barrier

.LBB0_1053:
	ds_read_b128 v[152:155], v149
	ds_read_b128 v[156:159], v149 offset:1024
	ds_read_b128 v[160:163], v149 offset:2048
	ds_read_b128 v[164:167], v149 offset:3072
	ds_read_b128 v[168:171], v150
	ds_read_b128 v[172:175], v150 offset:1024
	ds_read_b128 v[176:179], v150 offset:2048
	ds_read_b128 v[180:183], v150 offset:3072
	s_add_u32 s60, s42, 0xfffc0080
	s_addc_u32 s61, s43, -1
	s_cmp_eq_u32 s82, 12
	s_cselect_b32 s63, s27, s61
	s_cselect_b32 s62, s55, s60
	s_cselect_b32 s61, s25, s81
	s_cselect_b32 s60, s79, s80
	s_add_i32 m0, s35, 0xc000
	ds_read_b128 v[184:187], v151
	ds_read_b128 v[192:195], v151 offset:1024
	ds_read_b128 v[196:199], v151 offset:2048
	ds_read_b128 v[200:203], v151 offset:3072
	ds_read_b128 v[204:207], v151 offset:4096
	ds_read_b128 v[208:211], v151 offset:5120
	ds_read_b128 v[212:215], v151 offset:6144
	ds_read_b128 v[216:219], v151 offset:7168
	global_load_lds_dwordx4 v136, s[42:43]
	s_add_i32 m0, s35, 0xe000
	s_nop 0
	global_load_lds_dwordx4 v138, s[42:43]
	s_waitcnt vmcnt(8)
	s_waitcnt lgkmcnt(0)
	s_barrier
	s_setprio 1
	s_waitcnt lgkmcnt(0)
	v_mfma_f32_16x16x32_bf16 v[124:127], v[152:155], v[184:187], v[124:127]
	v_mfma_f32_16x16x32_bf16 v[120:123], v[160:163], v[184:187], v[120:123]
	v_mfma_f32_16x16x32_bf16 v[116:119], v[152:155], v[196:199], v[116:119]
	v_mfma_f32_16x16x32_bf16 v[108:111], v[160:163], v[196:199], v[108:111]
	v_mfma_f32_16x16x32_bf16 v[100:103], v[152:155], v[204:207], v[100:103]
	v_mfma_f32_16x16x32_bf16 v[92:95], v[160:163], v[204:207], v[92:95]
	v_mfma_f32_16x16x32_bf16 v[84:87], v[152:155], v[212:215], v[84:87]
	v_mfma_f32_16x16x32_bf16 v[76:79], v[160:163], v[212:215], v[76:79]
	v_mfma_f32_16x16x32_bf16 v[124:127], v[156:159], v[192:195], v[124:127]
	v_mfma_f32_16x16x32_bf16 v[120:123], v[164:167], v[192:195], v[120:123]
	v_mfma_f32_16x16x32_bf16 v[116:119], v[156:159], v[200:203], v[116:119]
	v_mfma_f32_16x16x32_bf16 v[108:111], v[164:167], v[200:203], v[108:111]
	v_mfma_f32_16x16x32_bf16 v[100:103], v[156:159], v[208:211], v[100:103]
	v_mfma_f32_16x16x32_bf16 v[92:95], v[164:167], v[208:211], v[92:95]
	v_mfma_f32_16x16x32_bf16 v[84:87], v[156:159], v[216:219], v[84:87]
	v_mfma_f32_16x16x32_bf16 v[76:79], v[164:167], v[216:219], v[76:79]
	s_setprio 0
	s_setprio 1
	v_mfma_f32_16x16x32_bf16 v[112:115], v[168:171], v[184:187], v[112:115]
	v_mfma_f32_16x16x32_bf16 v[104:107], v[176:179], v[184:187], v[104:107]
	v_mfma_f32_16x16x32_bf16 v[96:99], v[168:171], v[196:199], v[96:99]
	v_mfma_f32_16x16x32_bf16 v[88:91], v[176:179], v[196:199], v[88:91]
	v_mfma_f32_16x16x32_bf16 v[80:83], v[168:171], v[204:207], v[80:83]
	v_mfma_f32_16x16x32_bf16 v[72:75], v[176:179], v[204:207], v[72:75]
	v_mfma_f32_16x16x32_bf16 v[68:71], v[168:171], v[212:215], v[68:71]
	v_mfma_f32_16x16x32_bf16 v[64:67], v[176:179], v[212:215], v[64:67]
	v_mfma_f32_16x16x32_bf16 v[112:115], v[172:175], v[192:195], v[112:115]
	v_mfma_f32_16x16x32_bf16 v[104:107], v[180:183], v[192:195], v[104:107]
	v_mfma_f32_16x16x32_bf16 v[96:99], v[172:175], v[200:203], v[96:99]
	v_mfma_f32_16x16x32_bf16 v[88:91], v[180:183], v[200:203], v[88:91]
	v_mfma_f32_16x16x32_bf16 v[80:83], v[172:175], v[208:211], v[80:83]
	v_mfma_f32_16x16x32_bf16 v[72:75], v[180:183], v[208:211], v[72:75]
	v_mfma_f32_16x16x32_bf16 v[68:71], v[172:175], v[216:219], v[68:71]
	v_mfma_f32_16x16x32_bf16 v[64:67], v[180:183], v[216:219], v[64:67]
	s_setprio 0
	s_barrier
	s_add_i32 s83, s72, s65
	s_add_u32 s98, s60, 0x80
	s_addc_u32 s99, s61, 0
	s_mov_b32 m0, s83
	ds_read_b128 v[184:187], v151 offset:16384
	ds_read_b128 v[192:195], v151 offset:17408
	ds_read_b128 v[196:199], v151 offset:18432
	ds_read_b128 v[200:203], v151 offset:19456
	ds_read_b128 v[204:207], v151 offset:20480
	ds_read_b128 v[208:211], v151 offset:21504
	ds_read_b128 v[212:215], v151 offset:22528
	ds_read_b128 v[216:219], v151 offset:23552
	global_load_lds_dwordx4 v130, s[60:61]
	s_add_i32 m0, s83, 0x2000
	s_add_u32 s84, s60, 0x40000
	s_addc_u32 s85, s61, 0
	s_add_i32 s83, s73, s65
	global_load_lds_dwordx4 v134, s[60:61]
	s_mov_b32 m0, s83
	s_add_u32 s100, s62, 0x80
	s_addc_u32 s101, s63, 0
	global_load_lds_dwordx4 v130, s[84:85]
	s_add_i32 m0, s83, 0x2000
	s_nop 0
	global_load_lds_dwordx4 v134, s[84:85]
	s_mov_b32 m0, s35
	s_nop 0
	global_load_lds_dwordx4 v128, s[62:63]
	s_mov_b32 m0, s33
	s_nop 0
	global_load_lds_dwordx4 v132, s[62:63]
	s_waitcnt vmcnt(8)
	s_waitcnt lgkmcnt(0)
	s_barrier
	s_setprio 1
	s_waitcnt lgkmcnt(0)
	v_mfma_f32_16x16x32_bf16 v[60:63], v[152:155], v[184:187], v[60:63]
	v_mfma_f32_16x16x32_bf16 v[56:59], v[160:163], v[184:187], v[56:59]
	v_mfma_f32_16x16x32_bf16 v[52:55], v[152:155], v[196:199], v[52:55]
	v_mfma_f32_16x16x32_bf16 v[44:47], v[160:163], v[196:199], v[44:47]
	v_mfma_f32_16x16x32_bf16 v[36:39], v[152:155], v[204:207], v[36:39]
	v_mfma_f32_16x16x32_bf16 v[28:31], v[160:163], v[204:207], v[28:31]
	v_mfma_f32_16x16x32_bf16 v[20:23], v[152:155], v[212:215], v[20:23]
	v_mfma_f32_16x16x32_bf16 v[12:15], v[160:163], v[212:215], v[12:15]
	v_mfma_f32_16x16x32_bf16 v[60:63], v[156:159], v[192:195], v[60:63]
	v_mfma_f32_16x16x32_bf16 v[56:59], v[164:167], v[192:195], v[56:59]
	v_mfma_f32_16x16x32_bf16 v[52:55], v[156:159], v[200:203], v[52:55]
	v_mfma_f32_16x16x32_bf16 v[44:47], v[164:167], v[200:203], v[44:47]
	v_mfma_f32_16x16x32_bf16 v[36:39], v[156:159], v[208:211], v[36:39]
	v_mfma_f32_16x16x32_bf16 v[28:31], v[164:167], v[208:211], v[28:31]
	v_mfma_f32_16x16x32_bf16 v[20:23], v[156:159], v[216:219], v[20:23]
	v_mfma_f32_16x16x32_bf16 v[12:15], v[164:167], v[216:219], v[12:15]
	s_setprio 0
	s_setprio 1
	v_mfma_f32_16x16x32_bf16 v[48:51], v[168:171], v[184:187], v[48:51]
	v_mfma_f32_16x16x32_bf16 v[40:43], v[176:179], v[184:187], v[40:43]
	v_mfma_f32_16x16x32_bf16 v[32:35], v[168:171], v[196:199], v[32:35]
	v_mfma_f32_16x16x32_bf16 v[24:27], v[176:179], v[196:199], v[24:27]
	v_mfma_f32_16x16x32_bf16 v[16:19], v[168:171], v[204:207], v[16:19]
	v_mfma_f32_16x16x32_bf16 v[8:11], v[176:179], v[204:207], v[8:11]
	v_mfma_f32_16x16x32_bf16 v[4:7], v[168:171], v[212:215], v[4:7]
	v_mfma_f32_16x16x32_bf16 v[0:3], v[176:179], v[212:215], v[0:3]
	v_mfma_f32_16x16x32_bf16 v[48:51], v[172:175], v[192:195], v[48:51]
	v_mfma_f32_16x16x32_bf16 v[40:43], v[180:183], v[192:195], v[40:43]
	v_mfma_f32_16x16x32_bf16 v[32:35], v[172:175], v[200:203], v[32:35]
	v_mfma_f32_16x16x32_bf16 v[24:27], v[180:183], v[200:203], v[24:27]
	v_mfma_f32_16x16x32_bf16 v[16:19], v[172:175], v[208:211], v[16:19]
	v_mfma_f32_16x16x32_bf16 v[8:11], v[180:183], v[208:211], v[8:11]
	v_mfma_f32_16x16x32_bf16 v[4:7], v[172:175], v[216:219], v[4:7]
	v_mfma_f32_16x16x32_bf16 v[0:3], v[180:183], v[216:219], v[0:3]
	s_setprio 0
	s_barrier
	s_add_i32 s83, 0, 0x18000
	s_add_i32 s84, 0, 0x1c000
	v_add_u32_e32 v164, s83, v147
	v_add_u32_e32 v180, s84, v147
	ds_read_b128 v[152:155], v164
	ds_read_b128 v[156:159], v164 offset:1024
	ds_read_b128 v[160:163], v164 offset:2048
	ds_read_b128 v[164:167], v164 offset:3072
	ds_read_b128 v[168:171], v180
	ds_read_b128 v[172:175], v180 offset:1024
	ds_read_b128 v[176:179], v180 offset:2048
	ds_read_b128 v[180:183], v180 offset:3072
	s_add_u32 s62, s62, 0x40000
	s_addc_u32 s63, s63, 0
	s_mov_b32 m0, s66
	ds_read_b128 v[184:187], v151 offset:32768
	ds_read_b128 v[192:195], v151 offset:33792
	ds_read_b128 v[196:199], v151 offset:34816
	ds_read_b128 v[200:203], v151 offset:35840
	ds_read_b128 v[204:207], v151 offset:36864
	ds_read_b128 v[208:211], v151 offset:37888
	ds_read_b128 v[212:215], v151 offset:38912
	ds_read_b128 v[216:219], v151 offset:39936
	global_load_lds_dwordx4 v128, s[62:63]
	s_mov_b32 m0, s67
	s_nop 0
	global_load_lds_dwordx4 v132, s[62:63]
	s_waitcnt vmcnt(8)
	s_waitcnt lgkmcnt(0)
	s_barrier
	s_setprio 1
	s_waitcnt lgkmcnt(0)
	v_mfma_f32_16x16x32_bf16 v[124:127], v[152:155], v[184:187], v[124:127]
	v_mfma_f32_16x16x32_bf16 v[120:123], v[160:163], v[184:187], v[120:123]
	v_mfma_f32_16x16x32_bf16 v[116:119], v[152:155], v[196:199], v[116:119]
	v_mfma_f32_16x16x32_bf16 v[108:111], v[160:163], v[196:199], v[108:111]
	v_mfma_f32_16x16x32_bf16 v[100:103], v[152:155], v[204:207], v[100:103]
	v_mfma_f32_16x16x32_bf16 v[92:95], v[160:163], v[204:207], v[92:95]
	v_mfma_f32_16x16x32_bf16 v[84:87], v[152:155], v[212:215], v[84:87]
	v_mfma_f32_16x16x32_bf16 v[76:79], v[160:163], v[212:215], v[76:79]
	v_mfma_f32_16x16x32_bf16 v[124:127], v[156:159], v[192:195], v[124:127]
	v_mfma_f32_16x16x32_bf16 v[120:123], v[164:167], v[192:195], v[120:123]
	v_mfma_f32_16x16x32_bf16 v[116:119], v[156:159], v[200:203], v[116:119]
	v_mfma_f32_16x16x32_bf16 v[108:111], v[164:167], v[200:203], v[108:111]
	v_mfma_f32_16x16x32_bf16 v[100:103], v[156:159], v[208:211], v[100:103]
	v_mfma_f32_16x16x32_bf16 v[92:95], v[164:167], v[208:211], v[92:95]
	v_mfma_f32_16x16x32_bf16 v[84:87], v[156:159], v[216:219], v[84:87]
	v_mfma_f32_16x16x32_bf16 v[76:79], v[164:167], v[216:219], v[76:79]
	s_setprio 0
	s_setprio 1
	v_mfma_f32_16x16x32_bf16 v[112:115], v[168:171], v[184:187], v[112:115]
	v_mfma_f32_16x16x32_bf16 v[104:107], v[176:179], v[184:187], v[104:107]
	v_mfma_f32_16x16x32_bf16 v[96:99], v[168:171], v[196:199], v[96:99]
	v_mfma_f32_16x16x32_bf16 v[88:91], v[176:179], v[196:199], v[88:91]
	v_mfma_f32_16x16x32_bf16 v[80:83], v[168:171], v[204:207], v[80:83]
	v_mfma_f32_16x16x32_bf16 v[72:75], v[176:179], v[204:207], v[72:75]
	v_mfma_f32_16x16x32_bf16 v[68:71], v[168:171], v[212:215], v[68:71]
	v_mfma_f32_16x16x32_bf16 v[64:67], v[176:179], v[212:215], v[64:67]
	v_mfma_f32_16x16x32_bf16 v[112:115], v[172:175], v[192:195], v[112:115]
	v_mfma_f32_16x16x32_bf16 v[104:107], v[180:183], v[192:195], v[104:107]
	v_mfma_f32_16x16x32_bf16 v[96:99], v[172:175], v[200:203], v[96:99]
	v_mfma_f32_16x16x32_bf16 v[88:91], v[180:183], v[200:203], v[88:91]
	v_mfma_f32_16x16x32_bf16 v[80:83], v[172:175], v[208:211], v[80:83]
	v_mfma_f32_16x16x32_bf16 v[72:75], v[180:183], v[208:211], v[72:75]
	v_mfma_f32_16x16x32_bf16 v[68:71], v[172:175], v[216:219], v[68:71]
	v_mfma_f32_16x16x32_bf16 v[64:67], v[180:183], v[216:219], v[64:67]
	s_setprio 0
	s_barrier
	s_add_i32 s62, s83, s65
	s_mov_b32 m0, s62
	ds_read_b128 v[184:187], v151 offset:49152
	ds_read_b128 v[192:195], v151 offset:50176
	ds_read_b128 v[196:199], v151 offset:51200
	ds_read_b128 v[200:203], v151 offset:52224
	ds_read_b128 v[204:207], v151 offset:53248
	ds_read_b128 v[208:211], v151 offset:54272
	ds_read_b128 v[212:215], v151 offset:55296
	ds_read_b128 v[216:219], v151 offset:56320
	global_load_lds_dwordx4 v130, s[98:99]
	s_add_i32 m0, s62, 0x2000
	s_add_u32 s60, s60, 0x40080
	s_addc_u32 s61, s61, 0
	s_add_i32 s62, s84, s65
	global_load_lds_dwordx4 v134, s[98:99]
	s_mov_b32 m0, s62
	s_nop 0
	global_load_lds_dwordx4 v130, s[60:61]
	s_add_i32 m0, s62, 0x2000
	s_nop 0
	global_load_lds_dwordx4 v134, s[60:61]
	s_mov_b32 m0, s69
	s_nop 0
	global_load_lds_dwordx4 v128, s[100:101]
	s_mov_b32 m0, s70
	s_nop 0
	global_load_lds_dwordx4 v132, s[100:101]
	s_waitcnt vmcnt(8)
	s_waitcnt lgkmcnt(0)
	s_barrier
	s_setprio 1
	s_waitcnt lgkmcnt(0)
	v_mfma_f32_16x16x32_bf16 v[60:63], v[152:155], v[184:187], v[60:63]
	v_mfma_f32_16x16x32_bf16 v[56:59], v[160:163], v[184:187], v[56:59]
	v_mfma_f32_16x16x32_bf16 v[52:55], v[152:155], v[196:199], v[52:55]
	v_mfma_f32_16x16x32_bf16 v[44:47], v[160:163], v[196:199], v[44:47]
	v_mfma_f32_16x16x32_bf16 v[36:39], v[152:155], v[204:207], v[36:39]
	v_mfma_f32_16x16x32_bf16 v[28:31], v[160:163], v[204:207], v[28:31]
	v_mfma_f32_16x16x32_bf16 v[20:23], v[152:155], v[212:215], v[20:23]
	v_mfma_f32_16x16x32_bf16 v[12:15], v[160:163], v[212:215], v[12:15]
	v_mfma_f32_16x16x32_bf16 v[60:63], v[156:159], v[192:195], v[60:63]
	v_mfma_f32_16x16x32_bf16 v[56:59], v[164:167], v[192:195], v[56:59]
	v_mfma_f32_16x16x32_bf16 v[52:55], v[156:159], v[200:203], v[52:55]
	v_mfma_f32_16x16x32_bf16 v[44:47], v[164:167], v[200:203], v[44:47]
	v_mfma_f32_16x16x32_bf16 v[36:39], v[156:159], v[208:211], v[36:39]
	v_mfma_f32_16x16x32_bf16 v[28:31], v[164:167], v[208:211], v[28:31]
	v_mfma_f32_16x16x32_bf16 v[20:23], v[156:159], v[216:219], v[20:23]
	v_mfma_f32_16x16x32_bf16 v[12:15], v[164:167], v[216:219], v[12:15]
	s_setprio 0
	s_setprio 1
	v_mfma_f32_16x16x32_bf16 v[48:51], v[168:171], v[184:187], v[48:51]
	v_mfma_f32_16x16x32_bf16 v[40:43], v[176:179], v[184:187], v[40:43]
	v_mfma_f32_16x16x32_bf16 v[32:35], v[168:171], v[196:199], v[32:35]
	v_mfma_f32_16x16x32_bf16 v[24:27], v[176:179], v[196:199], v[24:27]
	v_mfma_f32_16x16x32_bf16 v[16:19], v[168:171], v[204:207], v[16:19]
	v_mfma_f32_16x16x32_bf16 v[8:11], v[176:179], v[204:207], v[8:11]
	v_mfma_f32_16x16x32_bf16 v[4:7], v[168:171], v[212:215], v[4:7]
	v_mfma_f32_16x16x32_bf16 v[0:3], v[176:179], v[212:215], v[0:3]
	v_mfma_f32_16x16x32_bf16 v[48:51], v[172:175], v[192:195], v[48:51]
	v_mfma_f32_16x16x32_bf16 v[40:43], v[180:183], v[192:195], v[40:43]
	v_mfma_f32_16x16x32_bf16 v[32:35], v[172:175], v[200:203], v[32:35]
	v_mfma_f32_16x16x32_bf16 v[24:27], v[180:183], v[200:203], v[24:27]
	v_mfma_f32_16x16x32_bf16 v[16:19], v[172:175], v[208:211], v[16:19]
	v_mfma_f32_16x16x32_bf16 v[8:11], v[180:183], v[208:211], v[8:11]
	v_mfma_f32_16x16x32_bf16 v[4:7], v[172:175], v[216:219], v[4:7]
	v_mfma_f32_16x16x32_bf16 v[0:3], v[180:183], v[216:219], v[0:3]
	s_setprio 0
	s_barrier
	s_add_i32 s82, s82, 2
	s_add_u32 s42, s42, 0x100
	s_addc_u32 s43, s43, 0
	s_add_u32 s80, s80, 0x100
	s_addc_u32 s81, s81, 0
	s_cmp_gt_u32 s82, 13
	s_cbranch_scc0 .LBB0_1053
	s_and_b64 vcc, exec, s[14:15]
	s_cbranch_vccz .LBB0_1056
	s_barrier

.LBB0_1266:
	ds_read_b128 v[144:147], v151
	ds_read_b128 v[154:157], v151 offset:1024
	ds_read_b128 v[158:161], v151 offset:2048
	ds_read_b128 v[162:165], v151 offset:3072
	ds_read_b128 v[166:169], v152
	ds_read_b128 v[170:173], v152 offset:1024
	ds_read_b128 v[174:177], v152 offset:2048
	ds_read_b128 v[178:181], v152 offset:3072
	s_add_u32 s18, s16, 0x100
	s_addc_u32 s19, s17, 0
	s_cmp_eq_u32 s67, 2
	s_cselect_b32 s23, s5, s19
	s_cselect_b32 s22, s4, s18
	s_cselect_b32 s21, s15, s66
	s_cselect_b32 s20, s14, s65
	v_lshl_add_u64 v[216:217], s[16:17], 0, v[136:137]
	s_add_i32 m0, s31, 0xc000
	ds_read_b128 v[182:185], v153
	ds_read_b128 v[186:189], v153 offset:1024
	ds_read_b128 v[192:195], v153 offset:2048
	ds_read_b128 v[196:199], v153 offset:3072
	ds_read_b128 v[200:203], v153 offset:4096
	ds_read_b128 v[204:207], v153 offset:5120
	ds_read_b128 v[208:211], v153 offset:6144
	ds_read_b128 v[212:215], v153 offset:7168
	global_load_lds_dwordx4 v[216:217], off
	v_lshl_add_u64 v[216:217], s[16:17], 0, v[138:139]
	s_add_i32 m0, s31, 0xe000
	s_nop 0
	global_load_lds_dwordx4 v[216:217], off
	s_waitcnt vmcnt(8)
	s_waitcnt lgkmcnt(0)
	s_barrier
	s_setprio 1
	s_waitcnt lgkmcnt(0)
	v_mfma_f32_16x16x32_bf16 v[124:127], v[144:147], v[182:185], v[124:127]
	v_mfma_f32_16x16x32_bf16 v[120:123], v[158:161], v[182:185], v[120:123]
	v_mfma_f32_16x16x32_bf16 v[116:119], v[144:147], v[192:195], v[116:119]
	v_mfma_f32_16x16x32_bf16 v[108:111], v[158:161], v[192:195], v[108:111]
	v_mfma_f32_16x16x32_bf16 v[100:103], v[144:147], v[200:203], v[100:103]
	v_mfma_f32_16x16x32_bf16 v[92:95], v[158:161], v[200:203], v[92:95]
	v_mfma_f32_16x16x32_bf16 v[84:87], v[144:147], v[208:211], v[84:87]
	v_mfma_f32_16x16x32_bf16 v[76:79], v[158:161], v[208:211], v[76:79]
	v_mfma_f32_16x16x32_bf16 v[124:127], v[154:157], v[186:189], v[124:127]
	v_mfma_f32_16x16x32_bf16 v[120:123], v[162:165], v[186:189], v[120:123]
	v_mfma_f32_16x16x32_bf16 v[116:119], v[154:157], v[196:199], v[116:119]
	v_mfma_f32_16x16x32_bf16 v[108:111], v[162:165], v[196:199], v[108:111]
	v_mfma_f32_16x16x32_bf16 v[100:103], v[154:157], v[204:207], v[100:103]
	v_mfma_f32_16x16x32_bf16 v[92:95], v[162:165], v[204:207], v[92:95]
	v_mfma_f32_16x16x32_bf16 v[84:87], v[154:157], v[212:215], v[84:87]
	v_mfma_f32_16x16x32_bf16 v[76:79], v[162:165], v[212:215], v[76:79]
	s_setprio 0
	s_setprio 1
	v_mfma_f32_16x16x32_bf16 v[112:115], v[166:169], v[182:185], v[112:115]
	v_mfma_f32_16x16x32_bf16 v[104:107], v[174:177], v[182:185], v[104:107]
	v_mfma_f32_16x16x32_bf16 v[96:99], v[166:169], v[192:195], v[96:99]
	v_mfma_f32_16x16x32_bf16 v[88:91], v[174:177], v[192:195], v[88:91]
	v_mfma_f32_16x16x32_bf16 v[80:83], v[166:169], v[200:203], v[80:83]
	v_mfma_f32_16x16x32_bf16 v[72:75], v[174:177], v[200:203], v[72:75]
	v_mfma_f32_16x16x32_bf16 v[68:71], v[166:169], v[208:211], v[68:71]
	v_mfma_f32_16x16x32_bf16 v[64:67], v[174:177], v[208:211], v[64:67]
	v_mfma_f32_16x16x32_bf16 v[112:115], v[170:173], v[186:189], v[112:115]
	v_mfma_f32_16x16x32_bf16 v[104:107], v[178:181], v[186:189], v[104:107]
	v_mfma_f32_16x16x32_bf16 v[96:99], v[170:173], v[196:199], v[96:99]
	v_mfma_f32_16x16x32_bf16 v[88:91], v[178:181], v[196:199], v[88:91]
	v_mfma_f32_16x16x32_bf16 v[80:83], v[170:173], v[204:207], v[80:83]
	v_mfma_f32_16x16x32_bf16 v[72:75], v[178:181], v[204:207], v[72:75]
	v_mfma_f32_16x16x32_bf16 v[68:71], v[170:173], v[212:215], v[68:71]
	v_mfma_f32_16x16x32_bf16 v[64:67], v[178:181], v[212:215], v[64:67]
	s_setprio 0
	s_barrier
	s_add_i32 s16, s60, s28
	s_add_u32 s98, s20, 0x80
	s_addc_u32 s99, s21, 0
	s_mov_b32 m0, s16
	ds_read_b128 v[182:185], v153 offset:16384
	ds_read_b128 v[186:189], v153 offset:17408
	ds_read_b128 v[192:195], v153 offset:18432
	ds_read_b128 v[196:199], v153 offset:19456
	ds_read_b128 v[200:203], v153 offset:20480
	ds_read_b128 v[204:207], v153 offset:21504
	ds_read_b128 v[208:211], v153 offset:22528
	ds_read_b128 v[212:215], v153 offset:23552
	global_load_lds_dwordx4 v132, s[20:21]
	s_add_i32 m0, s16, 0x2000
	s_add_u32 s16, s20, 0x18000
	s_addc_u32 s17, s21, 0
	s_add_i32 s68, s61, s28
	global_load_lds_dwordx4 v128, s[20:21]
	s_mov_b32 m0, s68
	s_add_u32 s100, s22, 0x80
	s_addc_u32 s101, s23, 0
	global_load_lds_dwordx4 v132, s[16:17]
	s_add_i32 m0, s68, 0x2000
	s_nop 0
	global_load_lds_dwordx4 v128, s[16:17]
	s_mov_b32 m0, s31
	s_nop 0
	global_load_lds_dwordx4 v134, s[22:23]
	s_mov_b32 m0, s33
	s_nop 0
	global_load_lds_dwordx4 v130, s[22:23]
	s_waitcnt vmcnt(8)
	s_waitcnt lgkmcnt(0)
	s_barrier
	s_setprio 1
	s_waitcnt lgkmcnt(0)
	v_mfma_f32_16x16x32_bf16 v[60:63], v[144:147], v[182:185], v[60:63]
	v_mfma_f32_16x16x32_bf16 v[56:59], v[158:161], v[182:185], v[56:59]
	v_mfma_f32_16x16x32_bf16 v[52:55], v[144:147], v[192:195], v[52:55]
	v_mfma_f32_16x16x32_bf16 v[44:47], v[158:161], v[192:195], v[44:47]
	v_mfma_f32_16x16x32_bf16 v[36:39], v[144:147], v[200:203], v[36:39]
	v_mfma_f32_16x16x32_bf16 v[28:31], v[158:161], v[200:203], v[28:31]
	v_mfma_f32_16x16x32_bf16 v[20:23], v[144:147], v[208:211], v[20:23]
	v_mfma_f32_16x16x32_bf16 v[12:15], v[158:161], v[208:211], v[12:15]
	v_mfma_f32_16x16x32_bf16 v[60:63], v[154:157], v[186:189], v[60:63]
	v_mfma_f32_16x16x32_bf16 v[56:59], v[162:165], v[186:189], v[56:59]
	v_mfma_f32_16x16x32_bf16 v[52:55], v[154:157], v[196:199], v[52:55]
	v_mfma_f32_16x16x32_bf16 v[44:47], v[162:165], v[196:199], v[44:47]
	v_mfma_f32_16x16x32_bf16 v[36:39], v[154:157], v[204:207], v[36:39]
	v_mfma_f32_16x16x32_bf16 v[28:31], v[162:165], v[204:207], v[28:31]
	v_mfma_f32_16x16x32_bf16 v[20:23], v[154:157], v[212:215], v[20:23]
	v_mfma_f32_16x16x32_bf16 v[12:15], v[162:165], v[212:215], v[12:15]
	s_setprio 0
	s_setprio 1
	v_mfma_f32_16x16x32_bf16 v[48:51], v[166:169], v[182:185], v[48:51]
	v_mfma_f32_16x16x32_bf16 v[40:43], v[174:177], v[182:185], v[40:43]
	v_mfma_f32_16x16x32_bf16 v[32:35], v[166:169], v[192:195], v[32:35]
	v_mfma_f32_16x16x32_bf16 v[24:27], v[174:177], v[192:195], v[24:27]
	v_mfma_f32_16x16x32_bf16 v[16:19], v[166:169], v[200:203], v[16:19]
	v_mfma_f32_16x16x32_bf16 v[8:11], v[174:177], v[200:203], v[8:11]
	v_mfma_f32_16x16x32_bf16 v[4:7], v[166:169], v[208:211], v[4:7]
	v_mfma_f32_16x16x32_bf16 v[0:3], v[174:177], v[208:211], v[0:3]
	v_mfma_f32_16x16x32_bf16 v[48:51], v[170:173], v[186:189], v[48:51]
	v_mfma_f32_16x16x32_bf16 v[40:43], v[178:181], v[186:189], v[40:43]
	v_mfma_f32_16x16x32_bf16 v[32:35], v[170:173], v[196:199], v[32:35]
	v_mfma_f32_16x16x32_bf16 v[24:27], v[178:181], v[196:199], v[24:27]
	v_mfma_f32_16x16x32_bf16 v[16:19], v[170:173], v[204:207], v[16:19]
	v_mfma_f32_16x16x32_bf16 v[8:11], v[178:181], v[204:207], v[8:11]
	v_mfma_f32_16x16x32_bf16 v[4:7], v[170:173], v[212:215], v[4:7]
	v_mfma_f32_16x16x32_bf16 v[0:3], v[178:181], v[212:215], v[0:3]
	s_setprio 0
	s_barrier
	s_add_i32 s68, 0, 0x18000
	s_add_i32 s69, 0, 0x1c000
	v_add_u32_e32 v162, s68, v149
	v_add_u32_e32 v178, s69, v149
	ds_read_b128 v[144:147], v162
	ds_read_b128 v[154:157], v162 offset:1024
	ds_read_b128 v[158:161], v162 offset:2048
	ds_read_b128 v[162:165], v162 offset:3072
	ds_read_b128 v[166:169], v178
	ds_read_b128 v[170:173], v178 offset:1024
	ds_read_b128 v[174:177], v178 offset:2048
	ds_read_b128 v[178:181], v178 offset:3072
	s_add_u32 s16, s22, 0x18000
	s_addc_u32 s17, s23, 0
	s_mov_b32 m0, s34
	ds_read_b128 v[182:185], v153 offset:32768
	ds_read_b128 v[186:189], v153 offset:33792
	ds_read_b128 v[192:195], v153 offset:34816
	ds_read_b128 v[196:199], v153 offset:35840
	ds_read_b128 v[200:203], v153 offset:36864
	ds_read_b128 v[204:207], v153 offset:37888
	ds_read_b128 v[208:211], v153 offset:38912
	ds_read_b128 v[212:215], v153 offset:39936
	global_load_lds_dwordx4 v134, s[16:17]
	s_mov_b32 m0, s35
	s_nop 0
	global_load_lds_dwordx4 v130, s[16:17]
	s_waitcnt vmcnt(8)
	s_waitcnt lgkmcnt(0)
	s_barrier
	s_setprio 1
	s_waitcnt lgkmcnt(0)
	v_mfma_f32_16x16x32_bf16 v[124:127], v[144:147], v[182:185], v[124:127]
	v_mfma_f32_16x16x32_bf16 v[120:123], v[158:161], v[182:185], v[120:123]
	v_mfma_f32_16x16x32_bf16 v[116:119], v[144:147], v[192:195], v[116:119]
	v_mfma_f32_16x16x32_bf16 v[108:111], v[158:161], v[192:195], v[108:111]
	v_mfma_f32_16x16x32_bf16 v[100:103], v[144:147], v[200:203], v[100:103]
	v_mfma_f32_16x16x32_bf16 v[92:95], v[158:161], v[200:203], v[92:95]
	v_mfma_f32_16x16x32_bf16 v[84:87], v[144:147], v[208:211], v[84:87]
	v_mfma_f32_16x16x32_bf16 v[76:79], v[158:161], v[208:211], v[76:79]
	v_mfma_f32_16x16x32_bf16 v[124:127], v[154:157], v[186:189], v[124:127]
	v_mfma_f32_16x16x32_bf16 v[120:123], v[162:165], v[186:189], v[120:123]
	v_mfma_f32_16x16x32_bf16 v[116:119], v[154:157], v[196:199], v[116:119]
	v_mfma_f32_16x16x32_bf16 v[108:111], v[162:165], v[196:199], v[108:111]
	v_mfma_f32_16x16x32_bf16 v[100:103], v[154:157], v[204:207], v[100:103]
	v_mfma_f32_16x16x32_bf16 v[92:95], v[162:165], v[204:207], v[92:95]
	v_mfma_f32_16x16x32_bf16 v[84:87], v[154:157], v[212:215], v[84:87]
	v_mfma_f32_16x16x32_bf16 v[76:79], v[162:165], v[212:215], v[76:79]
	s_setprio 0
	s_setprio 1
	v_mfma_f32_16x16x32_bf16 v[112:115], v[166:169], v[182:185], v[112:115]
	v_mfma_f32_16x16x32_bf16 v[104:107], v[174:177], v[182:185], v[104:107]
	v_mfma_f32_16x16x32_bf16 v[96:99], v[166:169], v[192:195], v[96:99]
	v_mfma_f32_16x16x32_bf16 v[88:91], v[174:177], v[192:195], v[88:91]
	v_mfma_f32_16x16x32_bf16 v[80:83], v[166:169], v[200:203], v[80:83]
	v_mfma_f32_16x16x32_bf16 v[72:75], v[174:177], v[200:203], v[72:75]
	v_mfma_f32_16x16x32_bf16 v[68:71], v[166:169], v[208:211], v[68:71]
	v_mfma_f32_16x16x32_bf16 v[64:67], v[174:177], v[208:211], v[64:67]
	v_mfma_f32_16x16x32_bf16 v[112:115], v[170:173], v[186:189], v[112:115]
	v_mfma_f32_16x16x32_bf16 v[104:107], v[178:181], v[186:189], v[104:107]
	v_mfma_f32_16x16x32_bf16 v[96:99], v[170:173], v[196:199], v[96:99]
	v_mfma_f32_16x16x32_bf16 v[88:91], v[178:181], v[196:199], v[88:91]
	v_mfma_f32_16x16x32_bf16 v[80:83], v[170:173], v[204:207], v[80:83]
	v_mfma_f32_16x16x32_bf16 v[72:75], v[178:181], v[204:207], v[72:75]
	v_mfma_f32_16x16x32_bf16 v[68:71], v[170:173], v[212:215], v[68:71]
	v_mfma_f32_16x16x32_bf16 v[64:67], v[178:181], v[212:215], v[64:67]
	s_setprio 0
	s_barrier
	s_add_i32 s16, s68, s28
	s_mov_b32 m0, s16
	ds_read_b128 v[182:185], v153 offset:49152
	ds_read_b128 v[186:189], v153 offset:50176
	ds_read_b128 v[192:195], v153 offset:51200
	ds_read_b128 v[196:199], v153 offset:52224
	ds_read_b128 v[200:203], v153 offset:53248
	ds_read_b128 v[204:207], v153 offset:54272
	ds_read_b128 v[208:211], v153 offset:55296
	ds_read_b128 v[212:215], v153 offset:56320
	global_load_lds_dwordx4 v132, s[98:99]
	s_add_i32 m0, s16, 0x2000
	s_add_u32 s16, s20, 0x18080
	s_addc_u32 s17, s21, 0
	s_add_i32 s20, s69, s28
	global_load_lds_dwordx4 v128, s[98:99]
	s_mov_b32 m0, s20
	s_nop 0
	global_load_lds_dwordx4 v132, s[16:17]
	s_add_i32 m0, s20, 0x2000
	s_nop 0
	global_load_lds_dwordx4 v128, s[16:17]
	s_mov_b32 m0, s43
	s_nop 0
	global_load_lds_dwordx4 v134, s[100:101]
	s_mov_b32 m0, s52
	s_nop 0
	global_load_lds_dwordx4 v130, s[100:101]
	s_waitcnt vmcnt(8)
	s_waitcnt lgkmcnt(0)
	s_barrier
	s_setprio 1
	s_waitcnt lgkmcnt(0)
	v_mfma_f32_16x16x32_bf16 v[60:63], v[144:147], v[182:185], v[60:63]
	v_mfma_f32_16x16x32_bf16 v[56:59], v[158:161], v[182:185], v[56:59]
	v_mfma_f32_16x16x32_bf16 v[52:55], v[144:147], v[192:195], v[52:55]
	v_mfma_f32_16x16x32_bf16 v[44:47], v[158:161], v[192:195], v[44:47]
	v_mfma_f32_16x16x32_bf16 v[36:39], v[144:147], v[200:203], v[36:39]
	v_mfma_f32_16x16x32_bf16 v[28:31], v[158:161], v[200:203], v[28:31]
	v_mfma_f32_16x16x32_bf16 v[20:23], v[144:147], v[208:211], v[20:23]
	v_mfma_f32_16x16x32_bf16 v[12:15], v[158:161], v[208:211], v[12:15]
	v_mfma_f32_16x16x32_bf16 v[60:63], v[154:157], v[186:189], v[60:63]
	v_mfma_f32_16x16x32_bf16 v[56:59], v[162:165], v[186:189], v[56:59]
	v_mfma_f32_16x16x32_bf16 v[52:55], v[154:157], v[196:199], v[52:55]
	v_mfma_f32_16x16x32_bf16 v[44:47], v[162:165], v[196:199], v[44:47]
	v_mfma_f32_16x16x32_bf16 v[36:39], v[154:157], v[204:207], v[36:39]
	v_mfma_f32_16x16x32_bf16 v[28:31], v[162:165], v[204:207], v[28:31]
	v_mfma_f32_16x16x32_bf16 v[20:23], v[154:157], v[212:215], v[20:23]
	v_mfma_f32_16x16x32_bf16 v[12:15], v[162:165], v[212:215], v[12:15]
	s_setprio 0
	s_setprio 1
	v_mfma_f32_16x16x32_bf16 v[48:51], v[166:169], v[182:185], v[48:51]
	v_mfma_f32_16x16x32_bf16 v[40:43], v[174:177], v[182:185], v[40:43]
	v_mfma_f32_16x16x32_bf16 v[32:35], v[166:169], v[192:195], v[32:35]
	v_mfma_f32_16x16x32_bf16 v[24:27], v[174:177], v[192:195], v[24:27]
	v_mfma_f32_16x16x32_bf16 v[16:19], v[166:169], v[200:203], v[16:19]
	v_mfma_f32_16x16x32_bf16 v[8:11], v[174:177], v[200:203], v[8:11]
	v_mfma_f32_16x16x32_bf16 v[4:7], v[166:169], v[208:211], v[4:7]
	v_mfma_f32_16x16x32_bf16 v[0:3], v[174:177], v[208:211], v[0:3]
	v_mfma_f32_16x16x32_bf16 v[48:51], v[170:173], v[186:189], v[48:51]
	v_mfma_f32_16x16x32_bf16 v[40:43], v[178:181], v[186:189], v[40:43]
	v_mfma_f32_16x16x32_bf16 v[32:35], v[170:173], v[196:199], v[32:35]
	v_mfma_f32_16x16x32_bf16 v[24:27], v[178:181], v[196:199], v[24:27]
	v_mfma_f32_16x16x32_bf16 v[16:19], v[170:173], v[204:207], v[16:19]
	v_mfma_f32_16x16x32_bf16 v[8:11], v[178:181], v[204:207], v[8:11]
	v_mfma_f32_16x16x32_bf16 v[4:7], v[170:173], v[212:215], v[4:7]
	v_mfma_f32_16x16x32_bf16 v[0:3], v[178:181], v[212:215], v[0:3]
	s_setprio 0
	s_barrier
	s_add_i32 s67, s67, 2
	s_add_u32 s65, s65, 0x100
	s_addc_u32 s66, s66, 0
	s_cmp_gt_u32 s67, 3
	s_mov_b64 s[16:17], s[18:19]
	s_cbranch_scc0 .LBB0_1266
	s_and_b64 vcc, exec, s[12:13]
	s_cbranch_vccz .LBB0_1269
	s_barrier

.LBB0_1434:
	ds_read_b128 v[152:155], v149
	ds_read_b128 v[156:159], v149 offset:1024
	ds_read_b128 v[160:163], v149 offset:2048
	ds_read_b128 v[164:167], v149 offset:3072
	ds_read_b128 v[168:171], v150
	ds_read_b128 v[172:175], v150 offset:1024
	ds_read_b128 v[176:179], v150 offset:2048
	ds_read_b128 v[180:183], v150 offset:3072
	s_add_u32 s34, s30, 0xfffc0080
	s_addc_u32 s35, s31, -1
	s_cmp_eq_u32 s77, 12
	s_cselect_b32 s43, s23, s35
	s_cselect_b32 s42, s55, s34
	s_cselect_b32 s35, s21, s76
	s_cselect_b32 s34, s74, s75
	s_add_i32 m0, s29, 0xc000
	ds_read_b128 v[184:187], v151
	ds_read_b128 v[192:195], v151 offset:1024
	ds_read_b128 v[196:199], v151 offset:2048
	ds_read_b128 v[200:203], v151 offset:3072
	ds_read_b128 v[204:207], v151 offset:4096
	ds_read_b128 v[208:211], v151 offset:5120
	ds_read_b128 v[212:215], v151 offset:6144
	ds_read_b128 v[216:219], v151 offset:7168
	global_load_lds_dwordx4 v136, s[30:31]
	s_add_i32 m0, s29, 0xe000
	s_nop 0
	global_load_lds_dwordx4 v138, s[30:31]
	s_waitcnt vmcnt(8)
	s_waitcnt lgkmcnt(0)
	s_barrier
	s_setprio 1
	s_waitcnt lgkmcnt(0)
	v_mfma_f32_16x16x32_bf16 v[124:127], v[152:155], v[184:187], v[124:127]
	v_mfma_f32_16x16x32_bf16 v[120:123], v[160:163], v[184:187], v[120:123]
	v_mfma_f32_16x16x32_bf16 v[116:119], v[152:155], v[196:199], v[116:119]
	v_mfma_f32_16x16x32_bf16 v[108:111], v[160:163], v[196:199], v[108:111]
	v_mfma_f32_16x16x32_bf16 v[100:103], v[152:155], v[204:207], v[100:103]
	v_mfma_f32_16x16x32_bf16 v[92:95], v[160:163], v[204:207], v[92:95]
	v_mfma_f32_16x16x32_bf16 v[84:87], v[152:155], v[212:215], v[84:87]
	v_mfma_f32_16x16x32_bf16 v[76:79], v[160:163], v[212:215], v[76:79]
	v_mfma_f32_16x16x32_bf16 v[124:127], v[156:159], v[192:195], v[124:127]
	v_mfma_f32_16x16x32_bf16 v[120:123], v[164:167], v[192:195], v[120:123]
	v_mfma_f32_16x16x32_bf16 v[116:119], v[156:159], v[200:203], v[116:119]
	v_mfma_f32_16x16x32_bf16 v[108:111], v[164:167], v[200:203], v[108:111]
	v_mfma_f32_16x16x32_bf16 v[100:103], v[156:159], v[208:211], v[100:103]
	v_mfma_f32_16x16x32_bf16 v[92:95], v[164:167], v[208:211], v[92:95]
	v_mfma_f32_16x16x32_bf16 v[84:87], v[156:159], v[216:219], v[84:87]
	v_mfma_f32_16x16x32_bf16 v[76:79], v[164:167], v[216:219], v[76:79]
	s_setprio 0
	s_setprio 1
	v_mfma_f32_16x16x32_bf16 v[112:115], v[168:171], v[184:187], v[112:115]
	v_mfma_f32_16x16x32_bf16 v[104:107], v[176:179], v[184:187], v[104:107]
	v_mfma_f32_16x16x32_bf16 v[96:99], v[168:171], v[196:199], v[96:99]
	v_mfma_f32_16x16x32_bf16 v[88:91], v[176:179], v[196:199], v[88:91]
	v_mfma_f32_16x16x32_bf16 v[80:83], v[168:171], v[204:207], v[80:83]
	v_mfma_f32_16x16x32_bf16 v[72:75], v[176:179], v[204:207], v[72:75]
	v_mfma_f32_16x16x32_bf16 v[68:71], v[168:171], v[212:215], v[68:71]
	v_mfma_f32_16x16x32_bf16 v[64:67], v[176:179], v[212:215], v[64:67]
	v_mfma_f32_16x16x32_bf16 v[112:115], v[172:175], v[192:195], v[112:115]
	v_mfma_f32_16x16x32_bf16 v[104:107], v[180:183], v[192:195], v[104:107]
	v_mfma_f32_16x16x32_bf16 v[96:99], v[172:175], v[200:203], v[96:99]
	v_mfma_f32_16x16x32_bf16 v[88:91], v[180:183], v[200:203], v[88:91]
	v_mfma_f32_16x16x32_bf16 v[80:83], v[172:175], v[208:211], v[80:83]
	v_mfma_f32_16x16x32_bf16 v[72:75], v[180:183], v[208:211], v[72:75]
	v_mfma_f32_16x16x32_bf16 v[68:71], v[172:175], v[216:219], v[68:71]
	v_mfma_f32_16x16x32_bf16 v[64:67], v[180:183], v[216:219], v[64:67]
	s_setprio 0
	s_barrier
	s_add_i32 s79, s68, s61
	s_add_u32 s98, s34, 0x80
	s_addc_u32 s99, s35, 0
	s_mov_b32 m0, s79
	ds_read_b128 v[184:187], v151 offset:16384
	ds_read_b128 v[192:195], v151 offset:17408
	ds_read_b128 v[196:199], v151 offset:18432
	ds_read_b128 v[200:203], v151 offset:19456
	ds_read_b128 v[204:207], v151 offset:20480
	ds_read_b128 v[208:211], v151 offset:21504
	ds_read_b128 v[212:215], v151 offset:22528
	ds_read_b128 v[216:219], v151 offset:23552
	global_load_lds_dwordx4 v130, s[34:35]
	s_add_i32 m0, s79, 0x2000
	s_add_u32 s80, s34, 0x40000
	s_addc_u32 s81, s35, 0
	s_add_i32 s79, s69, s61
	global_load_lds_dwordx4 v134, s[34:35]
	s_mov_b32 m0, s79
	s_add_u32 s100, s42, 0x80
	s_addc_u32 s101, s43, 0
	global_load_lds_dwordx4 v130, s[80:81]
	s_add_i32 m0, s79, 0x2000
	s_nop 0
	global_load_lds_dwordx4 v134, s[80:81]
	s_mov_b32 m0, s29
	s_nop 0
	global_load_lds_dwordx4 v128, s[42:43]
	s_mov_b32 m0, s33
	s_nop 0
	global_load_lds_dwordx4 v132, s[42:43]
	s_waitcnt vmcnt(8)
	s_waitcnt lgkmcnt(0)
	s_barrier
	s_setprio 1
	s_waitcnt lgkmcnt(0)
	v_mfma_f32_16x16x32_bf16 v[60:63], v[152:155], v[184:187], v[60:63]
	v_mfma_f32_16x16x32_bf16 v[56:59], v[160:163], v[184:187], v[56:59]
	v_mfma_f32_16x16x32_bf16 v[52:55], v[152:155], v[196:199], v[52:55]
	v_mfma_f32_16x16x32_bf16 v[44:47], v[160:163], v[196:199], v[44:47]
	v_mfma_f32_16x16x32_bf16 v[36:39], v[152:155], v[204:207], v[36:39]
	v_mfma_f32_16x16x32_bf16 v[28:31], v[160:163], v[204:207], v[28:31]
	v_mfma_f32_16x16x32_bf16 v[20:23], v[152:155], v[212:215], v[20:23]
	v_mfma_f32_16x16x32_bf16 v[12:15], v[160:163], v[212:215], v[12:15]
	v_mfma_f32_16x16x32_bf16 v[60:63], v[156:159], v[192:195], v[60:63]
	v_mfma_f32_16x16x32_bf16 v[56:59], v[164:167], v[192:195], v[56:59]
	v_mfma_f32_16x16x32_bf16 v[52:55], v[156:159], v[200:203], v[52:55]
	v_mfma_f32_16x16x32_bf16 v[44:47], v[164:167], v[200:203], v[44:47]
	v_mfma_f32_16x16x32_bf16 v[36:39], v[156:159], v[208:211], v[36:39]
	v_mfma_f32_16x16x32_bf16 v[28:31], v[164:167], v[208:211], v[28:31]
	v_mfma_f32_16x16x32_bf16 v[20:23], v[156:159], v[216:219], v[20:23]
	v_mfma_f32_16x16x32_bf16 v[12:15], v[164:167], v[216:219], v[12:15]
	s_setprio 0
	s_setprio 1
	v_mfma_f32_16x16x32_bf16 v[48:51], v[168:171], v[184:187], v[48:51]
	v_mfma_f32_16x16x32_bf16 v[40:43], v[176:179], v[184:187], v[40:43]
	v_mfma_f32_16x16x32_bf16 v[32:35], v[168:171], v[196:199], v[32:35]
	v_mfma_f32_16x16x32_bf16 v[24:27], v[176:179], v[196:199], v[24:27]
	v_mfma_f32_16x16x32_bf16 v[16:19], v[168:171], v[204:207], v[16:19]
	v_mfma_f32_16x16x32_bf16 v[8:11], v[176:179], v[204:207], v[8:11]
	v_mfma_f32_16x16x32_bf16 v[4:7], v[168:171], v[212:215], v[4:7]
	v_mfma_f32_16x16x32_bf16 v[0:3], v[176:179], v[212:215], v[0:3]
	v_mfma_f32_16x16x32_bf16 v[48:51], v[172:175], v[192:195], v[48:51]
	v_mfma_f32_16x16x32_bf16 v[40:43], v[180:183], v[192:195], v[40:43]
	v_mfma_f32_16x16x32_bf16 v[32:35], v[172:175], v[200:203], v[32:35]
	v_mfma_f32_16x16x32_bf16 v[24:27], v[180:183], v[200:203], v[24:27]
	v_mfma_f32_16x16x32_bf16 v[16:19], v[172:175], v[208:211], v[16:19]
	v_mfma_f32_16x16x32_bf16 v[8:11], v[180:183], v[208:211], v[8:11]
	v_mfma_f32_16x16x32_bf16 v[4:7], v[172:175], v[216:219], v[4:7]
	v_mfma_f32_16x16x32_bf16 v[0:3], v[180:183], v[216:219], v[0:3]
	s_setprio 0
	s_barrier
	s_add_i32 s79, 0, 0x18000
	s_add_i32 s80, 0, 0x1c000
	v_add_u32_e32 v164, s79, v147
	v_add_u32_e32 v180, s80, v147
	ds_read_b128 v[152:155], v164
	ds_read_b128 v[156:159], v164 offset:1024
	ds_read_b128 v[160:163], v164 offset:2048
	ds_read_b128 v[164:167], v164 offset:3072
	ds_read_b128 v[168:171], v180
	ds_read_b128 v[172:175], v180 offset:1024
	ds_read_b128 v[176:179], v180 offset:2048
	ds_read_b128 v[180:183], v180 offset:3072
	s_add_u32 s42, s42, 0x40000
	s_addc_u32 s43, s43, 0
	s_mov_b32 m0, s62
	ds_read_b128 v[184:187], v151 offset:32768
	ds_read_b128 v[192:195], v151 offset:33792
	ds_read_b128 v[196:199], v151 offset:34816
	ds_read_b128 v[200:203], v151 offset:35840
	ds_read_b128 v[204:207], v151 offset:36864
	ds_read_b128 v[208:211], v151 offset:37888
	ds_read_b128 v[212:215], v151 offset:38912
	ds_read_b128 v[216:219], v151 offset:39936
	global_load_lds_dwordx4 v128, s[42:43]
	s_mov_b32 m0, s63
	s_nop 0
	global_load_lds_dwordx4 v132, s[42:43]
	s_waitcnt vmcnt(8)
	s_waitcnt lgkmcnt(0)
	s_barrier
	s_setprio 1
	s_waitcnt lgkmcnt(0)
	v_mfma_f32_16x16x32_bf16 v[124:127], v[152:155], v[184:187], v[124:127]
	v_mfma_f32_16x16x32_bf16 v[120:123], v[160:163], v[184:187], v[120:123]
	v_mfma_f32_16x16x32_bf16 v[116:119], v[152:155], v[196:199], v[116:119]
	v_mfma_f32_16x16x32_bf16 v[108:111], v[160:163], v[196:199], v[108:111]
	v_mfma_f32_16x16x32_bf16 v[100:103], v[152:155], v[204:207], v[100:103]
	v_mfma_f32_16x16x32_bf16 v[92:95], v[160:163], v[204:207], v[92:95]
	v_mfma_f32_16x16x32_bf16 v[84:87], v[152:155], v[212:215], v[84:87]
	v_mfma_f32_16x16x32_bf16 v[76:79], v[160:163], v[212:215], v[76:79]
	v_mfma_f32_16x16x32_bf16 v[124:127], v[156:159], v[192:195], v[124:127]
	v_mfma_f32_16x16x32_bf16 v[120:123], v[164:167], v[192:195], v[120:123]
	v_mfma_f32_16x16x32_bf16 v[116:119], v[156:159], v[200:203], v[116:119]
	v_mfma_f32_16x16x32_bf16 v[108:111], v[164:167], v[200:203], v[108:111]
	v_mfma_f32_16x16x32_bf16 v[100:103], v[156:159], v[208:211], v[100:103]
	v_mfma_f32_16x16x32_bf16 v[92:95], v[164:167], v[208:211], v[92:95]
	v_mfma_f32_16x16x32_bf16 v[84:87], v[156:159], v[216:219], v[84:87]
	v_mfma_f32_16x16x32_bf16 v[76:79], v[164:167], v[216:219], v[76:79]
	s_setprio 0
	s_setprio 1
	v_mfma_f32_16x16x32_bf16 v[112:115], v[168:171], v[184:187], v[112:115]
	v_mfma_f32_16x16x32_bf16 v[104:107], v[176:179], v[184:187], v[104:107]
	v_mfma_f32_16x16x32_bf16 v[96:99], v[168:171], v[196:199], v[96:99]
	v_mfma_f32_16x16x32_bf16 v[88:91], v[176:179], v[196:199], v[88:91]
	v_mfma_f32_16x16x32_bf16 v[80:83], v[168:171], v[204:207], v[80:83]
	v_mfma_f32_16x16x32_bf16 v[72:75], v[176:179], v[204:207], v[72:75]
	v_mfma_f32_16x16x32_bf16 v[68:71], v[168:171], v[212:215], v[68:71]
	v_mfma_f32_16x16x32_bf16 v[64:67], v[176:179], v[212:215], v[64:67]
	v_mfma_f32_16x16x32_bf16 v[112:115], v[172:175], v[192:195], v[112:115]
	v_mfma_f32_16x16x32_bf16 v[104:107], v[180:183], v[192:195], v[104:107]
	v_mfma_f32_16x16x32_bf16 v[96:99], v[172:175], v[200:203], v[96:99]
	v_mfma_f32_16x16x32_bf16 v[88:91], v[180:183], v[200:203], v[88:91]
	v_mfma_f32_16x16x32_bf16 v[80:83], v[172:175], v[208:211], v[80:83]
	v_mfma_f32_16x16x32_bf16 v[72:75], v[180:183], v[208:211], v[72:75]
	v_mfma_f32_16x16x32_bf16 v[68:71], v[172:175], v[216:219], v[68:71]
	v_mfma_f32_16x16x32_bf16 v[64:67], v[180:183], v[216:219], v[64:67]
	s_setprio 0
	s_barrier
	s_add_i32 s42, s79, s61
	s_mov_b32 m0, s42
	ds_read_b128 v[184:187], v151 offset:49152
	ds_read_b128 v[192:195], v151 offset:50176
	ds_read_b128 v[196:199], v151 offset:51200
	ds_read_b128 v[200:203], v151 offset:52224
	ds_read_b128 v[204:207], v151 offset:53248
	ds_read_b128 v[208:211], v151 offset:54272
	ds_read_b128 v[212:215], v151 offset:55296
	ds_read_b128 v[216:219], v151 offset:56320
	global_load_lds_dwordx4 v130, s[98:99]
	s_add_i32 m0, s42, 0x2000
	s_add_u32 s34, s34, 0x40080
	s_addc_u32 s35, s35, 0
	s_add_i32 s42, s80, s61
	global_load_lds_dwordx4 v134, s[98:99]
	s_mov_b32 m0, s42
	s_nop 0
	global_load_lds_dwordx4 v130, s[34:35]
	s_add_i32 m0, s42, 0x2000
	s_nop 0
	global_load_lds_dwordx4 v134, s[34:35]
	s_mov_b32 m0, s65
	s_nop 0
	global_load_lds_dwordx4 v128, s[100:101]
	s_mov_b32 m0, s66
	s_nop 0
	global_load_lds_dwordx4 v132, s[100:101]
	s_waitcnt vmcnt(8)
	s_waitcnt lgkmcnt(0)
	s_barrier
	s_setprio 1
	s_waitcnt lgkmcnt(0)
	v_mfma_f32_16x16x32_bf16 v[60:63], v[152:155], v[184:187], v[60:63]
	v_mfma_f32_16x16x32_bf16 v[56:59], v[160:163], v[184:187], v[56:59]
	v_mfma_f32_16x16x32_bf16 v[52:55], v[152:155], v[196:199], v[52:55]
	v_mfma_f32_16x16x32_bf16 v[44:47], v[160:163], v[196:199], v[44:47]
	v_mfma_f32_16x16x32_bf16 v[36:39], v[152:155], v[204:207], v[36:39]
	v_mfma_f32_16x16x32_bf16 v[28:31], v[160:163], v[204:207], v[28:31]
	v_mfma_f32_16x16x32_bf16 v[20:23], v[152:155], v[212:215], v[20:23]
	v_mfma_f32_16x16x32_bf16 v[12:15], v[160:163], v[212:215], v[12:15]
	v_mfma_f32_16x16x32_bf16 v[60:63], v[156:159], v[192:195], v[60:63]
	v_mfma_f32_16x16x32_bf16 v[56:59], v[164:167], v[192:195], v[56:59]
	v_mfma_f32_16x16x32_bf16 v[52:55], v[156:159], v[200:203], v[52:55]
	v_mfma_f32_16x16x32_bf16 v[44:47], v[164:167], v[200:203], v[44:47]
	v_mfma_f32_16x16x32_bf16 v[36:39], v[156:159], v[208:211], v[36:39]
	v_mfma_f32_16x16x32_bf16 v[28:31], v[164:167], v[208:211], v[28:31]
	v_mfma_f32_16x16x32_bf16 v[20:23], v[156:159], v[216:219], v[20:23]
	v_mfma_f32_16x16x32_bf16 v[12:15], v[164:167], v[216:219], v[12:15]
	s_setprio 0
	s_setprio 1
	v_mfma_f32_16x16x32_bf16 v[48:51], v[168:171], v[184:187], v[48:51]
	v_mfma_f32_16x16x32_bf16 v[40:43], v[176:179], v[184:187], v[40:43]
	v_mfma_f32_16x16x32_bf16 v[32:35], v[168:171], v[196:199], v[32:35]
	v_mfma_f32_16x16x32_bf16 v[24:27], v[176:179], v[196:199], v[24:27]
	v_mfma_f32_16x16x32_bf16 v[16:19], v[168:171], v[204:207], v[16:19]
	v_mfma_f32_16x16x32_bf16 v[8:11], v[176:179], v[204:207], v[8:11]
	v_mfma_f32_16x16x32_bf16 v[4:7], v[168:171], v[212:215], v[4:7]
	v_mfma_f32_16x16x32_bf16 v[0:3], v[176:179], v[212:215], v[0:3]
	v_mfma_f32_16x16x32_bf16 v[48:51], v[172:175], v[192:195], v[48:51]
	v_mfma_f32_16x16x32_bf16 v[40:43], v[180:183], v[192:195], v[40:43]
	v_mfma_f32_16x16x32_bf16 v[32:35], v[172:175], v[200:203], v[32:35]
	v_mfma_f32_16x16x32_bf16 v[24:27], v[180:183], v[200:203], v[24:27]
	v_mfma_f32_16x16x32_bf16 v[16:19], v[172:175], v[208:211], v[16:19]
	v_mfma_f32_16x16x32_bf16 v[8:11], v[180:183], v[208:211], v[8:11]
	v_mfma_f32_16x16x32_bf16 v[4:7], v[172:175], v[216:219], v[4:7]
	v_mfma_f32_16x16x32_bf16 v[0:3], v[180:183], v[216:219], v[0:3]
	s_setprio 0
	s_barrier
	s_add_i32 s77, s77, 2
	s_add_u32 s30, s30, 0x100
	s_addc_u32 s31, s31, 0
	s_add_u32 s75, s75, 0x100
	s_addc_u32 s76, s76, 0
	s_cmp_gt_u32 s77, 13
	s_cbranch_scc0 .LBB0_1434
	s_and_b64 vcc, exec, s[12:13]
	s_cbranch_vccz .LBB0_1437
	s_barrier

.LBB0_1571:
	ds_read_b128 v[152:155], v149
	ds_read_b128 v[156:159], v149 offset:1024
	ds_read_b128 v[160:163], v149 offset:2048
	ds_read_b128 v[164:167], v149 offset:3072
	ds_read_b128 v[168:171], v150
	ds_read_b128 v[172:175], v150 offset:1024
	ds_read_b128 v[176:179], v150 offset:2048
	ds_read_b128 v[180:183], v150 offset:3072
	s_add_u32 s34, s30, 0xfffc0080
	s_addc_u32 s35, s31, -1
	s_cmp_eq_u32 s77, 12
	s_cselect_b32 s43, s23, s35
	s_cselect_b32 s42, s54, s34
	s_cselect_b32 s35, s21, s76
	s_cselect_b32 s34, s55, s75
	s_add_i32 m0, s29, 0xc000
	ds_read_b128 v[184:187], v151
	ds_read_b128 v[192:195], v151 offset:1024
	ds_read_b128 v[196:199], v151 offset:2048
	ds_read_b128 v[200:203], v151 offset:3072
	ds_read_b128 v[204:207], v151 offset:4096
	ds_read_b128 v[208:211], v151 offset:5120
	ds_read_b128 v[212:215], v151 offset:6144
	ds_read_b128 v[216:219], v151 offset:7168
	global_load_lds_dwordx4 v136, s[30:31]
	s_add_i32 m0, s29, 0xe000
	s_nop 0
	global_load_lds_dwordx4 v138, s[30:31]
	s_waitcnt vmcnt(8)
	s_waitcnt lgkmcnt(0)
	s_barrier
	s_setprio 1
	s_waitcnt lgkmcnt(0)
	v_mfma_f32_16x16x32_bf16 v[124:127], v[152:155], v[184:187], v[124:127]
	v_mfma_f32_16x16x32_bf16 v[120:123], v[160:163], v[184:187], v[120:123]
	v_mfma_f32_16x16x32_bf16 v[108:111], v[152:155], v[196:199], v[108:111]
	v_mfma_f32_16x16x32_bf16 v[104:107], v[160:163], v[196:199], v[104:107]
	v_mfma_f32_16x16x32_bf16 v[92:95], v[152:155], v[204:207], v[92:95]
	v_mfma_f32_16x16x32_bf16 v[88:91], v[160:163], v[204:207], v[88:91]
	v_mfma_f32_16x16x32_bf16 v[76:79], v[152:155], v[212:215], v[76:79]
	v_mfma_f32_16x16x32_bf16 v[72:75], v[160:163], v[212:215], v[72:75]
	v_mfma_f32_16x16x32_bf16 v[124:127], v[156:159], v[192:195], v[124:127]
	v_mfma_f32_16x16x32_bf16 v[120:123], v[164:167], v[192:195], v[120:123]
	v_mfma_f32_16x16x32_bf16 v[108:111], v[156:159], v[200:203], v[108:111]
	v_mfma_f32_16x16x32_bf16 v[104:107], v[164:167], v[200:203], v[104:107]
	v_mfma_f32_16x16x32_bf16 v[92:95], v[156:159], v[208:211], v[92:95]
	v_mfma_f32_16x16x32_bf16 v[88:91], v[164:167], v[208:211], v[88:91]
	v_mfma_f32_16x16x32_bf16 v[76:79], v[156:159], v[216:219], v[76:79]
	v_mfma_f32_16x16x32_bf16 v[72:75], v[164:167], v[216:219], v[72:75]
	s_setprio 0
	s_setprio 1
	v_mfma_f32_16x16x32_bf16 v[116:119], v[168:171], v[184:187], v[116:119]
	v_mfma_f32_16x16x32_bf16 v[112:115], v[176:179], v[184:187], v[112:115]
	v_mfma_f32_16x16x32_bf16 v[100:103], v[168:171], v[196:199], v[100:103]
	v_mfma_f32_16x16x32_bf16 v[96:99], v[176:179], v[196:199], v[96:99]
	v_mfma_f32_16x16x32_bf16 v[84:87], v[168:171], v[204:207], v[84:87]
	v_mfma_f32_16x16x32_bf16 v[80:83], v[176:179], v[204:207], v[80:83]
	v_mfma_f32_16x16x32_bf16 v[68:71], v[168:171], v[212:215], v[68:71]
	v_mfma_f32_16x16x32_bf16 v[64:67], v[176:179], v[212:215], v[64:67]
	v_mfma_f32_16x16x32_bf16 v[116:119], v[172:175], v[192:195], v[116:119]
	v_mfma_f32_16x16x32_bf16 v[112:115], v[180:183], v[192:195], v[112:115]
	v_mfma_f32_16x16x32_bf16 v[100:103], v[172:175], v[200:203], v[100:103]
	v_mfma_f32_16x16x32_bf16 v[96:99], v[180:183], v[200:203], v[96:99]
	v_mfma_f32_16x16x32_bf16 v[84:87], v[172:175], v[208:211], v[84:87]
	v_mfma_f32_16x16x32_bf16 v[80:83], v[180:183], v[208:211], v[80:83]
	v_mfma_f32_16x16x32_bf16 v[68:71], v[172:175], v[216:219], v[68:71]
	v_mfma_f32_16x16x32_bf16 v[64:67], v[180:183], v[216:219], v[64:67]
	s_setprio 0
	s_barrier
	s_add_i32 s79, s69, s63
	s_add_u32 s98, s34, 0x80
	s_addc_u32 s99, s35, 0
	s_mov_b32 m0, s79
	ds_read_b128 v[184:187], v151 offset:16384
	ds_read_b128 v[192:195], v151 offset:17408
	ds_read_b128 v[196:199], v151 offset:18432
	ds_read_b128 v[200:203], v151 offset:19456
	ds_read_b128 v[204:207], v151 offset:20480
	ds_read_b128 v[208:211], v151 offset:21504
	ds_read_b128 v[212:215], v151 offset:22528
	ds_read_b128 v[216:219], v151 offset:23552
	global_load_lds_dwordx4 v130, s[34:35]
	s_add_i32 m0, s79, 0x2000
	s_add_u32 s80, s34, 0x40000
	s_addc_u32 s81, s35, 0
	s_add_i32 s79, s70, s63
	global_load_lds_dwordx4 v134, s[34:35]
	s_mov_b32 m0, s79
	s_add_u32 s100, s42, 0x80
	s_addc_u32 s101, s43, 0
	global_load_lds_dwordx4 v130, s[80:81]
	s_add_i32 m0, s79, 0x2000
	s_nop 0
	global_load_lds_dwordx4 v134, s[80:81]
	s_mov_b32 m0, s29
	s_nop 0
	global_load_lds_dwordx4 v128, s[42:43]
	s_mov_b32 m0, s64
	s_nop 0
	global_load_lds_dwordx4 v132, s[42:43]
	s_waitcnt vmcnt(8)
	s_waitcnt lgkmcnt(0)
	s_barrier
	s_setprio 1
	s_waitcnt lgkmcnt(0)
	v_mfma_f32_16x16x32_bf16 v[60:63], v[152:155], v[184:187], v[60:63]
	v_mfma_f32_16x16x32_bf16 v[56:59], v[160:163], v[184:187], v[56:59]
	v_mfma_f32_16x16x32_bf16 v[44:47], v[152:155], v[196:199], v[44:47]
	v_mfma_f32_16x16x32_bf16 v[40:43], v[160:163], v[196:199], v[40:43]
	v_mfma_f32_16x16x32_bf16 v[28:31], v[152:155], v[204:207], v[28:31]
	v_mfma_f32_16x16x32_bf16 v[24:27], v[160:163], v[204:207], v[24:27]
	v_mfma_f32_16x16x32_bf16 v[12:15], v[152:155], v[212:215], v[12:15]
	v_mfma_f32_16x16x32_bf16 v[8:11], v[160:163], v[212:215], v[8:11]
	v_mfma_f32_16x16x32_bf16 v[60:63], v[156:159], v[192:195], v[60:63]
	v_mfma_f32_16x16x32_bf16 v[56:59], v[164:167], v[192:195], v[56:59]
	v_mfma_f32_16x16x32_bf16 v[44:47], v[156:159], v[200:203], v[44:47]
	v_mfma_f32_16x16x32_bf16 v[40:43], v[164:167], v[200:203], v[40:43]
	v_mfma_f32_16x16x32_bf16 v[28:31], v[156:159], v[208:211], v[28:31]
	v_mfma_f32_16x16x32_bf16 v[24:27], v[164:167], v[208:211], v[24:27]
	v_mfma_f32_16x16x32_bf16 v[12:15], v[156:159], v[216:219], v[12:15]
	v_mfma_f32_16x16x32_bf16 v[8:11], v[164:167], v[216:219], v[8:11]
	s_setprio 0
	s_setprio 1
	v_mfma_f32_16x16x32_bf16 v[52:55], v[168:171], v[184:187], v[52:55]
	v_mfma_f32_16x16x32_bf16 v[48:51], v[176:179], v[184:187], v[48:51]
	v_mfma_f32_16x16x32_bf16 v[36:39], v[168:171], v[196:199], v[36:39]
	v_mfma_f32_16x16x32_bf16 v[32:35], v[176:179], v[196:199], v[32:35]
	v_mfma_f32_16x16x32_bf16 v[20:23], v[168:171], v[204:207], v[20:23]
	v_mfma_f32_16x16x32_bf16 v[16:19], v[176:179], v[204:207], v[16:19]
	v_mfma_f32_16x16x32_bf16 v[4:7], v[168:171], v[212:215], v[4:7]
	v_mfma_f32_16x16x32_bf16 v[0:3], v[176:179], v[212:215], v[0:3]
	v_mfma_f32_16x16x32_bf16 v[52:55], v[172:175], v[192:195], v[52:55]
	v_mfma_f32_16x16x32_bf16 v[48:51], v[180:183], v[192:195], v[48:51]
	v_mfma_f32_16x16x32_bf16 v[36:39], v[172:175], v[200:203], v[36:39]
	v_mfma_f32_16x16x32_bf16 v[32:35], v[180:183], v[200:203], v[32:35]
	v_mfma_f32_16x16x32_bf16 v[20:23], v[172:175], v[208:211], v[20:23]
	v_mfma_f32_16x16x32_bf16 v[16:19], v[180:183], v[208:211], v[16:19]
	v_mfma_f32_16x16x32_bf16 v[4:7], v[172:175], v[216:219], v[4:7]
	v_mfma_f32_16x16x32_bf16 v[0:3], v[180:183], v[216:219], v[0:3]
	s_setprio 0
	s_barrier
	s_add_i32 s79, 0, 0x18000
	s_add_i32 s80, 0, 0x1c000
	v_add_u32_e32 v164, s79, v147
	v_add_u32_e32 v180, s80, v147
	ds_read_b128 v[152:155], v164
	ds_read_b128 v[156:159], v164 offset:1024
	ds_read_b128 v[160:163], v164 offset:2048
	ds_read_b128 v[164:167], v164 offset:3072
	ds_read_b128 v[168:171], v180
	ds_read_b128 v[172:175], v180 offset:1024
	ds_read_b128 v[176:179], v180 offset:2048
	ds_read_b128 v[180:183], v180 offset:3072
	s_add_u32 s42, s42, 0x40000
	s_addc_u32 s43, s43, 0
	s_mov_b32 m0, s65
	ds_read_b128 v[184:187], v151 offset:32768
	ds_read_b128 v[192:195], v151 offset:33792
	ds_read_b128 v[196:199], v151 offset:34816
	ds_read_b128 v[200:203], v151 offset:35840
	ds_read_b128 v[204:207], v151 offset:36864
	ds_read_b128 v[208:211], v151 offset:37888
	ds_read_b128 v[212:215], v151 offset:38912
	ds_read_b128 v[216:219], v151 offset:39936
	global_load_lds_dwordx4 v128, s[42:43]
	s_mov_b32 m0, s66
	s_nop 0
	global_load_lds_dwordx4 v132, s[42:43]
	s_waitcnt vmcnt(8)
	s_waitcnt lgkmcnt(0)
	s_barrier
	s_setprio 1
	s_waitcnt lgkmcnt(0)
	v_mfma_f32_16x16x32_bf16 v[124:127], v[152:155], v[184:187], v[124:127]
	v_mfma_f32_16x16x32_bf16 v[120:123], v[160:163], v[184:187], v[120:123]
	v_mfma_f32_16x16x32_bf16 v[108:111], v[152:155], v[196:199], v[108:111]
	v_mfma_f32_16x16x32_bf16 v[104:107], v[160:163], v[196:199], v[104:107]
	v_mfma_f32_16x16x32_bf16 v[92:95], v[152:155], v[204:207], v[92:95]
	v_mfma_f32_16x16x32_bf16 v[88:91], v[160:163], v[204:207], v[88:91]
	v_mfma_f32_16x16x32_bf16 v[76:79], v[152:155], v[212:215], v[76:79]
	v_mfma_f32_16x16x32_bf16 v[72:75], v[160:163], v[212:215], v[72:75]
	v_mfma_f32_16x16x32_bf16 v[124:127], v[156:159], v[192:195], v[124:127]
	v_mfma_f32_16x16x32_bf16 v[120:123], v[164:167], v[192:195], v[120:123]
	v_mfma_f32_16x16x32_bf16 v[108:111], v[156:159], v[200:203], v[108:111]
	v_mfma_f32_16x16x32_bf16 v[104:107], v[164:167], v[200:203], v[104:107]
	v_mfma_f32_16x16x32_bf16 v[92:95], v[156:159], v[208:211], v[92:95]
	v_mfma_f32_16x16x32_bf16 v[88:91], v[164:167], v[208:211], v[88:91]
	v_mfma_f32_16x16x32_bf16 v[76:79], v[156:159], v[216:219], v[76:79]
	v_mfma_f32_16x16x32_bf16 v[72:75], v[164:167], v[216:219], v[72:75]
	s_setprio 0
	s_setprio 1
	v_mfma_f32_16x16x32_bf16 v[116:119], v[168:171], v[184:187], v[116:119]
	v_mfma_f32_16x16x32_bf16 v[112:115], v[176:179], v[184:187], v[112:115]
	v_mfma_f32_16x16x32_bf16 v[100:103], v[168:171], v[196:199], v[100:103]
	v_mfma_f32_16x16x32_bf16 v[96:99], v[176:179], v[196:199], v[96:99]
	v_mfma_f32_16x16x32_bf16 v[84:87], v[168:171], v[204:207], v[84:87]
	v_mfma_f32_16x16x32_bf16 v[80:83], v[176:179], v[204:207], v[80:83]
	v_mfma_f32_16x16x32_bf16 v[68:71], v[168:171], v[212:215], v[68:71]
	v_mfma_f32_16x16x32_bf16 v[64:67], v[176:179], v[212:215], v[64:67]
	v_mfma_f32_16x16x32_bf16 v[116:119], v[172:175], v[192:195], v[116:119]
	v_mfma_f32_16x16x32_bf16 v[112:115], v[180:183], v[192:195], v[112:115]
	v_mfma_f32_16x16x32_bf16 v[100:103], v[172:175], v[200:203], v[100:103]
	v_mfma_f32_16x16x32_bf16 v[96:99], v[180:183], v[200:203], v[96:99]
	v_mfma_f32_16x16x32_bf16 v[84:87], v[172:175], v[208:211], v[84:87]
	v_mfma_f32_16x16x32_bf16 v[80:83], v[180:183], v[208:211], v[80:83]
	v_mfma_f32_16x16x32_bf16 v[68:71], v[172:175], v[216:219], v[68:71]
	v_mfma_f32_16x16x32_bf16 v[64:67], v[180:183], v[216:219], v[64:67]
	s_setprio 0
	s_barrier
	s_add_i32 s42, s79, s63
	s_mov_b32 m0, s42
	ds_read_b128 v[184:187], v151 offset:49152
	ds_read_b128 v[192:195], v151 offset:50176
	ds_read_b128 v[196:199], v151 offset:51200
	ds_read_b128 v[200:203], v151 offset:52224
	ds_read_b128 v[204:207], v151 offset:53248
	ds_read_b128 v[208:211], v151 offset:54272
	ds_read_b128 v[212:215], v151 offset:55296
	ds_read_b128 v[216:219], v151 offset:56320
	global_load_lds_dwordx4 v130, s[98:99]
	s_add_i32 m0, s42, 0x2000
	s_add_u32 s34, s34, 0x40080
	s_addc_u32 s35, s35, 0
	s_add_i32 s42, s80, s63
	global_load_lds_dwordx4 v134, s[98:99]
	s_mov_b32 m0, s42
	s_nop 0
	global_load_lds_dwordx4 v130, s[34:35]
	s_add_i32 m0, s42, 0x2000
	s_nop 0
	global_load_lds_dwordx4 v134, s[34:35]
	s_mov_b32 m0, s52
	s_nop 0
	global_load_lds_dwordx4 v128, s[100:101]
	s_mov_b32 m0, s53
	s_nop 0
	global_load_lds_dwordx4 v132, s[100:101]
	s_waitcnt vmcnt(8)
	s_waitcnt lgkmcnt(0)
	s_barrier
	s_setprio 1
	s_waitcnt lgkmcnt(0)
	v_mfma_f32_16x16x32_bf16 v[60:63], v[152:155], v[184:187], v[60:63]
	v_mfma_f32_16x16x32_bf16 v[56:59], v[160:163], v[184:187], v[56:59]
	v_mfma_f32_16x16x32_bf16 v[44:47], v[152:155], v[196:199], v[44:47]
	v_mfma_f32_16x16x32_bf16 v[40:43], v[160:163], v[196:199], v[40:43]
	v_mfma_f32_16x16x32_bf16 v[28:31], v[152:155], v[204:207], v[28:31]
	v_mfma_f32_16x16x32_bf16 v[24:27], v[160:163], v[204:207], v[24:27]
	v_mfma_f32_16x16x32_bf16 v[12:15], v[152:155], v[212:215], v[12:15]
	v_mfma_f32_16x16x32_bf16 v[8:11], v[160:163], v[212:215], v[8:11]
	v_mfma_f32_16x16x32_bf16 v[60:63], v[156:159], v[192:195], v[60:63]
	v_mfma_f32_16x16x32_bf16 v[56:59], v[164:167], v[192:195], v[56:59]
	v_mfma_f32_16x16x32_bf16 v[44:47], v[156:159], v[200:203], v[44:47]
	v_mfma_f32_16x16x32_bf16 v[40:43], v[164:167], v[200:203], v[40:43]
	v_mfma_f32_16x16x32_bf16 v[28:31], v[156:159], v[208:211], v[28:31]
	v_mfma_f32_16x16x32_bf16 v[24:27], v[164:167], v[208:211], v[24:27]
	v_mfma_f32_16x16x32_bf16 v[12:15], v[156:159], v[216:219], v[12:15]
	v_mfma_f32_16x16x32_bf16 v[8:11], v[164:167], v[216:219], v[8:11]
	s_setprio 0
	s_setprio 1
	v_mfma_f32_16x16x32_bf16 v[52:55], v[168:171], v[184:187], v[52:55]
	v_mfma_f32_16x16x32_bf16 v[48:51], v[176:179], v[184:187], v[48:51]
	v_mfma_f32_16x16x32_bf16 v[36:39], v[168:171], v[196:199], v[36:39]
	v_mfma_f32_16x16x32_bf16 v[32:35], v[176:179], v[196:199], v[32:35]
	v_mfma_f32_16x16x32_bf16 v[20:23], v[168:171], v[204:207], v[20:23]
	v_mfma_f32_16x16x32_bf16 v[16:19], v[176:179], v[204:207], v[16:19]
	v_mfma_f32_16x16x32_bf16 v[4:7], v[168:171], v[212:215], v[4:7]
	v_mfma_f32_16x16x32_bf16 v[0:3], v[176:179], v[212:215], v[0:3]
	v_mfma_f32_16x16x32_bf16 v[52:55], v[172:175], v[192:195], v[52:55]
	v_mfma_f32_16x16x32_bf16 v[48:51], v[180:183], v[192:195], v[48:51]
	v_mfma_f32_16x16x32_bf16 v[36:39], v[172:175], v[200:203], v[36:39]
	v_mfma_f32_16x16x32_bf16 v[32:35], v[180:183], v[200:203], v[32:35]
	v_mfma_f32_16x16x32_bf16 v[20:23], v[172:175], v[208:211], v[20:23]
	v_mfma_f32_16x16x32_bf16 v[16:19], v[180:183], v[208:211], v[16:19]
	v_mfma_f32_16x16x32_bf16 v[4:7], v[172:175], v[216:219], v[4:7]
	v_mfma_f32_16x16x32_bf16 v[0:3], v[180:183], v[216:219], v[0:3]
	s_setprio 0
	s_barrier
	s_add_i32 s77, s77, 2
	s_add_u32 s30, s30, 0x100
	s_addc_u32 s31, s31, 0
	s_add_u32 s75, s75, 0x100
	s_addc_u32 s76, s76, 0
	s_cmp_gt_u32 s77, 13
	s_cbranch_scc0 .LBB0_1571
	s_and_b64 vcc, exec, s[10:11]
	s_cbranch_vccz .LBB0_1574
	s_barrier

.LBB0_1650:
	ds_read_b128 v[152:155], v149
	ds_read_b128 v[156:159], v149 offset:1024
	ds_read_b128 v[160:163], v149 offset:2048
	ds_read_b128 v[164:167], v149 offset:3072
	ds_read_b128 v[168:171], v150
	ds_read_b128 v[172:175], v150 offset:1024
	ds_read_b128 v[176:179], v150 offset:2048
	ds_read_b128 v[180:183], v150 offset:3072
	s_add_u32 s34, s30, 0xfff00080
	s_addc_u32 s35, s31, -1
	s_cmp_eq_u32 s75, 60
	s_cselect_b32 s43, s23, s35
	s_cselect_b32 s42, s55, s34
	s_cselect_b32 s35, s21, s74
	s_cselect_b32 s34, s72, s73
	s_add_i32 m0, s29, 0xc000
	ds_read_b128 v[184:187], v151
	ds_read_b128 v[192:195], v151 offset:1024
	ds_read_b128 v[196:199], v151 offset:2048
	ds_read_b128 v[200:203], v151 offset:3072
	ds_read_b128 v[204:207], v151 offset:4096
	ds_read_b128 v[208:211], v151 offset:5120
	ds_read_b128 v[212:215], v151 offset:6144
	ds_read_b128 v[216:219], v151 offset:7168
	global_load_lds_dwordx4 v136, s[30:31]
	s_add_i32 m0, s29, 0xe000
	s_nop 0
	global_load_lds_dwordx4 v138, s[30:31]
	s_waitcnt vmcnt(8)
	s_waitcnt lgkmcnt(0)
	s_barrier
	s_setprio 1
	s_waitcnt lgkmcnt(0)
	v_mfma_f32_16x16x32_bf16 v[124:127], v[152:155], v[184:187], v[124:127]
	v_mfma_f32_16x16x32_bf16 v[120:123], v[160:163], v[184:187], v[120:123]
	v_mfma_f32_16x16x32_bf16 v[116:119], v[152:155], v[196:199], v[116:119]
	v_mfma_f32_16x16x32_bf16 v[108:111], v[160:163], v[196:199], v[108:111]
	v_mfma_f32_16x16x32_bf16 v[100:103], v[152:155], v[204:207], v[100:103]
	v_mfma_f32_16x16x32_bf16 v[92:95], v[160:163], v[204:207], v[92:95]
	v_mfma_f32_16x16x32_bf16 v[84:87], v[152:155], v[212:215], v[84:87]
	v_mfma_f32_16x16x32_bf16 v[76:79], v[160:163], v[212:215], v[76:79]
	v_mfma_f32_16x16x32_bf16 v[124:127], v[156:159], v[192:195], v[124:127]
	v_mfma_f32_16x16x32_bf16 v[120:123], v[164:167], v[192:195], v[120:123]
	v_mfma_f32_16x16x32_bf16 v[116:119], v[156:159], v[200:203], v[116:119]
	v_mfma_f32_16x16x32_bf16 v[108:111], v[164:167], v[200:203], v[108:111]
	v_mfma_f32_16x16x32_bf16 v[100:103], v[156:159], v[208:211], v[100:103]
	v_mfma_f32_16x16x32_bf16 v[92:95], v[164:167], v[208:211], v[92:95]
	v_mfma_f32_16x16x32_bf16 v[84:87], v[156:159], v[216:219], v[84:87]
	v_mfma_f32_16x16x32_bf16 v[76:79], v[164:167], v[216:219], v[76:79]
	s_setprio 0
	s_setprio 1
	v_mfma_f32_16x16x32_bf16 v[112:115], v[168:171], v[184:187], v[112:115]
	v_mfma_f32_16x16x32_bf16 v[104:107], v[176:179], v[184:187], v[104:107]
	v_mfma_f32_16x16x32_bf16 v[96:99], v[168:171], v[196:199], v[96:99]
	v_mfma_f32_16x16x32_bf16 v[88:91], v[176:179], v[196:199], v[88:91]
	v_mfma_f32_16x16x32_bf16 v[80:83], v[168:171], v[204:207], v[80:83]
	v_mfma_f32_16x16x32_bf16 v[72:75], v[176:179], v[204:207], v[72:75]
	v_mfma_f32_16x16x32_bf16 v[68:71], v[168:171], v[212:215], v[68:71]
	v_mfma_f32_16x16x32_bf16 v[64:67], v[176:179], v[212:215], v[64:67]
	v_mfma_f32_16x16x32_bf16 v[112:115], v[172:175], v[192:195], v[112:115]
	v_mfma_f32_16x16x32_bf16 v[104:107], v[180:183], v[192:195], v[104:107]
	v_mfma_f32_16x16x32_bf16 v[96:99], v[172:175], v[200:203], v[96:99]
	v_mfma_f32_16x16x32_bf16 v[88:91], v[180:183], v[200:203], v[88:91]
	v_mfma_f32_16x16x32_bf16 v[80:83], v[172:175], v[208:211], v[80:83]
	v_mfma_f32_16x16x32_bf16 v[72:75], v[180:183], v[208:211], v[72:75]
	v_mfma_f32_16x16x32_bf16 v[68:71], v[172:175], v[216:219], v[68:71]
	v_mfma_f32_16x16x32_bf16 v[64:67], v[180:183], v[216:219], v[64:67]
	s_setprio 0
	s_barrier
	s_add_i32 s76, s66, s59
	s_add_u32 s98, s34, 0x80
	s_addc_u32 s99, s35, 0
	s_mov_b32 m0, s76
	ds_read_b128 v[184:187], v151 offset:16384
	ds_read_b128 v[192:195], v151 offset:17408
	ds_read_b128 v[196:199], v151 offset:18432
	ds_read_b128 v[200:203], v151 offset:19456
	ds_read_b128 v[204:207], v151 offset:20480
	ds_read_b128 v[208:211], v151 offset:21504
	ds_read_b128 v[212:215], v151 offset:22528
	ds_read_b128 v[216:219], v151 offset:23552
	global_load_lds_dwordx4 v130, s[34:35]
	s_add_i32 m0, s76, 0x2000
	s_add_u32 s76, s34, 0x100000
	s_addc_u32 s77, s35, 0
	s_add_i32 s79, s67, s59
	global_load_lds_dwordx4 v134, s[34:35]
	s_mov_b32 m0, s79
	s_add_u32 s100, s42, 0x80
	s_addc_u32 s101, s43, 0
	global_load_lds_dwordx4 v130, s[76:77]
	s_add_i32 m0, s79, 0x2000
	s_nop 0
	global_load_lds_dwordx4 v134, s[76:77]
	s_mov_b32 m0, s29
	s_nop 0
	global_load_lds_dwordx4 v128, s[42:43]
	s_mov_b32 m0, s33
	s_nop 0
	global_load_lds_dwordx4 v132, s[42:43]
	s_waitcnt vmcnt(8)
	s_waitcnt lgkmcnt(0)
	s_barrier
	s_setprio 1
	s_waitcnt lgkmcnt(0)
	v_mfma_f32_16x16x32_bf16 v[60:63], v[152:155], v[184:187], v[60:63]
	v_mfma_f32_16x16x32_bf16 v[56:59], v[160:163], v[184:187], v[56:59]
	v_mfma_f32_16x16x32_bf16 v[52:55], v[152:155], v[196:199], v[52:55]
	v_mfma_f32_16x16x32_bf16 v[44:47], v[160:163], v[196:199], v[44:47]
	v_mfma_f32_16x16x32_bf16 v[36:39], v[152:155], v[204:207], v[36:39]
	v_mfma_f32_16x16x32_bf16 v[28:31], v[160:163], v[204:207], v[28:31]
	v_mfma_f32_16x16x32_bf16 v[20:23], v[152:155], v[212:215], v[20:23]
	v_mfma_f32_16x16x32_bf16 v[12:15], v[160:163], v[212:215], v[12:15]
	v_mfma_f32_16x16x32_bf16 v[60:63], v[156:159], v[192:195], v[60:63]
	v_mfma_f32_16x16x32_bf16 v[56:59], v[164:167], v[192:195], v[56:59]
	v_mfma_f32_16x16x32_bf16 v[52:55], v[156:159], v[200:203], v[52:55]
	v_mfma_f32_16x16x32_bf16 v[44:47], v[164:167], v[200:203], v[44:47]
	v_mfma_f32_16x16x32_bf16 v[36:39], v[156:159], v[208:211], v[36:39]
	v_mfma_f32_16x16x32_bf16 v[28:31], v[164:167], v[208:211], v[28:31]
	v_mfma_f32_16x16x32_bf16 v[20:23], v[156:159], v[216:219], v[20:23]
	v_mfma_f32_16x16x32_bf16 v[12:15], v[164:167], v[216:219], v[12:15]
	s_setprio 0
	s_setprio 1
	v_mfma_f32_16x16x32_bf16 v[48:51], v[168:171], v[184:187], v[48:51]
	v_mfma_f32_16x16x32_bf16 v[40:43], v[176:179], v[184:187], v[40:43]
	v_mfma_f32_16x16x32_bf16 v[32:35], v[168:171], v[196:199], v[32:35]
	v_mfma_f32_16x16x32_bf16 v[24:27], v[176:179], v[196:199], v[24:27]
	v_mfma_f32_16x16x32_bf16 v[16:19], v[168:171], v[204:207], v[16:19]
	v_mfma_f32_16x16x32_bf16 v[8:11], v[176:179], v[204:207], v[8:11]
	v_mfma_f32_16x16x32_bf16 v[4:7], v[168:171], v[212:215], v[4:7]
	v_mfma_f32_16x16x32_bf16 v[0:3], v[176:179], v[212:215], v[0:3]
	v_mfma_f32_16x16x32_bf16 v[48:51], v[172:175], v[192:195], v[48:51]
	v_mfma_f32_16x16x32_bf16 v[40:43], v[180:183], v[192:195], v[40:43]
	v_mfma_f32_16x16x32_bf16 v[32:35], v[172:175], v[200:203], v[32:35]
	v_mfma_f32_16x16x32_bf16 v[24:27], v[180:183], v[200:203], v[24:27]
	v_mfma_f32_16x16x32_bf16 v[16:19], v[172:175], v[208:211], v[16:19]
	v_mfma_f32_16x16x32_bf16 v[8:11], v[180:183], v[208:211], v[8:11]
	v_mfma_f32_16x16x32_bf16 v[4:7], v[172:175], v[216:219], v[4:7]
	v_mfma_f32_16x16x32_bf16 v[0:3], v[180:183], v[216:219], v[0:3]
	s_setprio 0
	s_barrier
	s_add_i32 s76, 0, 0x18000
	s_add_i32 s77, 0, 0x1c000
	v_add_u32_e32 v164, s76, v147
	v_add_u32_e32 v180, s77, v147
	ds_read_b128 v[152:155], v164
	ds_read_b128 v[156:159], v164 offset:1024
	ds_read_b128 v[160:163], v164 offset:2048
	ds_read_b128 v[164:167], v164 offset:3072
	ds_read_b128 v[168:171], v180
	ds_read_b128 v[172:175], v180 offset:1024
	ds_read_b128 v[176:179], v180 offset:2048
	ds_read_b128 v[180:183], v180 offset:3072
	s_add_u32 s42, s42, 0x100000
	s_addc_u32 s43, s43, 0
	s_mov_b32 m0, s60
	ds_read_b128 v[184:187], v151 offset:32768
	ds_read_b128 v[192:195], v151 offset:33792
	ds_read_b128 v[196:199], v151 offset:34816
	ds_read_b128 v[200:203], v151 offset:35840
	ds_read_b128 v[204:207], v151 offset:36864
	ds_read_b128 v[208:211], v151 offset:37888
	ds_read_b128 v[212:215], v151 offset:38912
	ds_read_b128 v[216:219], v151 offset:39936
	global_load_lds_dwordx4 v128, s[42:43]
	s_mov_b32 m0, s61
	s_nop 0
	global_load_lds_dwordx4 v132, s[42:43]
	s_waitcnt vmcnt(8)
	s_waitcnt lgkmcnt(0)
	s_barrier
	s_setprio 1
	s_waitcnt lgkmcnt(0)
	v_mfma_f32_16x16x32_bf16 v[124:127], v[152:155], v[184:187], v[124:127]
	v_mfma_f32_16x16x32_bf16 v[120:123], v[160:163], v[184:187], v[120:123]
	v_mfma_f32_16x16x32_bf16 v[116:119], v[152:155], v[196:199], v[116:119]
	v_mfma_f32_16x16x32_bf16 v[108:111], v[160:163], v[196:199], v[108:111]
	v_mfma_f32_16x16x32_bf16 v[100:103], v[152:155], v[204:207], v[100:103]
	v_mfma_f32_16x16x32_bf16 v[92:95], v[160:163], v[204:207], v[92:95]
	v_mfma_f32_16x16x32_bf16 v[84:87], v[152:155], v[212:215], v[84:87]
	v_mfma_f32_16x16x32_bf16 v[76:79], v[160:163], v[212:215], v[76:79]
	v_mfma_f32_16x16x32_bf16 v[124:127], v[156:159], v[192:195], v[124:127]
	v_mfma_f32_16x16x32_bf16 v[120:123], v[164:167], v[192:195], v[120:123]
	v_mfma_f32_16x16x32_bf16 v[116:119], v[156:159], v[200:203], v[116:119]
	v_mfma_f32_16x16x32_bf16 v[108:111], v[164:167], v[200:203], v[108:111]
	v_mfma_f32_16x16x32_bf16 v[100:103], v[156:159], v[208:211], v[100:103]
	v_mfma_f32_16x16x32_bf16 v[92:95], v[164:167], v[208:211], v[92:95]
	v_mfma_f32_16x16x32_bf16 v[84:87], v[156:159], v[216:219], v[84:87]
	v_mfma_f32_16x16x32_bf16 v[76:79], v[164:167], v[216:219], v[76:79]
	s_setprio 0
	s_setprio 1
	v_mfma_f32_16x16x32_bf16 v[112:115], v[168:171], v[184:187], v[112:115]
	v_mfma_f32_16x16x32_bf16 v[104:107], v[176:179], v[184:187], v[104:107]
	v_mfma_f32_16x16x32_bf16 v[96:99], v[168:171], v[196:199], v[96:99]
	v_mfma_f32_16x16x32_bf16 v[88:91], v[176:179], v[196:199], v[88:91]
	v_mfma_f32_16x16x32_bf16 v[80:83], v[168:171], v[204:207], v[80:83]
	v_mfma_f32_16x16x32_bf16 v[72:75], v[176:179], v[204:207], v[72:75]
	v_mfma_f32_16x16x32_bf16 v[68:71], v[168:171], v[212:215], v[68:71]
	v_mfma_f32_16x16x32_bf16 v[64:67], v[176:179], v[212:215], v[64:67]
	v_mfma_f32_16x16x32_bf16 v[112:115], v[172:175], v[192:195], v[112:115]
	v_mfma_f32_16x16x32_bf16 v[104:107], v[180:183], v[192:195], v[104:107]
	v_mfma_f32_16x16x32_bf16 v[96:99], v[172:175], v[200:203], v[96:99]
	v_mfma_f32_16x16x32_bf16 v[88:91], v[180:183], v[200:203], v[88:91]
	v_mfma_f32_16x16x32_bf16 v[80:83], v[172:175], v[208:211], v[80:83]
	v_mfma_f32_16x16x32_bf16 v[72:75], v[180:183], v[208:211], v[72:75]
	v_mfma_f32_16x16x32_bf16 v[68:71], v[172:175], v[216:219], v[68:71]
	v_mfma_f32_16x16x32_bf16 v[64:67], v[180:183], v[216:219], v[64:67]
	s_setprio 0
	s_barrier
	s_add_i32 s42, s76, s59
	s_mov_b32 m0, s42
	ds_read_b128 v[184:187], v151 offset:49152
	ds_read_b128 v[192:195], v151 offset:50176
	ds_read_b128 v[196:199], v151 offset:51200
	ds_read_b128 v[200:203], v151 offset:52224
	ds_read_b128 v[204:207], v151 offset:53248
	ds_read_b128 v[208:211], v151 offset:54272
	ds_read_b128 v[212:215], v151 offset:55296
	ds_read_b128 v[216:219], v151 offset:56320
	global_load_lds_dwordx4 v130, s[98:99]
	s_add_i32 m0, s42, 0x2000
	s_add_u32 s34, s34, 0x100080
	s_addc_u32 s35, s35, 0
	s_add_i32 s42, s77, s59
	global_load_lds_dwordx4 v134, s[98:99]
	s_mov_b32 m0, s42
	s_nop 0
	global_load_lds_dwordx4 v130, s[34:35]
	s_add_i32 m0, s42, 0x2000
	s_nop 0
	global_load_lds_dwordx4 v134, s[34:35]
	s_mov_b32 m0, s63
	s_nop 0
	global_load_lds_dwordx4 v128, s[100:101]
	s_mov_b32 m0, s64
	s_nop 0
	global_load_lds_dwordx4 v132, s[100:101]
	s_waitcnt vmcnt(8)
	s_waitcnt lgkmcnt(0)
	s_barrier
	s_setprio 1
	s_waitcnt lgkmcnt(0)
	v_mfma_f32_16x16x32_bf16 v[60:63], v[152:155], v[184:187], v[60:63]
	v_mfma_f32_16x16x32_bf16 v[56:59], v[160:163], v[184:187], v[56:59]
	v_mfma_f32_16x16x32_bf16 v[52:55], v[152:155], v[196:199], v[52:55]
	v_mfma_f32_16x16x32_bf16 v[44:47], v[160:163], v[196:199], v[44:47]
	v_mfma_f32_16x16x32_bf16 v[36:39], v[152:155], v[204:207], v[36:39]
	v_mfma_f32_16x16x32_bf16 v[28:31], v[160:163], v[204:207], v[28:31]
	v_mfma_f32_16x16x32_bf16 v[20:23], v[152:155], v[212:215], v[20:23]
	v_mfma_f32_16x16x32_bf16 v[12:15], v[160:163], v[212:215], v[12:15]
	v_mfma_f32_16x16x32_bf16 v[60:63], v[156:159], v[192:195], v[60:63]
	v_mfma_f32_16x16x32_bf16 v[56:59], v[164:167], v[192:195], v[56:59]
	v_mfma_f32_16x16x32_bf16 v[52:55], v[156:159], v[200:203], v[52:55]
	v_mfma_f32_16x16x32_bf16 v[44:47], v[164:167], v[200:203], v[44:47]
	v_mfma_f32_16x16x32_bf16 v[36:39], v[156:159], v[208:211], v[36:39]
	v_mfma_f32_16x16x32_bf16 v[28:31], v[164:167], v[208:211], v[28:31]
	v_mfma_f32_16x16x32_bf16 v[20:23], v[156:159], v[216:219], v[20:23]
	v_mfma_f32_16x16x32_bf16 v[12:15], v[164:167], v[216:219], v[12:15]
	s_setprio 0
	s_setprio 1
	v_mfma_f32_16x16x32_bf16 v[48:51], v[168:171], v[184:187], v[48:51]
	v_mfma_f32_16x16x32_bf16 v[40:43], v[176:179], v[184:187], v[40:43]
	v_mfma_f32_16x16x32_bf16 v[32:35], v[168:171], v[196:199], v[32:35]
	v_mfma_f32_16x16x32_bf16 v[24:27], v[176:179], v[196:199], v[24:27]
	v_mfma_f32_16x16x32_bf16 v[16:19], v[168:171], v[204:207], v[16:19]
	v_mfma_f32_16x16x32_bf16 v[8:11], v[176:179], v[204:207], v[8:11]
	v_mfma_f32_16x16x32_bf16 v[4:7], v[168:171], v[212:215], v[4:7]
	v_mfma_f32_16x16x32_bf16 v[0:3], v[176:179], v[212:215], v[0:3]
	v_mfma_f32_16x16x32_bf16 v[48:51], v[172:175], v[192:195], v[48:51]
	v_mfma_f32_16x16x32_bf16 v[40:43], v[180:183], v[192:195], v[40:43]
	v_mfma_f32_16x16x32_bf16 v[32:35], v[172:175], v[200:203], v[32:35]
	v_mfma_f32_16x16x32_bf16 v[24:27], v[180:183], v[200:203], v[24:27]
	v_mfma_f32_16x16x32_bf16 v[16:19], v[172:175], v[208:211], v[16:19]
	v_mfma_f32_16x16x32_bf16 v[8:11], v[180:183], v[208:211], v[8:11]
	v_mfma_f32_16x16x32_bf16 v[4:7], v[172:175], v[216:219], v[4:7]
	v_mfma_f32_16x16x32_bf16 v[0:3], v[180:183], v[216:219], v[0:3]
	s_setprio 0
	s_barrier
	s_add_i32 s75, s75, 2
	s_add_u32 s30, s30, 0x100
	s_addc_u32 s31, s31, 0
	s_add_u32 s73, s73, 0x100
	s_addc_u32 s74, s74, 0
	s_cmp_gt_u32 s75, 61
	s_cbranch_scc0 .LBB0_1650
	s_and_b64 vcc, exec, s[10:11]
	s_cbranch_vccz .LBB0_1653
	s_barrier

	.amdhsa_kernel _Z8yoco_fwd4Args
		.amdhsa_group_segment_fixed_size 0
		.amdhsa_private_segment_fixed_size 0
		.amdhsa_kernarg_size 584
		.amdhsa_user_sgpr_count 2
		.amdhsa_user_sgpr_dispatch_ptr 0
		.amdhsa_user_sgpr_queue_ptr 0
		.amdhsa_user_sgpr_kernarg_segment_ptr 1
		.amdhsa_user_sgpr_dispatch_id 0
		.amdhsa_user_sgpr_kernarg_preload_length 0
		.amdhsa_user_sgpr_kernarg_preload_offset 0
		.amdhsa_user_sgpr_private_segment_size 0
		.amdhsa_uses_dynamic_stack 0
		.amdhsa_enable_private_segment 0
		.amdhsa_system_sgpr_workgroup_id_x 1
		.amdhsa_system_sgpr_workgroup_id_y 0
		.amdhsa_system_sgpr_workgroup_id_z 0
		.amdhsa_system_sgpr_workgroup_info 0
		.amdhsa_system_vgpr_workitem_id 2
		.amdhsa_next_free_vgpr 248
		.amdhsa_next_free_sgpr 102
		.amdhsa_accum_offset 248
		.amdhsa_reserve_vcc 1
		.amdhsa_float_round_mode_32 0
		.amdhsa_float_round_mode_16_64 0
		.amdhsa_float_denorm_mode_32 3
		.amdhsa_float_denorm_mode_16_64 3
		.amdhsa_dx10_clamp 1
		.amdhsa_ieee_mode 1
		.amdhsa_fp16_overflow 0
		.amdhsa_tg_split 0
		.amdhsa_exception_fp_ieee_invalid_op 0
		.amdhsa_exception_fp_denorm_src 0
		.amdhsa_exception_fp_ieee_div_zero 0
		.amdhsa_exception_fp_ieee_overflow 0
		.amdhsa_exception_fp_ieee_underflow 0
		.amdhsa_exception_fp_ieee_inexact 0
		.amdhsa_exception_int_div_zero 0
	.end_amdhsa_kernel

amdhsa.kernels:
  - .agpr_count:     0
    .args:
      - .offset:         0
        .size:           328
        .value_kind:     by_value
      - .offset:         328
        .size:           4
        .value_kind:     hidden_block_count_x
      - .offset:         332
        .size:           4
        .value_kind:     hidden_block_count_y
      - .offset:         336
        .size:           4
        .value_kind:     hidden_block_count_z
      - .offset:         340
        .size:           2
        .value_kind:     hidden_group_size_x
      - .offset:         342
        .size:           2
        .value_kind:     hidden_group_size_y
      - .offset:         344
        .size:           2
        .value_kind:     hidden_group_size_z
      - .offset:         346
        .size:           2
        .value_kind:     hidden_remainder_x
      - .offset:         348
        .size:           2
        .value_kind:     hidden_remainder_y
      - .offset:         350
        .size:           2
        .value_kind:     hidden_remainder_z
      - .offset:         368
        .size:           8
        .value_kind:     hidden_global_offset_x
      - .offset:         376
        .size:           8
        .value_kind:     hidden_global_offset_y
      - .offset:         384
        .size:           8
        .value_kind:     hidden_global_offset_z
      - .offset:         392
        .size:           2
        .value_kind:     hidden_grid_dims
      - .offset:         416
        .size:           8
        .value_kind:     hidden_multigrid_sync_arg
      - .offset:         448
        .size:           4
        .value_kind:     hidden_dynamic_lds_size
    .group_segment_fixed_size: 0
    .kernarg_segment_align: 8
    .kernarg_segment_size: 584
    .language:       OpenCL C
    .language_version:
      - 2
      - 0
    .max_flat_workgroup_size: 512
    .name:           _Z8yoco_fwd4Args
    .private_segment_fixed_size: 0
    .sgpr_count:     108
    .sgpr_spill_count: 5
    .symbol:         _Z8yoco_fwd4Args.kd
    .uniform_work_group_size: 1
    .uses_dynamic_stack: false
    .vgpr_count:     248
    .vgpr_spill_count: 0
    .wavefront_size: 64
